# write-through (sc1) stores before chip-wide barriers (P0, Proj epilogue, LRU passes) + batched epilogue loads
# speedup vs baseline: 1.0055x; 1.0055x over previous
; __global__ void __launch_bounds__(512, 2) fwd_mega(Args a) {
;     ...
;     if (blockIdx.x == 0) for (int i = tid; i < XCD_BAR_WORDS + 64 + 2048; i += 512) ((unsigned*)(ws + WS_BAR))[i] = 0u;
.LBB0_3:
	v_add_u32_e32 v8, -2, v8
	v_ashrrev_i32_e32 v11, 31, v5
	v_mov_b32_e32 v10, v5
	v_ashrrev_i32_e32 v13, 31, v4
	v_mov_b32_e32 v12, v4
	v_cmp_eq_u32_e32 vcc, 0, v8
	v_add_u32_e32 v5, 0x400, v5
	v_add_u32_e32 v4, 0x400, v4
	v_lshl_add_u64 v[12:13], v[12:13], 2, s[10:11]
	v_lshl_add_u64 v[10:11], v[10:11], 2, s[10:11]
	s_or_b64 s[12:13], vcc, s[12:13]
	global_store_dword v[12:13], v7, off sc1
	global_store_dword v[10:11], v7, off sc1
	s_andn2_b64 exec, exec, s[12:13]
	s_cbranch_execnz .LBB0_3
	s_or_b64 exec, exec, s[12:13]
	v_cmp_ne_u32_e32 vcc, v1, v6
	v_lshl_add_u32 v4, v6, 9, v2
	s_orn2_b64 s[10:11], vcc, exec

; __global__ void __launch_bounds__(512, 2) fwd_mega(Args a) {
;     ...
;     if (blockIdx.x == 0) for (int i = tid; i < XCD_BAR_WORDS + 64 + 2048; i += 512) ((unsigned*)(ws + WS_BAR))[i] = 0u;
.LBB0_7:
	v_add_u32_e32 v1, 0x200, v1
	v_cmp_lt_i32_e32 vcc, s12, v1
	global_store_dword v[4:5], v3, off sc1
	s_or_b64 s[8:9], vcc, s[8:9]
	v_lshl_add_u64 v[4:5], v[4:5], 0, s[10:11]
	s_andn2_b64 exec, exec, s[8:9]
	s_cbranch_execnz .LBB0_7

; #define LAS __attribute__((address_space(3)))
; __device__ __forceinline__ unsigned cvt_pk_bf16(float lo, float hi) { unsigned r; asm volatile("v_cvt_pk_bf16_f32 %0, %1, %2" : "=v"(r) : "v"(lo), "v"(hi)); return r; }
; __device__ __forceinline__ void tr_item32(const float* W, int K, int N, bf16_t* WT, const float* gsc, bool swz, LAS float* scr, int item, int lane) {
;     ...
;     for (int hf = 0; hf < 2; ++hf)
; #pragma unroll
;         for (int i = 0; i < 4; ++i) v[hf][i] = *(const f32x4*)(W + (size_t)(k0 + kr + 8 * i) * N + n0 + 32 * hf + 4 * n4);
;     if (gsc) {
; #pragma unroll
;         for (int i = 0; i < 4; ++i) { const float gg = gsc[k0 + kr + 8 * i]; v[0][i] = v[0][i] * gg; v[1][i] = v[1][i] * gg; }
;     }
;     const int c = lane & 3;
; #pragma unroll
;     for (int hf = 0; hf < 2; ++hf) {
; #pragma unroll
;         for (int i = 0; i < 4; ++i)
; #pragma unroll
;             for (int e = 0; e < 4; ++e) scr[(kr + 8 * i) * 33 + 4 * n4 + e] = v[hf][i][e];
;         asm volatile("s_waitcnt lgkmcnt(0)" ::: "memory");
; #pragma unroll
;         for (int j = 0; j < 2; ++j) { const int n = (lane >> 2) + 16 * j; const LAS float* sp = scr + (8 * c) * 33 + n;
;             u32x4 o; o.x = cvt_pk_bf16(sp[0 * 33], sp[1 * 33]); o.y = cvt_pk_bf16(sp[2 * 33], sp[3 * 33]); o.z = cvt_pk_bf16(sp[4 * 33], sp[5 * 33]); o.w = cvt_pk_bf16(sp[6 * 33], sp[7 * 33]);
;             *(u32x4*)(WT + (size_t)(rbase + 32 * hf + n) * K + k0 + 8 * c) = o; }
;         asm volatile("s_waitcnt lgkmcnt(0)" ::: "memory");
;     }
.LBB0_26:
	s_waitcnt vmcnt(7)
	ds_write2_b32 v43, v28, v29 offset1:1
	ds_write2_b32 v43, v30, v31 offset0:2 offset1:3
	v_add_u32_e32 v29, 0x428, v43
	v_add_u32_e32 v28, 0x420, v43
	s_waitcnt vmcnt(5)
	ds_write2_b32 v29, v26, v27 offset1:1
	v_add_u32_e32 v26, 0x840, v43
	v_add_u32_e32 v27, 0x848, v43
	v_add_u32_e32 v30, 0xc60, v43
	v_add_u32_e32 v31, 0xc68, v43
	ds_write2_b32 v28, v24, v25 offset1:1
	s_waitcnt vmcnt(3)
	ds_write2_b32 v26, v20, v21 offset1:1
	ds_write2_b32 v27, v22, v23 offset1:1
	s_waitcnt vmcnt(1)
	ds_write2_b32 v30, v16, v17 offset1:1
	ds_write2_b32 v31, v18, v19 offset1:1
	s_waitcnt lgkmcnt(0)
	ds_read2_b32 v[16:17], v41 offset1:33
	s_waitcnt lgkmcnt(0)
	v_cvt_pk_bf16_f32 v16, v16, v17
	ds_read2_b32 v[18:19], v41 offset0:66 offset1:99
	s_ashr_i32 s35, s34, 31
	s_waitcnt lgkmcnt(0)
	v_cvt_pk_bf16_f32 v17, v18, v19
	ds_read2_b32 v[18:19], v41 offset0:132 offset1:165
	s_lshl_b64 s[28:29], s[34:35], 1
	s_waitcnt lgkmcnt(0)
	v_cvt_pk_bf16_f32 v18, v18, v19
	ds_read2_b32 v[20:21], v41 offset0:198 offset1:231
	s_add_u32 s26, s26, s28
	v_add_u32_e32 v24, s33, v40
	s_addc_u32 s27, s27, s29
	s_waitcnt lgkmcnt(0)
	v_cvt_pk_bf16_f32 v19, v20, v21
	v_ashrrev_i32_e32 v20, 31, v24
	v_lshl_add_u64 v[22:23], s[26:27], 0, v[32:33]
	v_mul_lo_u32 v36, s24, v20
	v_mul_lo_u32 v37, s25, v24
	v_mad_u64_u32 v[24:25], s[26:27], s24, v24, 0
	v_add3_u32 v25, v25, v36, v37
	v_lshl_add_u64 v[24:25], v[24:25], 1, v[22:23]
	ds_read2_b32 v[20:21], v41 offset0:16 offset1:49
	global_store_dwordx4 v[24:25], v[16:19], off sc1
	s_add_i32 s28, s33, 32
	s_add_i32 s7, s7, s44
	s_waitcnt lgkmcnt(0)
	v_cvt_pk_bf16_f32 v16, v20, v21
	ds_read2_b32 v[18:19], v41 offset0:82 offset1:115
	s_waitcnt lgkmcnt(0)
	v_cvt_pk_bf16_f32 v17, v18, v19
	ds_read2_b32 v[18:19], v41 offset0:148 offset1:181
	s_waitcnt lgkmcnt(0)
	v_cvt_pk_bf16_f32 v18, v18, v19
	ds_read2_b32 v[20:21], v41 offset0:214 offset1:247
	s_waitcnt lgkmcnt(0)
	v_cvt_pk_bf16_f32 v19, v20, v21
	v_add_u32_e32 v20, s33, v42
	v_ashrrev_i32_e32 v21, 31, v20
	v_mul_lo_u32 v24, s24, v21
	v_mul_lo_u32 v25, s25, v20
	v_mad_u64_u32 v[20:21], s[26:27], s24, v20, 0
	v_add3_u32 v21, v21, v24, v25
	v_lshl_add_u64 v[20:21], v[20:21], 1, v[22:23]
	global_store_dwordx4 v[20:21], v[16:19], off sc1
	s_waitcnt lgkmcnt(0)
	ds_write2_b32 v43, v12, v13 offset1:1
	ds_write2_b32 v43, v14, v15 offset0:2 offset1:3
	ds_write2_b32 v28, v8, v9 offset1:1
	ds_write2_b32 v29, v10, v11 offset1:1
	ds_write2_b32 v26, v4, v5 offset1:1
	ds_write2_b32 v27, v6, v7 offset1:1
	s_waitcnt vmcnt(2)
	ds_write2_b32 v30, v0, v1 offset1:1
	ds_write2_b32 v31, v2, v3 offset1:1
	s_waitcnt lgkmcnt(0)
	ds_read2_b32 v[0:1], v41 offset1:33
	s_waitcnt lgkmcnt(0)
	v_cvt_pk_bf16_f32 v0, v0, v1
	ds_read2_b32 v[2:3], v41 offset0:66 offset1:99
	s_waitcnt lgkmcnt(0)
	v_cvt_pk_bf16_f32 v1, v2, v3
	ds_read2_b32 v[2:3], v41 offset0:132 offset1:165
	s_waitcnt lgkmcnt(0)
	v_cvt_pk_bf16_f32 v2, v2, v3
	ds_read2_b32 v[4:5], v41 offset0:198 offset1:231
	v_add_u32_e32 v6, s28, v40
	s_waitcnt lgkmcnt(0)
	v_cvt_pk_bf16_f32 v3, v4, v5
	v_ashrrev_i32_e32 v4, 31, v6
	v_mul_lo_u32 v8, s24, v4
	v_mul_lo_u32 v9, s25, v6
	v_mad_u64_u32 v[6:7], s[26:27], s24, v6, 0
	v_add3_u32 v7, v7, v8, v9
	v_lshl_add_u64 v[6:7], v[6:7], 1, v[22:23]
	ds_read2_b32 v[4:5], v41 offset0:16 offset1:49
	global_store_dwordx4 v[6:7], v[0:3], off sc1
	s_cmpk_lt_i32 s7, 0x3140
	s_waitcnt lgkmcnt(0)
	v_cvt_pk_bf16_f32 v0, v4, v5
	ds_read2_b32 v[2:3], v41 offset0:82 offset1:115
	s_waitcnt lgkmcnt(0)
	v_cvt_pk_bf16_f32 v1, v2, v3
	ds_read2_b32 v[2:3], v41 offset0:148 offset1:181
	s_waitcnt lgkmcnt(0)
	v_cvt_pk_bf16_f32 v2, v2, v3
	ds_read2_b32 v[4:5], v41 offset0:214 offset1:247
	s_waitcnt lgkmcnt(0)
	v_cvt_pk_bf16_f32 v3, v4, v5
	v_add_u32_e32 v4, s28, v42
	v_ashrrev_i32_e32 v5, 31, v4
	v_mul_lo_u32 v6, s24, v5
	v_mul_lo_u32 v7, s25, v4
	v_mad_u64_u32 v[4:5], s[24:25], s24, v4, 0
	v_add3_u32 v5, v5, v6, v7
	v_lshl_add_u64 v[4:5], v[4:5], 1, v[22:23]
	global_store_dwordx4 v[4:5], v[0:3], off sc1
	s_waitcnt lgkmcnt(0)
	s_cbranch_scc0 .LBB0_71

; __device__ __forceinline__ unsigned cvt_pk_bf16(float lo, float hi) { unsigned r; asm volatile("v_cvt_pk_bf16_f32 %0, %1, %2" : "=v"(r) : "v"(lo), "v"(hi)); return r; }
; __global__ void __launch_bounds__(512, 2) fwd_mega(Args a) {
;     ...
;     for (int row = gw; row < M; row += NGW) {
;         const f32x4* xr = (const f32x4*)(a.x + (size_t)row * D) + lane; float s = 0.f;
; #pragma unroll
;         for (int j = 0; j < 4; ++j) { const f32x4 v = xr[64 * j]; s += (v[0] * v[0] + v[1] * v[1]) + (v[2] * v[2] + v[3] * v[3]);
;             u32x2 o; o.x = cvt_pk_bf16(v[0], v[1]); o.y = cvt_pk_bf16(v[2], v[3]); *((u32x2*)(XB + (size_t)row * D) + lane + 64 * j) = o; }
;         s = wave_sum(s); if (lane < 16) SS[(size_t)row * 16 + lane] = lane == 0 ? s : 0.f;
;     }
.LBB0_74:
	v_lshl_add_u64 v[20:21], s[64:65], 0, v[2:3]
	v_add_co_u32_e64 v32, s[4:5], s7, v20
	s_waitcnt lgkmcnt(0)
	global_load_dwordx4 v[16:19], v[4:5], off offset:-3072
	v_addc_co_u32_e64 v33, s[4:5], 0, v21, s[4:5]
	s_waitcnt vmcnt(0)
	v_cvt_pk_bf16_f32 v20, v16, v17
	v_cvt_pk_bf16_f32 v21, v18, v19
	global_store_dwordx2 v[32:33], v[20:21], off sc1
	global_load_dwordx4 v[20:23], v[4:5], off offset:-2048
	s_waitcnt vmcnt(0)
	v_cvt_pk_bf16_f32 v24, v20, v21
	v_cvt_pk_bf16_f32 v25, v22, v23
	global_store_dwordx2 v[32:33], v[24:25], off offset:512 sc1
	global_load_dwordx4 v[24:27], v[4:5], off offset:-1024
	s_waitcnt vmcnt(0)
	v_cvt_pk_bf16_f32 v28, v24, v25
	v_cvt_pk_bf16_f32 v29, v26, v27
	global_store_dwordx2 v[32:33], v[28:29], off offset:1024 sc1
	global_load_dwordx4 v[28:31], v[4:5], off
	v_cmp_lt_i32_e64 s[4:5], v9, v8
	v_mul_f32_e32 v17, v17, v17
	v_mul_f32_e32 v19, v19, v19
	v_fmac_f32_e32 v17, v16, v16
	v_fmac_f32_e32 v19, v18, v18
	v_add_f32_e32 v16, v17, v19
	v_cndmask_b32_e64 v15, v7, v9, s[4:5]
	v_mul_f32_e32 v17, v21, v21
	v_mul_f32_e32 v18, v23, v23
	v_fmac_f32_e32 v17, v20, v20
	v_fmac_f32_e32 v18, v22, v22
	v_add_f32_e32 v17, v17, v18
	v_add_f32_e32 v16, v16, v17
	v_mul_f32_e32 v17, v25, v25
	v_mul_f32_e32 v18, v27, v27
	v_fmac_f32_e32 v17, v24, v24
	v_fmac_f32_e32 v18, v26, v26
	v_add_f32_e32 v17, v17, v18
	v_add_f32_e32 v16, v16, v17
	s_waitcnt vmcnt(0)
	v_mul_f32_e32 v17, v29, v29
	v_mul_f32_e32 v18, v31, v31
	v_fmac_f32_e32 v17, v28, v28
	v_fmac_f32_e32 v18, v30, v30
	v_add_f32_e32 v17, v17, v18
	v_lshlrev_b32_e32 v15, 2, v15
	v_add_f32_e32 v16, v16, v17
	ds_bpermute_b32 v15, v15, v16
	v_cmp_lt_i32_e64 s[4:5], v10, v8
	v_cvt_pk_bf16_f32 v18, v28, v29
	v_cvt_pk_bf16_f32 v19, v30, v31
	global_store_dwordx2 v[32:33], v[18:19], off offset:1536 sc1
	s_waitcnt lgkmcnt(0)
	v_add_f32_e32 v15, v16, v15
	v_cndmask_b32_e64 v17, v7, v10, s[4:5]
	v_lshlrev_b32_e32 v17, 2, v17
	ds_bpermute_b32 v16, v17, v15
	v_cmp_lt_i32_e64 s[4:5], v11, v8
	s_waitcnt lgkmcnt(0)
	v_add_f32_e32 v15, v15, v16
	v_cndmask_b32_e64 v17, v7, v11, s[4:5]
	v_lshlrev_b32_e32 v17, 2, v17
	ds_bpermute_b32 v16, v17, v15
	v_cmp_lt_i32_e64 s[4:5], v12, v8
	s_waitcnt lgkmcnt(0)
	v_add_f32_e32 v15, v15, v16
	v_cndmask_b32_e64 v17, v7, v12, s[4:5]
	v_lshlrev_b32_e32 v17, 2, v17
	ds_bpermute_b32 v16, v17, v15
	v_cmp_lt_i32_e64 s[4:5], v13, v8
	s_waitcnt lgkmcnt(0)
	v_add_f32_e32 v15, v15, v16
	v_cndmask_b32_e64 v17, v7, v13, s[4:5]
	v_lshlrev_b32_e32 v17, 2, v17
	ds_bpermute_b32 v16, v17, v15
	v_cmp_lt_i32_e64 s[4:5], v14, v8
	s_waitcnt lgkmcnt(0)
	v_add_f32_e32 v15, v15, v16
	v_cndmask_b32_e64 v17, v7, v14, s[4:5]
	v_lshlrev_b32_e32 v16, 2, v17
	ds_bpermute_b32 v16, v16, v15
	s_and_saveexec_b64 s[4:5], vcc
	s_cbranch_execz .LBB0_73
	s_waitcnt lgkmcnt(0)
	v_add_f32_e32 v15, v15, v16
	v_lshl_add_u64 v[18:19], s[64:65], 0, v[0:1]
	v_cndmask_b32_e64 v15, 0, v15, s[0:1]
	global_store_dword v[18:19], v15, off sc1
	s_branch .LBB0_73

; __device__ __forceinline__ u32x4 pack8(const f32x4 a, const f32x4 b) { u32x4 w; w.x = cvt_pk_bf16(a[0], a[1]); w.y = cvt_pk_bf16(a[2], a[3]); w.z = cvt_pk_bf16(b[0], b[1]); w.w = cvt_pk_bf16(b[2], b[3]); return w; }
;     __device__ __forceinline__ void operator()(const f32x4 (&acc)[2][2][4][2], const Unit& u, int wr, int wc, int fr, int fq) const {
;         const int row0 = u.pm * 256 + wr * 64 + fr; const int kind = u.pn < 7 ? 0 : (u.pn < 12 ? 1 : 2);
;         bf16_t* base = kind == 0 ? P1 : P2; const int ld = kind == 0 ? P1W : P2W; const int col0 = (kind == 0 ? u.pn : u.pn - 7) * 256 + wc * 32 + 8 * fq;
;         const float c3 = kind == 1 ? -LOG2E_ * 1.5957691216f * 0.044715f : 0.f, c1 = kind == 1 ? -LOG2E_ * 1.5957691216f : -LOG2E_;
; #pragma unroll
;         for (int ai = 0; ai < 2; ++ai)
; #pragma unroll
;             for (int m = 0; m < 4; ++m) {
;                 const int row = row0 + ai * 128 + m * 16; const float rs = (u.pm == pm0) ? RS[row & 255] : row_rstd(ss, row);
; #pragma unroll
;                 for (int bj = 0; bj < 2; ++bj) {
;                     f32x4 v[2], e[2];
; #pragma unroll
;                     for (int n = 0; n < 2; ++n) { v[n] = acc[ai][bj][m][n] * rs; e[n] = v[n] * ((v[n] * v[n]) * c3 + c1); }
;                     if (kind != 0) {
; #pragma unroll
;                         for (int n = 0; n < 2; ++n)
; #pragma unroll
;                             for (int j = 0; j < 4; ++j) e[n][j] = __builtin_amdgcn_exp2f(e[n][j]);
; #pragma unroll
;                         for (int n = 0; n < 2; ++n) e[n] = e[n] + 1.0f;
; #pragma unroll
;                         for (int n = 0; n < 2; ++n)
; #pragma unroll
;                             for (int j = 0; j < 4; ++j) e[n][j] = __builtin_amdgcn_rcpf(e[n][j]);
;                         if (kind == 1) { v[0] = v[0] * e[0]; v[1] = v[1] * e[1]; } else { v[0] = e[0]; v[1] = e[1]; }
;                     }
;                     __builtin_nontemporal_store(pack8(v[0], v[1]), (u32x4*)(base + (size_t)row * ld + col0 + bj * 128));
;                 }
.LBB0_503:
	s_and_b64 s[22:23], s[8:9], exec
	s_movk_i32 s7, 0xd00
	s_cselect_b32 s15, s56, s36
	s_cselect_b32 s13, s7, 0x700
	s_cselect_b32 s7, s57, s37
	v_mov_b32_e32 v122, s15
	s_lshl_b32 s15, s6, 8
	s_add_i32 s22, s15, 0xfffff900
	v_mov_b32_e32 v123, s7
	s_and_b64 s[6:7], s[8:9], exec
	s_cselect_b32 s6, s22, s15
	v_or_b32_e32 v124, s6, v163
	v_ashrrev_i32_e32 v125, 31, v124
	v_lshl_add_u64 v[122:123], v[124:125], 1, v[122:123]
	v_mad_u64_u32 v[124:125], s[6:7], v148, s13, 0
	v_mov_b32_e32 v138, v125
	v_mad_u64_u32 v[138:139], s[6:7], v149, s13, v[138:139]
	v_mov_b32_e32 v125, v138
	v_lshl_add_u64 v[124:125], v[124:125], 1, v[122:123]
	v_cvt_pk_bf16_f32 v126, v126, v127
	v_cvt_pk_bf16_f32 v127, v128, v129
	v_cvt_pk_bf16_f32 v128, v152, v153
	v_cvt_pk_bf16_f32 v129, v154, v155
	global_store_dwordx4 v[124:125], v[126:129], off sc1
	v_mov_b32_e32 v151, v150
	v_pk_mul_f32 v[118:119], v[118:119], v[150:151]
	v_mov_b32_e32 v126, v150
	v_mov_b32_e32 v127, v150
	v_pk_mul_f32 v[120:121], v[120:121], v[126:127]
	v_pk_mul_f32 v[116:117], v[116:117], v[126:127]
	v_cndmask_b32_e64 v126, 0, 1, s[8:9]
	v_cmp_ne_u32_e64 s[6:7], 1, v126
	s_andn2_b64 vcc, exec, s[8:9]
	v_pk_mul_f32 v[114:115], v[114:115], v[150:151]
	s_cbranch_vccnz .LBB0_507
	v_pk_mul_f32 v[126:127], v[116:117], v[116:117]
	v_pk_mul_f32 v[128:129], v[114:115], v[114:115]
	v_mov_b32_e32 v138, v146
	v_mov_b32_e32 v139, v146
	v_mov_b32_e32 v140, v144
	v_mov_b32_e32 v141, v144
	v_pk_mul_f32 v[150:151], v[120:121], v[120:121]
	v_pk_mul_f32 v[152:153], v[118:119], v[118:119]
	v_pk_fma_f32 v[126:127], v[140:141], v[126:127], v[138:139]
	v_pk_fma_f32 v[128:129], v[144:145], v[128:129], v[146:147]
	v_pk_fma_f32 v[138:139], v[140:141], v[150:151], v[138:139]
	v_pk_fma_f32 v[140:141], v[144:145], v[152:153], v[146:147]
	v_pk_mul_f32 v[126:127], v[116:117], v[126:127]
	v_pk_mul_f32 v[128:129], v[114:115], v[128:129]
	v_pk_mul_f32 v[138:139], v[120:121], v[138:139]
	v_pk_mul_f32 v[140:141], v[118:119], v[140:141]
	v_exp_f32_e32 v138, v138
	v_exp_f32_e32 v140, v140
	v_exp_f32_e32 v141, v141
	v_exp_f32_e32 v139, v139
	v_exp_f32_e32 v128, v128
	v_exp_f32_e32 v126, v126
	v_exp_f32_e32 v127, v127
	v_exp_f32_e32 v129, v129
	v_pk_add_f32 v[138:139], v[138:139], 1.0 op_sel_hi:[1,0]
	v_pk_add_f32 v[140:141], v[140:141], 1.0 op_sel_hi:[1,0]
	v_pk_add_f32 v[152:153], v[126:127], 1.0 op_sel_hi:[1,0]
	v_pk_add_f32 v[150:151], v[128:129], 1.0 op_sel_hi:[1,0]
	v_rcp_f32_e32 v126, v140
	v_rcp_f32_e32 v127, v141
	v_rcp_f32_e32 v128, v138
	v_rcp_f32_e32 v129, v139
	v_rcp_f32_e32 v150, v150
	v_rcp_f32_e32 v151, v151
	v_rcp_f32_e32 v152, v152
	v_rcp_f32_e32 v153, v153
	s_and_b64 vcc, exec, s[4:5]
	s_cbranch_vccnz .LBB0_506
	v_pk_mul_f32 v[152:153], v[116:117], v[152:153]
	v_pk_mul_f32 v[150:151], v[114:115], v[150:151]
	v_pk_mul_f32 v[128:129], v[120:121], v[128:129]
	v_pk_mul_f32 v[126:127], v[118:119], v[126:127]

; __device__ __forceinline__ u32x4 pack8(const f32x4 a, const f32x4 b) { u32x4 w; w.x = cvt_pk_bf16(a[0], a[1]); w.y = cvt_pk_bf16(a[2], a[3]); w.z = cvt_pk_bf16(b[0], b[1]); w.w = cvt_pk_bf16(b[2], b[3]); return w; }
; __device__ __forceinline__ float row_rstd(const float* ss, int row) {
;     const f32x4* q = (const f32x4*)(ss + (size_t)row * 16); const f32x4 s4 = (q[0] + q[1]) + (q[2] + q[3]);
;     return rsqrtf(((s4[0] + s4[1]) + (s4[2] + s4[3])) * (1.0f / D) + EPS);
;     __device__ __forceinline__ void operator()(const f32x4 (&acc)[2][2][4][2], const Unit& u, int wr, int wc, int fr, int fq) const {
;     ...
;                     __builtin_nontemporal_store(pack8(v[0], v[1]), (u32x4*)(base + (size_t)row * ld + col0 + bj * 128));
.LBB0_507:
	v_cvt_pk_bf16_f32 v118, v118, v119
	v_cvt_pk_bf16_f32 v119, v120, v121
	v_cvt_pk_bf16_f32 v120, v114, v115
	v_or_b32_e32 v114, 16, v148
	v_cndmask_b32_e64 v115, 0, 1, s[20:21]
	s_mov_b64 s[22:23], -1
	v_cmp_ne_u32_e64 s[8:9], 1, v115
	s_andn2_b64 vcc, exec, s[20:21]
	v_ashrrev_i32_e32 v115, 31, v114
	v_cvt_pk_bf16_f32 v121, v116, v117
	global_store_dwordx4 v[124:125], v[118:121], off offset:256 sc1
	s_cbranch_vccnz .LBB0_509
	v_lshlrev_b64 v[116:117], 6, v[114:115]
	v_lshl_add_u64 v[120:121], s[80:81], 0, v[116:117]
	global_load_dwordx4 v[116:119], v[120:121], off
	global_load_dwordx4 v[124:127], v[120:121], off offset:16
	global_load_dwordx4 v[150:153], v[120:121], off offset:32
	global_load_dwordx4 v[154:157], v[120:121], off offset:48
	s_mov_b32 s15, 0x800000
	s_mov_b64 s[22:23], 0
	s_waitcnt vmcnt(0)
	v_pk_add_f32 v[118:119], v[118:119], v[126:127]
	v_pk_add_f32 v[116:117], v[116:117], v[124:125]
	v_pk_add_f32 v[120:121], v[152:153], v[156:157]
	v_pk_add_f32 v[124:125], v[150:151], v[154:155]
	v_pk_add_f32 v[118:119], v[118:119], v[120:121]
	v_pk_add_f32 v[116:117], v[116:117], v[124:125]
	s_nop 0
	v_pk_mov_b32 v[120:121], v[116:117], v[118:119] op_sel:[1,0]
	v_mov_b32_e32 v117, v119
	v_pk_add_f32 v[116:117], v[120:121], v[116:117]
	s_nop 0
	v_add_f32_e32 v116, v116, v117
	v_fmamk_f32 v116, v116, 0x3a800000, v208
	v_mul_f32_e32 v117, 0x4b800000, v116
	v_cmp_gt_f32_e32 vcc, s15, v116
	s_nop 1
	v_cndmask_b32_e32 v116, v116, v117, vcc
	v_rsq_f32_e32 v116, v116
	s_nop 0
	v_mul_f32_e32 v117, 0x45800000, v116
	v_cndmask_b32_e32 v116, v116, v117, vcc

;     __device__ __forceinline__ void operator()(const f32x4 (&acc)[2][2][4][2], const Unit& u, int wr, int wc, int fr, int fq) const {
;     ...
;                 const int row = row0 + ai * 128 + m * 16; const float rs = (u.pm == pm0) ? RS[row & 255] : row_rstd(ss, row);
; #pragma unroll
;                 for (int bj = 0; bj < 2; ++bj) {
;                     f32x4 v[2], e[2];
; #pragma unroll
;                     for (int n = 0; n < 2; ++n) { v[n] = acc[ai][bj][m][n] * rs; e[n] = v[n] * ((v[n] * v[n]) * c3 + c1); }
;                     if (kind != 0) {
; #pragma unroll
;                         for (int n = 0; n < 2; ++n)
; #pragma unroll
;                             for (int j = 0; j < 4; ++j) e[n][j] = __builtin_amdgcn_exp2f(e[n][j]);
; #pragma unroll
;                         for (int n = 0; n < 2; ++n) e[n] = e[n] + 1.0f;
; #pragma unroll
;                         for (int n = 0; n < 2; ++n)
; #pragma unroll
;                             for (int j = 0; j < 4; ++j) e[n][j] = __builtin_amdgcn_rcpf(e[n][j]);
;                         if (kind == 1) { v[0] = v[0] * e[0]; v[1] = v[1] * e[1]; } else { v[0] = e[0]; v[1] = e[1]; }
.LBB0_515:
	v_mad_u64_u32 v[106:107], s[20:21], v114, s13, 0
	v_mov_b32_e32 v114, v107
	v_mad_u64_u32 v[114:115], s[20:21], v115, s13, v[114:115]
	v_mov_b32_e32 v117, v116
	v_mov_b32_e32 v107, v114
	v_cvt_pk_bf16_f32 v110, v110, v111
	v_cvt_pk_bf16_f32 v111, v112, v113
	v_cvt_pk_bf16_f32 v112, v118, v119
	v_cvt_pk_bf16_f32 v113, v108, v109
	v_mov_b32_e32 v108, v116
	v_mov_b32_e32 v109, v116
	v_lshl_add_u64 v[106:107], v[106:107], 1, v[122:123]
	v_pk_mul_f32 v[104:105], v[104:105], v[108:109]
	v_pk_mul_f32 v[102:103], v[102:103], v[116:117]
	v_pk_mul_f32 v[100:101], v[100:101], v[108:109]
	s_and_b64 vcc, exec, s[6:7]
	v_pk_mul_f32 v[98:99], v[98:99], v[116:117]
	global_store_dwordx4 v[106:107], v[110:113], off sc1
	s_cbranch_vccnz .LBB0_519
	v_pk_mul_f32 v[108:109], v[100:101], v[100:101]
	v_pk_mul_f32 v[110:111], v[98:99], v[98:99]
	v_mov_b32_e32 v112, v146
	v_mov_b32_e32 v113, v146
	v_mov_b32_e32 v114, v144
	v_mov_b32_e32 v115, v144
	v_pk_mul_f32 v[116:117], v[104:105], v[104:105]
	v_pk_mul_f32 v[118:119], v[102:103], v[102:103]
	v_pk_fma_f32 v[108:109], v[114:115], v[108:109], v[112:113]
	v_pk_fma_f32 v[110:111], v[144:145], v[110:111], v[146:147]
	v_pk_fma_f32 v[112:113], v[114:115], v[116:117], v[112:113]
	v_pk_fma_f32 v[114:115], v[144:145], v[118:119], v[146:147]
	v_pk_mul_f32 v[108:109], v[100:101], v[108:109]
	v_pk_mul_f32 v[110:111], v[98:99], v[110:111]
	v_pk_mul_f32 v[112:113], v[104:105], v[112:113]
	v_pk_mul_f32 v[114:115], v[102:103], v[114:115]
	v_exp_f32_e32 v112, v112
	v_exp_f32_e32 v114, v114
	v_exp_f32_e32 v115, v115
	v_exp_f32_e32 v113, v113
	v_exp_f32_e32 v110, v110
	v_exp_f32_e32 v108, v108
	v_exp_f32_e32 v109, v109
	v_exp_f32_e32 v111, v111
	v_pk_add_f32 v[112:113], v[112:113], 1.0 op_sel_hi:[1,0]
	v_pk_add_f32 v[114:115], v[114:115], 1.0 op_sel_hi:[1,0]
	v_pk_add_f32 v[116:117], v[108:109], 1.0 op_sel_hi:[1,0]
	v_pk_add_f32 v[118:119], v[110:111], 1.0 op_sel_hi:[1,0]
	v_rcp_f32_e32 v108, v114
	v_rcp_f32_e32 v109, v115
	v_rcp_f32_e32 v110, v112
	v_rcp_f32_e32 v111, v113
	v_rcp_f32_e32 v112, v118
	v_rcp_f32_e32 v113, v119
	v_rcp_f32_e32 v114, v116
	v_rcp_f32_e32 v115, v117
	s_and_b64 vcc, exec, s[4:5]
	s_cbranch_vccnz .LBB0_518
	v_pk_mul_f32 v[114:115], v[100:101], v[114:115]
	v_pk_mul_f32 v[112:113], v[98:99], v[112:113]
	v_pk_mul_f32 v[110:111], v[104:105], v[110:111]
	v_pk_mul_f32 v[108:109], v[102:103], v[108:109]

; __device__ __forceinline__ u32x4 pack8(const f32x4 a, const f32x4 b) { u32x4 w; w.x = cvt_pk_bf16(a[0], a[1]); w.y = cvt_pk_bf16(a[2], a[3]); w.z = cvt_pk_bf16(b[0], b[1]); w.w = cvt_pk_bf16(b[2], b[3]); return w; }
; __device__ __forceinline__ float row_rstd(const float* ss, int row) {
;     const f32x4* q = (const f32x4*)(ss + (size_t)row * 16); const f32x4 s4 = (q[0] + q[1]) + (q[2] + q[3]);
;     return rsqrtf(((s4[0] + s4[1]) + (s4[2] + s4[3])) * (1.0f / D) + EPS);
;     __device__ __forceinline__ void operator()(const f32x4 (&acc)[2][2][4][2], const Unit& u, int wr, int wc, int fr, int fq) const {
;     ...
;                     __builtin_nontemporal_store(pack8(v[0], v[1]), (u32x4*)(base + (size_t)row * ld + col0 + bj * 128));
.LBB0_519:
	v_cvt_pk_bf16_f32 v102, v102, v103
	v_cvt_pk_bf16_f32 v103, v104, v105
	v_cvt_pk_bf16_f32 v104, v98, v99
	v_or_b32_e32 v98, 32, v148
	s_mov_b64 s[20:21], -1
	s_and_b64 vcc, exec, s[8:9]
	v_ashrrev_i32_e32 v99, 31, v98
	v_cvt_pk_bf16_f32 v105, v100, v101
	global_store_dwordx4 v[106:107], v[102:105], off offset:256 sc1
	s_cbranch_vccnz .LBB0_521
	v_lshlrev_b64 v[100:101], 6, v[98:99]
	v_lshl_add_u64 v[112:113], s[80:81], 0, v[100:101]
	global_load_dwordx4 v[100:103], v[112:113], off
	global_load_dwordx4 v[104:107], v[112:113], off offset:16
	global_load_dwordx4 v[108:111], v[112:113], off offset:32
	s_nop 0
	global_load_dwordx4 v[112:115], v[112:113], off offset:48
	s_mov_b32 s15, 0x800000
	s_mov_b64 s[20:21], 0
	s_waitcnt vmcnt(0)
	v_pk_add_f32 v[102:103], v[102:103], v[106:107]
	v_pk_add_f32 v[100:101], v[100:101], v[104:105]
	v_pk_add_f32 v[104:105], v[110:111], v[114:115]
	v_pk_add_f32 v[106:107], v[108:109], v[112:113]
	v_pk_add_f32 v[102:103], v[102:103], v[104:105]
	v_pk_add_f32 v[100:101], v[100:101], v[106:107]
	s_nop 0
	v_pk_mov_b32 v[104:105], v[100:101], v[102:103] op_sel:[1,0]
	v_mov_b32_e32 v101, v103
	v_pk_add_f32 v[100:101], v[104:105], v[100:101]
	s_nop 0
	v_add_f32_e32 v100, v100, v101
	v_fmamk_f32 v100, v100, 0x3a800000, v208
	v_mul_f32_e32 v101, 0x4b800000, v100
	v_cmp_gt_f32_e32 vcc, s15, v100
	s_nop 1
	v_cndmask_b32_e32 v100, v100, v101, vcc
	v_rsq_f32_e32 v100, v100
	s_nop 0
	v_mul_f32_e32 v101, 0x45800000, v100
	v_cndmask_b32_e32 v100, v100, v101, vcc

;     __device__ __forceinline__ void operator()(const f32x4 (&acc)[2][2][4][2], const Unit& u, int wr, int wc, int fr, int fq) const {
;     ...
;                 const int row = row0 + ai * 128 + m * 16; const float rs = (u.pm == pm0) ? RS[row & 255] : row_rstd(ss, row);
; #pragma unroll
;                 for (int bj = 0; bj < 2; ++bj) {
;                     f32x4 v[2], e[2];
; #pragma unroll
;                     for (int n = 0; n < 2; ++n) { v[n] = acc[ai][bj][m][n] * rs; e[n] = v[n] * ((v[n] * v[n]) * c3 + c1); }
;                     if (kind != 0) {
; #pragma unroll
;                         for (int n = 0; n < 2; ++n)
; #pragma unroll
;                             for (int j = 0; j < 4; ++j) e[n][j] = __builtin_amdgcn_exp2f(e[n][j]);
; #pragma unroll
;                         for (int n = 0; n < 2; ++n) e[n] = e[n] + 1.0f;
; #pragma unroll
;                         for (int n = 0; n < 2; ++n)
; #pragma unroll
;                             for (int j = 0; j < 4; ++j) e[n][j] = __builtin_amdgcn_rcpf(e[n][j]);
;                         if (kind == 1) { v[0] = v[0] * e[0]; v[1] = v[1] * e[1]; } else { v[0] = e[0]; v[1] = e[1]; }
.LBB0_527:
	v_mad_u64_u32 v[90:91], s[20:21], v98, s13, 0
	v_mov_b32_e32 v98, v91
	v_mad_u64_u32 v[98:99], s[20:21], v99, s13, v[98:99]
	v_mov_b32_e32 v101, v100
	v_mov_b32_e32 v91, v98
	v_cvt_pk_bf16_f32 v94, v94, v95
	v_cvt_pk_bf16_f32 v95, v96, v97
	v_cvt_pk_bf16_f32 v96, v102, v103
	v_cvt_pk_bf16_f32 v97, v92, v93
	v_mov_b32_e32 v92, v100
	v_mov_b32_e32 v93, v100
	v_lshl_add_u64 v[90:91], v[90:91], 1, v[122:123]
	v_pk_mul_f32 v[88:89], v[88:89], v[92:93]
	v_pk_mul_f32 v[86:87], v[86:87], v[100:101]
	v_pk_mul_f32 v[84:85], v[84:85], v[92:93]
	s_and_b64 vcc, exec, s[6:7]
	v_pk_mul_f32 v[82:83], v[82:83], v[100:101]
	global_store_dwordx4 v[90:91], v[94:97], off sc1
	s_cbranch_vccnz .LBB0_531
	v_pk_mul_f32 v[92:93], v[84:85], v[84:85]
	v_pk_mul_f32 v[94:95], v[82:83], v[82:83]
	v_mov_b32_e32 v96, v146
	v_mov_b32_e32 v97, v146
	v_mov_b32_e32 v98, v144
	v_mov_b32_e32 v99, v144
	v_pk_mul_f32 v[100:101], v[88:89], v[88:89]
	v_pk_mul_f32 v[102:103], v[86:87], v[86:87]
	v_pk_fma_f32 v[92:93], v[98:99], v[92:93], v[96:97]
	v_pk_fma_f32 v[94:95], v[144:145], v[94:95], v[146:147]
	v_pk_fma_f32 v[96:97], v[98:99], v[100:101], v[96:97]
	v_pk_fma_f32 v[98:99], v[144:145], v[102:103], v[146:147]
	v_pk_mul_f32 v[92:93], v[84:85], v[92:93]
	v_pk_mul_f32 v[94:95], v[82:83], v[94:95]
	v_pk_mul_f32 v[96:97], v[88:89], v[96:97]
	v_pk_mul_f32 v[98:99], v[86:87], v[98:99]
	v_exp_f32_e32 v96, v96
	v_exp_f32_e32 v98, v98
	v_exp_f32_e32 v99, v99
	v_exp_f32_e32 v97, v97
	v_exp_f32_e32 v94, v94
	v_exp_f32_e32 v92, v92
	v_exp_f32_e32 v93, v93
	v_exp_f32_e32 v95, v95
	v_pk_add_f32 v[96:97], v[96:97], 1.0 op_sel_hi:[1,0]
	v_pk_add_f32 v[98:99], v[98:99], 1.0 op_sel_hi:[1,0]
	v_pk_add_f32 v[100:101], v[92:93], 1.0 op_sel_hi:[1,0]
	v_pk_add_f32 v[102:103], v[94:95], 1.0 op_sel_hi:[1,0]
	v_rcp_f32_e32 v92, v98
	v_rcp_f32_e32 v93, v99
	v_rcp_f32_e32 v94, v96
	v_rcp_f32_e32 v95, v97
	v_rcp_f32_e32 v96, v102
	v_rcp_f32_e32 v97, v103
	v_rcp_f32_e32 v98, v100
	v_rcp_f32_e32 v99, v101
	s_and_b64 vcc, exec, s[4:5]
	s_cbranch_vccnz .LBB0_530
	v_pk_mul_f32 v[98:99], v[84:85], v[98:99]
	v_pk_mul_f32 v[96:97], v[82:83], v[96:97]
	v_pk_mul_f32 v[94:95], v[88:89], v[94:95]
	v_pk_mul_f32 v[92:93], v[86:87], v[92:93]

; __device__ __forceinline__ u32x4 pack8(const f32x4 a, const f32x4 b) { u32x4 w; w.x = cvt_pk_bf16(a[0], a[1]); w.y = cvt_pk_bf16(a[2], a[3]); w.z = cvt_pk_bf16(b[0], b[1]); w.w = cvt_pk_bf16(b[2], b[3]); return w; }
; __device__ __forceinline__ float row_rstd(const float* ss, int row) {
;     const f32x4* q = (const f32x4*)(ss + (size_t)row * 16); const f32x4 s4 = (q[0] + q[1]) + (q[2] + q[3]);
;     return rsqrtf(((s4[0] + s4[1]) + (s4[2] + s4[3])) * (1.0f / D) + EPS);
;     __device__ __forceinline__ void operator()(const f32x4 (&acc)[2][2][4][2], const Unit& u, int wr, int wc, int fr, int fq) const {
;     ...
;                     __builtin_nontemporal_store(pack8(v[0], v[1]), (u32x4*)(base + (size_t)row * ld + col0 + bj * 128));
.LBB0_531:
	v_cvt_pk_bf16_f32 v86, v86, v87
	v_cvt_pk_bf16_f32 v87, v88, v89
	v_cvt_pk_bf16_f32 v88, v82, v83
	v_or_b32_e32 v82, 48, v148
	s_mov_b64 s[20:21], -1
	s_and_b64 vcc, exec, s[8:9]
	v_ashrrev_i32_e32 v83, 31, v82
	v_cvt_pk_bf16_f32 v89, v84, v85
	global_store_dwordx4 v[90:91], v[86:89], off offset:256 sc1
	s_cbranch_vccnz .LBB0_533
	v_lshlrev_b64 v[84:85], 6, v[82:83]
	v_lshl_add_u64 v[96:97], s[80:81], 0, v[84:85]
	global_load_dwordx4 v[84:87], v[96:97], off
	global_load_dwordx4 v[88:91], v[96:97], off offset:16
	global_load_dwordx4 v[92:95], v[96:97], off offset:32
	s_nop 0
	global_load_dwordx4 v[96:99], v[96:97], off offset:48
	s_mov_b32 s15, 0x800000
	s_mov_b64 s[20:21], 0
	s_waitcnt vmcnt(0)
	v_pk_add_f32 v[86:87], v[86:87], v[90:91]
	v_pk_add_f32 v[84:85], v[84:85], v[88:89]
	v_pk_add_f32 v[88:89], v[94:95], v[98:99]
	v_pk_add_f32 v[90:91], v[92:93], v[96:97]
	v_pk_add_f32 v[86:87], v[86:87], v[88:89]
	v_pk_add_f32 v[84:85], v[84:85], v[90:91]
	s_nop 0
	v_pk_mov_b32 v[88:89], v[84:85], v[86:87] op_sel:[1,0]
	v_mov_b32_e32 v85, v87
	v_pk_add_f32 v[84:85], v[88:89], v[84:85]
	s_nop 0
	v_add_f32_e32 v84, v84, v85
	v_fmamk_f32 v84, v84, 0x3a800000, v208
	v_mul_f32_e32 v85, 0x4b800000, v84
	v_cmp_gt_f32_e32 vcc, s15, v84
	s_nop 1
	v_cndmask_b32_e32 v84, v84, v85, vcc
	v_rsq_f32_e32 v84, v84
	s_nop 0
	v_mul_f32_e32 v85, 0x45800000, v84
	v_cndmask_b32_e32 v84, v84, v85, vcc

;     __device__ __forceinline__ void operator()(const f32x4 (&acc)[2][2][4][2], const Unit& u, int wr, int wc, int fr, int fq) const {
;     ...
;                 const int row = row0 + ai * 128 + m * 16; const float rs = (u.pm == pm0) ? RS[row & 255] : row_rstd(ss, row);
; #pragma unroll
;                 for (int bj = 0; bj < 2; ++bj) {
;                     f32x4 v[2], e[2];
; #pragma unroll
;                     for (int n = 0; n < 2; ++n) { v[n] = acc[ai][bj][m][n] * rs; e[n] = v[n] * ((v[n] * v[n]) * c3 + c1); }
;                     if (kind != 0) {
; #pragma unroll
;                         for (int n = 0; n < 2; ++n)
; #pragma unroll
;                             for (int j = 0; j < 4; ++j) e[n][j] = __builtin_amdgcn_exp2f(e[n][j]);
; #pragma unroll
;                         for (int n = 0; n < 2; ++n) e[n] = e[n] + 1.0f;
; #pragma unroll
;                         for (int n = 0; n < 2; ++n)
; #pragma unroll
;                             for (int j = 0; j < 4; ++j) e[n][j] = __builtin_amdgcn_rcpf(e[n][j]);
;                         if (kind == 1) { v[0] = v[0] * e[0]; v[1] = v[1] * e[1]; } else { v[0] = e[0]; v[1] = e[1]; }
.LBB0_539:
	v_mad_u64_u32 v[74:75], s[20:21], v82, s13, 0
	v_mov_b32_e32 v82, v75
	v_mad_u64_u32 v[82:83], s[20:21], v83, s13, v[82:83]
	v_mov_b32_e32 v85, v84
	v_mov_b32_e32 v75, v82
	v_cvt_pk_bf16_f32 v78, v78, v79
	v_cvt_pk_bf16_f32 v79, v80, v81
	v_cvt_pk_bf16_f32 v80, v86, v87
	v_cvt_pk_bf16_f32 v81, v76, v77
	v_mov_b32_e32 v76, v84
	v_mov_b32_e32 v77, v84
	v_lshl_add_u64 v[74:75], v[74:75], 1, v[122:123]
	v_pk_mul_f32 v[72:73], v[72:73], v[76:77]
	v_pk_mul_f32 v[70:71], v[70:71], v[84:85]
	v_pk_mul_f32 v[68:69], v[68:69], v[76:77]
	s_and_b64 vcc, exec, s[6:7]
	v_pk_mul_f32 v[66:67], v[66:67], v[84:85]
	global_store_dwordx4 v[74:75], v[78:81], off sc1
	s_cbranch_vccnz .LBB0_543
	v_pk_mul_f32 v[76:77], v[68:69], v[68:69]
	v_pk_mul_f32 v[78:79], v[66:67], v[66:67]
	v_mov_b32_e32 v80, v146
	v_mov_b32_e32 v81, v146
	v_mov_b32_e32 v82, v144
	v_mov_b32_e32 v83, v144
	v_pk_mul_f32 v[84:85], v[72:73], v[72:73]
	v_pk_mul_f32 v[86:87], v[70:71], v[70:71]
	v_pk_fma_f32 v[76:77], v[82:83], v[76:77], v[80:81]
	v_pk_fma_f32 v[78:79], v[144:145], v[78:79], v[146:147]
	v_pk_fma_f32 v[80:81], v[82:83], v[84:85], v[80:81]
	v_pk_fma_f32 v[82:83], v[144:145], v[86:87], v[146:147]
	v_pk_mul_f32 v[76:77], v[68:69], v[76:77]
	v_pk_mul_f32 v[78:79], v[66:67], v[78:79]
	v_pk_mul_f32 v[80:81], v[72:73], v[80:81]
	v_pk_mul_f32 v[82:83], v[70:71], v[82:83]
	v_exp_f32_e32 v80, v80
	v_exp_f32_e32 v82, v82
	v_exp_f32_e32 v83, v83
	v_exp_f32_e32 v81, v81
	v_exp_f32_e32 v78, v78
	v_exp_f32_e32 v76, v76
	v_exp_f32_e32 v77, v77
	v_exp_f32_e32 v79, v79
	v_pk_add_f32 v[80:81], v[80:81], 1.0 op_sel_hi:[1,0]
	v_pk_add_f32 v[82:83], v[82:83], 1.0 op_sel_hi:[1,0]
	v_pk_add_f32 v[84:85], v[76:77], 1.0 op_sel_hi:[1,0]
	v_pk_add_f32 v[86:87], v[78:79], 1.0 op_sel_hi:[1,0]
	v_rcp_f32_e32 v76, v82
	v_rcp_f32_e32 v77, v83
	v_rcp_f32_e32 v78, v80
	v_rcp_f32_e32 v79, v81
	v_rcp_f32_e32 v80, v86
	v_rcp_f32_e32 v81, v87
	v_rcp_f32_e32 v82, v84
	v_rcp_f32_e32 v83, v85
	s_and_b64 vcc, exec, s[4:5]
	s_cbranch_vccnz .LBB0_542
	v_pk_mul_f32 v[82:83], v[68:69], v[82:83]
	v_pk_mul_f32 v[80:81], v[66:67], v[80:81]
	v_pk_mul_f32 v[78:79], v[72:73], v[78:79]
	v_pk_mul_f32 v[76:77], v[70:71], v[76:77]

; __device__ __forceinline__ u32x4 pack8(const f32x4 a, const f32x4 b) { u32x4 w; w.x = cvt_pk_bf16(a[0], a[1]); w.y = cvt_pk_bf16(a[2], a[3]); w.z = cvt_pk_bf16(b[0], b[1]); w.w = cvt_pk_bf16(b[2], b[3]); return w; }
; __device__ __forceinline__ float row_rstd(const float* ss, int row) {
;     const f32x4* q = (const f32x4*)(ss + (size_t)row * 16); const f32x4 s4 = (q[0] + q[1]) + (q[2] + q[3]);
;     return rsqrtf(((s4[0] + s4[1]) + (s4[2] + s4[3])) * (1.0f / D) + EPS);
;     __device__ __forceinline__ void operator()(const f32x4 (&acc)[2][2][4][2], const Unit& u, int wr, int wc, int fr, int fq) const {
;     ...
;                     __builtin_nontemporal_store(pack8(v[0], v[1]), (u32x4*)(base + (size_t)row * ld + col0 + bj * 128));
.LBB0_543:
	v_cvt_pk_bf16_f32 v70, v70, v71
	v_cvt_pk_bf16_f32 v71, v72, v73
	v_cvt_pk_bf16_f32 v72, v66, v67
	v_add_u32_e32 v66, 0x80, v148
	s_mov_b64 s[20:21], -1
	s_and_b64 vcc, exec, s[8:9]
	v_ashrrev_i32_e32 v67, 31, v66
	v_cvt_pk_bf16_f32 v73, v68, v69
	global_store_dwordx4 v[74:75], v[70:73], off offset:256 sc1
	s_cbranch_vccnz .LBB0_545
	v_lshlrev_b64 v[68:69], 6, v[66:67]
	v_lshl_add_u64 v[80:81], s[80:81], 0, v[68:69]
	global_load_dwordx4 v[68:71], v[80:81], off
	global_load_dwordx4 v[72:75], v[80:81], off offset:16
	global_load_dwordx4 v[76:79], v[80:81], off offset:32
	s_nop 0
	global_load_dwordx4 v[80:83], v[80:81], off offset:48
	s_mov_b32 s15, 0x800000
	s_mov_b64 s[20:21], 0
	s_waitcnt vmcnt(0)
	v_pk_add_f32 v[70:71], v[70:71], v[74:75]
	v_pk_add_f32 v[68:69], v[68:69], v[72:73]
	v_pk_add_f32 v[72:73], v[78:79], v[82:83]
	v_pk_add_f32 v[74:75], v[76:77], v[80:81]
	v_pk_add_f32 v[70:71], v[70:71], v[72:73]
	v_pk_add_f32 v[68:69], v[68:69], v[74:75]
	s_nop 0
	v_pk_mov_b32 v[72:73], v[68:69], v[70:71] op_sel:[1,0]
	v_mov_b32_e32 v69, v71
	v_pk_add_f32 v[68:69], v[72:73], v[68:69]
	s_nop 0
	v_add_f32_e32 v68, v68, v69
	v_fmamk_f32 v68, v68, 0x3a800000, v208
	v_mul_f32_e32 v69, 0x4b800000, v68
	v_cmp_gt_f32_e32 vcc, s15, v68
	s_nop 1
	v_cndmask_b32_e32 v68, v68, v69, vcc
	v_rsq_f32_e32 v68, v68
	s_nop 0
	v_mul_f32_e32 v69, 0x45800000, v68
	v_cndmask_b32_e32 v68, v68, v69, vcc

;     __device__ __forceinline__ void operator()(const f32x4 (&acc)[2][2][4][2], const Unit& u, int wr, int wc, int fr, int fq) const {
;     ...
;                 const int row = row0 + ai * 128 + m * 16; const float rs = (u.pm == pm0) ? RS[row & 255] : row_rstd(ss, row);
; #pragma unroll
;                 for (int bj = 0; bj < 2; ++bj) {
;                     f32x4 v[2], e[2];
; #pragma unroll
;                     for (int n = 0; n < 2; ++n) { v[n] = acc[ai][bj][m][n] * rs; e[n] = v[n] * ((v[n] * v[n]) * c3 + c1); }
;                     if (kind != 0) {
; #pragma unroll
;                         for (int n = 0; n < 2; ++n)
; #pragma unroll
;                             for (int j = 0; j < 4; ++j) e[n][j] = __builtin_amdgcn_exp2f(e[n][j]);
; #pragma unroll
;                         for (int n = 0; n < 2; ++n) e[n] = e[n] + 1.0f;
; #pragma unroll
;                         for (int n = 0; n < 2; ++n)
; #pragma unroll
;                             for (int j = 0; j < 4; ++j) e[n][j] = __builtin_amdgcn_rcpf(e[n][j]);
;                         if (kind == 1) { v[0] = v[0] * e[0]; v[1] = v[1] * e[1]; } else { v[0] = e[0]; v[1] = e[1]; }
.LBB0_551:
	v_mad_u64_u32 v[58:59], s[20:21], v66, s13, 0
	v_mov_b32_e32 v66, v59
	v_mad_u64_u32 v[66:67], s[20:21], v67, s13, v[66:67]
	v_mov_b32_e32 v69, v68
	v_mov_b32_e32 v59, v66
	v_cvt_pk_bf16_f32 v62, v62, v63
	v_cvt_pk_bf16_f32 v63, v64, v65
	v_cvt_pk_bf16_f32 v64, v70, v71
	v_cvt_pk_bf16_f32 v65, v60, v61
	v_mov_b32_e32 v60, v68
	v_mov_b32_e32 v61, v68
	v_lshl_add_u64 v[58:59], v[58:59], 1, v[122:123]
	v_pk_mul_f32 v[56:57], v[56:57], v[60:61]
	v_pk_mul_f32 v[54:55], v[54:55], v[68:69]
	v_pk_mul_f32 v[52:53], v[52:53], v[60:61]
	s_and_b64 vcc, exec, s[6:7]
	v_pk_mul_f32 v[50:51], v[50:51], v[68:69]
	global_store_dwordx4 v[58:59], v[62:65], off sc1
	s_cbranch_vccnz .LBB0_555
	v_pk_mul_f32 v[60:61], v[52:53], v[52:53]
	v_pk_mul_f32 v[62:63], v[50:51], v[50:51]
	v_mov_b32_e32 v64, v146
	v_mov_b32_e32 v65, v146
	v_mov_b32_e32 v66, v144
	v_mov_b32_e32 v67, v144
	v_pk_mul_f32 v[68:69], v[56:57], v[56:57]
	v_pk_mul_f32 v[70:71], v[54:55], v[54:55]
	v_pk_fma_f32 v[60:61], v[66:67], v[60:61], v[64:65]
	v_pk_fma_f32 v[62:63], v[144:145], v[62:63], v[146:147]
	v_pk_fma_f32 v[64:65], v[66:67], v[68:69], v[64:65]
	v_pk_fma_f32 v[66:67], v[144:145], v[70:71], v[146:147]
	v_pk_mul_f32 v[60:61], v[52:53], v[60:61]
	v_pk_mul_f32 v[62:63], v[50:51], v[62:63]
	v_pk_mul_f32 v[64:65], v[56:57], v[64:65]
	v_pk_mul_f32 v[66:67], v[54:55], v[66:67]
	v_exp_f32_e32 v64, v64
	v_exp_f32_e32 v66, v66
	v_exp_f32_e32 v67, v67
	v_exp_f32_e32 v65, v65
	v_exp_f32_e32 v62, v62
	v_exp_f32_e32 v60, v60
	v_exp_f32_e32 v61, v61
	v_exp_f32_e32 v63, v63
	v_pk_add_f32 v[64:65], v[64:65], 1.0 op_sel_hi:[1,0]
	v_pk_add_f32 v[66:67], v[66:67], 1.0 op_sel_hi:[1,0]
	v_pk_add_f32 v[68:69], v[60:61], 1.0 op_sel_hi:[1,0]
	v_pk_add_f32 v[70:71], v[62:63], 1.0 op_sel_hi:[1,0]
	v_rcp_f32_e32 v60, v66
	v_rcp_f32_e32 v61, v67
	v_rcp_f32_e32 v62, v64
	v_rcp_f32_e32 v63, v65
	v_rcp_f32_e32 v64, v70
	v_rcp_f32_e32 v65, v71
	v_rcp_f32_e32 v66, v68
	v_rcp_f32_e32 v67, v69
	s_and_b64 vcc, exec, s[4:5]
	s_cbranch_vccnz .LBB0_554
	v_pk_mul_f32 v[66:67], v[52:53], v[66:67]
	v_pk_mul_f32 v[64:65], v[50:51], v[64:65]
	v_pk_mul_f32 v[62:63], v[56:57], v[62:63]
	v_pk_mul_f32 v[60:61], v[54:55], v[60:61]

; __device__ __forceinline__ u32x4 pack8(const f32x4 a, const f32x4 b) { u32x4 w; w.x = cvt_pk_bf16(a[0], a[1]); w.y = cvt_pk_bf16(a[2], a[3]); w.z = cvt_pk_bf16(b[0], b[1]); w.w = cvt_pk_bf16(b[2], b[3]); return w; }
; __device__ __forceinline__ float row_rstd(const float* ss, int row) {
;     const f32x4* q = (const f32x4*)(ss + (size_t)row * 16); const f32x4 s4 = (q[0] + q[1]) + (q[2] + q[3]);
;     return rsqrtf(((s4[0] + s4[1]) + (s4[2] + s4[3])) * (1.0f / D) + EPS);
;     __device__ __forceinline__ void operator()(const f32x4 (&acc)[2][2][4][2], const Unit& u, int wr, int wc, int fr, int fq) const {
;     ...
;                     __builtin_nontemporal_store(pack8(v[0], v[1]), (u32x4*)(base + (size_t)row * ld + col0 + bj * 128));
.LBB0_555:
	v_cvt_pk_bf16_f32 v54, v54, v55
	v_cvt_pk_bf16_f32 v55, v56, v57
	v_cvt_pk_bf16_f32 v56, v50, v51
	v_add_u32_e32 v50, 0x90, v148
	s_mov_b64 s[20:21], -1
	s_and_b64 vcc, exec, s[8:9]
	v_ashrrev_i32_e32 v51, 31, v50
	v_cvt_pk_bf16_f32 v57, v52, v53
	global_store_dwordx4 v[58:59], v[54:57], off offset:256 sc1
	s_cbranch_vccnz .LBB0_557
	v_lshlrev_b64 v[52:53], 6, v[50:51]
	v_lshl_add_u64 v[64:65], s[80:81], 0, v[52:53]
	global_load_dwordx4 v[52:55], v[64:65], off
	global_load_dwordx4 v[56:59], v[64:65], off offset:16
	global_load_dwordx4 v[60:63], v[64:65], off offset:32
	s_nop 0
	global_load_dwordx4 v[64:67], v[64:65], off offset:48
	s_mov_b32 s15, 0x800000
	s_mov_b64 s[20:21], 0
	s_waitcnt vmcnt(0)
	v_pk_add_f32 v[54:55], v[54:55], v[58:59]
	v_pk_add_f32 v[52:53], v[52:53], v[56:57]
	v_pk_add_f32 v[56:57], v[62:63], v[66:67]
	v_pk_add_f32 v[58:59], v[60:61], v[64:65]
	v_pk_add_f32 v[54:55], v[54:55], v[56:57]
	v_pk_add_f32 v[52:53], v[52:53], v[58:59]
	s_nop 0
	v_pk_mov_b32 v[56:57], v[52:53], v[54:55] op_sel:[1,0]
	v_mov_b32_e32 v53, v55
	v_pk_add_f32 v[52:53], v[56:57], v[52:53]
	s_nop 0
	v_add_f32_e32 v52, v52, v53
	v_fmamk_f32 v52, v52, 0x3a800000, v208
	v_mul_f32_e32 v53, 0x4b800000, v52
	v_cmp_gt_f32_e32 vcc, s15, v52
	s_nop 1
	v_cndmask_b32_e32 v52, v52, v53, vcc
	v_rsq_f32_e32 v52, v52
	s_nop 0
	v_mul_f32_e32 v53, 0x45800000, v52
	v_cndmask_b32_e32 v52, v52, v53, vcc

;     __device__ __forceinline__ void operator()(const f32x4 (&acc)[2][2][4][2], const Unit& u, int wr, int wc, int fr, int fq) const {
;     ...
;                 const int row = row0 + ai * 128 + m * 16; const float rs = (u.pm == pm0) ? RS[row & 255] : row_rstd(ss, row);
; #pragma unroll
;                 for (int bj = 0; bj < 2; ++bj) {
;                     f32x4 v[2], e[2];
; #pragma unroll
;                     for (int n = 0; n < 2; ++n) { v[n] = acc[ai][bj][m][n] * rs; e[n] = v[n] * ((v[n] * v[n]) * c3 + c1); }
;                     if (kind != 0) {
; #pragma unroll
;                         for (int n = 0; n < 2; ++n)
; #pragma unroll
;                             for (int j = 0; j < 4; ++j) e[n][j] = __builtin_amdgcn_exp2f(e[n][j]);
; #pragma unroll
;                         for (int n = 0; n < 2; ++n) e[n] = e[n] + 1.0f;
; #pragma unroll
;                         for (int n = 0; n < 2; ++n)
; #pragma unroll
;                             for (int j = 0; j < 4; ++j) e[n][j] = __builtin_amdgcn_rcpf(e[n][j]);
;                         if (kind == 1) { v[0] = v[0] * e[0]; v[1] = v[1] * e[1]; } else { v[0] = e[0]; v[1] = e[1]; }
.LBB0_563:
	v_mad_u64_u32 v[42:43], s[20:21], v50, s13, 0
	v_mov_b32_e32 v50, v43
	v_mad_u64_u32 v[50:51], s[20:21], v51, s13, v[50:51]
	v_mov_b32_e32 v53, v52
	v_mov_b32_e32 v43, v50
	v_cvt_pk_bf16_f32 v46, v46, v47
	v_cvt_pk_bf16_f32 v47, v48, v49
	v_cvt_pk_bf16_f32 v48, v54, v55
	v_cvt_pk_bf16_f32 v49, v44, v45
	v_mov_b32_e32 v44, v52
	v_mov_b32_e32 v45, v52
	v_lshl_add_u64 v[42:43], v[42:43], 1, v[122:123]
	v_pk_mul_f32 v[40:41], v[40:41], v[44:45]
	v_pk_mul_f32 v[38:39], v[38:39], v[52:53]
	v_pk_mul_f32 v[36:37], v[36:37], v[44:45]
	s_and_b64 vcc, exec, s[6:7]
	v_pk_mul_f32 v[34:35], v[34:35], v[52:53]
	global_store_dwordx4 v[42:43], v[46:49], off sc1
	s_cbranch_vccnz .LBB0_567
	v_pk_mul_f32 v[44:45], v[36:37], v[36:37]
	v_pk_mul_f32 v[46:47], v[34:35], v[34:35]
	v_mov_b32_e32 v48, v146
	v_mov_b32_e32 v49, v146
	v_mov_b32_e32 v50, v144
	v_mov_b32_e32 v51, v144
	v_pk_mul_f32 v[52:53], v[40:41], v[40:41]
	v_pk_mul_f32 v[54:55], v[38:39], v[38:39]
	v_pk_fma_f32 v[44:45], v[50:51], v[44:45], v[48:49]
	v_pk_fma_f32 v[46:47], v[144:145], v[46:47], v[146:147]
	v_pk_fma_f32 v[48:49], v[50:51], v[52:53], v[48:49]
	v_pk_fma_f32 v[50:51], v[144:145], v[54:55], v[146:147]
	v_pk_mul_f32 v[44:45], v[36:37], v[44:45]
	v_pk_mul_f32 v[46:47], v[34:35], v[46:47]
	v_pk_mul_f32 v[48:49], v[40:41], v[48:49]
	v_pk_mul_f32 v[50:51], v[38:39], v[50:51]
	v_exp_f32_e32 v48, v48
	v_exp_f32_e32 v50, v50
	v_exp_f32_e32 v51, v51
	v_exp_f32_e32 v49, v49
	v_exp_f32_e32 v46, v46
	v_exp_f32_e32 v44, v44
	v_exp_f32_e32 v45, v45
	v_exp_f32_e32 v47, v47
	v_pk_add_f32 v[48:49], v[48:49], 1.0 op_sel_hi:[1,0]
	v_pk_add_f32 v[50:51], v[50:51], 1.0 op_sel_hi:[1,0]
	v_pk_add_f32 v[52:53], v[44:45], 1.0 op_sel_hi:[1,0]
	v_pk_add_f32 v[54:55], v[46:47], 1.0 op_sel_hi:[1,0]
	v_rcp_f32_e32 v44, v50
	v_rcp_f32_e32 v45, v51
	v_rcp_f32_e32 v46, v48
	v_rcp_f32_e32 v47, v49
	v_rcp_f32_e32 v48, v54
	v_rcp_f32_e32 v49, v55
	v_rcp_f32_e32 v50, v52
	v_rcp_f32_e32 v51, v53
	s_and_b64 vcc, exec, s[4:5]
	s_cbranch_vccnz .LBB0_566
	v_pk_mul_f32 v[50:51], v[36:37], v[50:51]
	v_pk_mul_f32 v[48:49], v[34:35], v[48:49]
	v_pk_mul_f32 v[46:47], v[40:41], v[46:47]
	v_pk_mul_f32 v[44:45], v[38:39], v[44:45]

; __device__ __forceinline__ u32x4 pack8(const f32x4 a, const f32x4 b) { u32x4 w; w.x = cvt_pk_bf16(a[0], a[1]); w.y = cvt_pk_bf16(a[2], a[3]); w.z = cvt_pk_bf16(b[0], b[1]); w.w = cvt_pk_bf16(b[2], b[3]); return w; }
; __device__ __forceinline__ float row_rstd(const float* ss, int row) {
;     const f32x4* q = (const f32x4*)(ss + (size_t)row * 16); const f32x4 s4 = (q[0] + q[1]) + (q[2] + q[3]);
;     return rsqrtf(((s4[0] + s4[1]) + (s4[2] + s4[3])) * (1.0f / D) + EPS);
;     __device__ __forceinline__ void operator()(const f32x4 (&acc)[2][2][4][2], const Unit& u, int wr, int wc, int fr, int fq) const {
;     ...
;                     __builtin_nontemporal_store(pack8(v[0], v[1]), (u32x4*)(base + (size_t)row * ld + col0 + bj * 128));
.LBB0_567:
	v_cvt_pk_bf16_f32 v38, v38, v39
	v_cvt_pk_bf16_f32 v39, v40, v41
	v_cvt_pk_bf16_f32 v40, v34, v35
	v_add_u32_e32 v34, 0xa0, v148
	s_mov_b64 s[20:21], -1
	s_and_b64 vcc, exec, s[8:9]
	v_ashrrev_i32_e32 v35, 31, v34
	v_cvt_pk_bf16_f32 v41, v36, v37
	global_store_dwordx4 v[42:43], v[38:41], off offset:256 sc1
	s_cbranch_vccnz .LBB0_569
	v_lshlrev_b64 v[36:37], 6, v[34:35]
	v_lshl_add_u64 v[48:49], s[80:81], 0, v[36:37]
	global_load_dwordx4 v[36:39], v[48:49], off
	global_load_dwordx4 v[40:43], v[48:49], off offset:16
	global_load_dwordx4 v[44:47], v[48:49], off offset:32
	s_nop 0
	global_load_dwordx4 v[48:51], v[48:49], off offset:48
	s_mov_b32 s15, 0x800000
	s_mov_b64 s[20:21], 0
	s_waitcnt vmcnt(0)
	v_pk_add_f32 v[38:39], v[38:39], v[42:43]
	v_pk_add_f32 v[36:37], v[36:37], v[40:41]
	v_pk_add_f32 v[40:41], v[46:47], v[50:51]
	v_pk_add_f32 v[42:43], v[44:45], v[48:49]
	v_pk_add_f32 v[38:39], v[38:39], v[40:41]
	v_pk_add_f32 v[36:37], v[36:37], v[42:43]
	s_nop 0
	v_pk_mov_b32 v[40:41], v[36:37], v[38:39] op_sel:[1,0]
	v_mov_b32_e32 v37, v39
	v_pk_add_f32 v[36:37], v[40:41], v[36:37]
	s_nop 0
	v_add_f32_e32 v36, v36, v37
	v_fmamk_f32 v36, v36, 0x3a800000, v208
	v_mul_f32_e32 v37, 0x4b800000, v36
	v_cmp_gt_f32_e32 vcc, s15, v36
	s_nop 1
	v_cndmask_b32_e32 v36, v36, v37, vcc
	v_rsq_f32_e32 v36, v36
	s_nop 0
	v_mul_f32_e32 v37, 0x45800000, v36
	v_cndmask_b32_e32 v36, v36, v37, vcc

;     __device__ __forceinline__ void operator()(const f32x4 (&acc)[2][2][4][2], const Unit& u, int wr, int wc, int fr, int fq) const {
;     ...
;                 const int row = row0 + ai * 128 + m * 16; const float rs = (u.pm == pm0) ? RS[row & 255] : row_rstd(ss, row);
; #pragma unroll
;                 for (int bj = 0; bj < 2; ++bj) {
;                     f32x4 v[2], e[2];
; #pragma unroll
;                     for (int n = 0; n < 2; ++n) { v[n] = acc[ai][bj][m][n] * rs; e[n] = v[n] * ((v[n] * v[n]) * c3 + c1); }
;                     if (kind != 0) {
; #pragma unroll
;                         for (int n = 0; n < 2; ++n)
; #pragma unroll
;                             for (int j = 0; j < 4; ++j) e[n][j] = __builtin_amdgcn_exp2f(e[n][j]);
; #pragma unroll
;                         for (int n = 0; n < 2; ++n) e[n] = e[n] + 1.0f;
; #pragma unroll
;                         for (int n = 0; n < 2; ++n)
; #pragma unroll
;                             for (int j = 0; j < 4; ++j) e[n][j] = __builtin_amdgcn_rcpf(e[n][j]);
;                         if (kind == 1) { v[0] = v[0] * e[0]; v[1] = v[1] * e[1]; } else { v[0] = e[0]; v[1] = e[1]; }
.LBB0_575:
	v_mad_u64_u32 v[26:27], s[20:21], v34, s13, 0
	v_mov_b32_e32 v34, v27
	v_mad_u64_u32 v[34:35], s[20:21], v35, s13, v[34:35]
	v_mov_b32_e32 v37, v36
	v_mov_b32_e32 v27, v34
	v_cvt_pk_bf16_f32 v30, v30, v31
	v_cvt_pk_bf16_f32 v31, v32, v33
	v_cvt_pk_bf16_f32 v32, v38, v39
	v_cvt_pk_bf16_f32 v33, v28, v29
	v_mov_b32_e32 v28, v36
	v_mov_b32_e32 v29, v36
	v_lshl_add_u64 v[26:27], v[26:27], 1, v[122:123]
	v_pk_mul_f32 v[24:25], v[24:25], v[28:29]
	v_pk_mul_f32 v[22:23], v[22:23], v[36:37]
	v_pk_mul_f32 v[20:21], v[20:21], v[28:29]
	s_and_b64 vcc, exec, s[6:7]
	v_pk_mul_f32 v[18:19], v[18:19], v[36:37]
	global_store_dwordx4 v[26:27], v[30:33], off sc1
	s_cbranch_vccnz .LBB0_579
	v_pk_mul_f32 v[28:29], v[20:21], v[20:21]
	v_pk_mul_f32 v[30:31], v[18:19], v[18:19]
	v_mov_b32_e32 v32, v146
	v_mov_b32_e32 v33, v146
	v_mov_b32_e32 v34, v144
	v_mov_b32_e32 v35, v144
	v_pk_mul_f32 v[36:37], v[24:25], v[24:25]
	v_pk_mul_f32 v[38:39], v[22:23], v[22:23]
	v_pk_fma_f32 v[28:29], v[34:35], v[28:29], v[32:33]
	v_pk_fma_f32 v[30:31], v[144:145], v[30:31], v[146:147]
	v_pk_fma_f32 v[32:33], v[34:35], v[36:37], v[32:33]
	v_pk_fma_f32 v[34:35], v[144:145], v[38:39], v[146:147]
	v_pk_mul_f32 v[28:29], v[20:21], v[28:29]
	v_pk_mul_f32 v[30:31], v[18:19], v[30:31]
	v_pk_mul_f32 v[32:33], v[24:25], v[32:33]
	v_pk_mul_f32 v[34:35], v[22:23], v[34:35]
	v_exp_f32_e32 v32, v32
	v_exp_f32_e32 v34, v34
	v_exp_f32_e32 v35, v35
	v_exp_f32_e32 v33, v33
	v_exp_f32_e32 v30, v30
	v_exp_f32_e32 v28, v28
	v_exp_f32_e32 v29, v29
	v_exp_f32_e32 v31, v31
	v_pk_add_f32 v[32:33], v[32:33], 1.0 op_sel_hi:[1,0]
	v_pk_add_f32 v[34:35], v[34:35], 1.0 op_sel_hi:[1,0]
	v_pk_add_f32 v[36:37], v[28:29], 1.0 op_sel_hi:[1,0]
	v_pk_add_f32 v[38:39], v[30:31], 1.0 op_sel_hi:[1,0]
	v_rcp_f32_e32 v28, v34
	v_rcp_f32_e32 v29, v35
	v_rcp_f32_e32 v30, v32
	v_rcp_f32_e32 v31, v33
	v_rcp_f32_e32 v32, v38
	v_rcp_f32_e32 v33, v39
	v_rcp_f32_e32 v34, v36
	v_rcp_f32_e32 v35, v37
	s_and_b64 vcc, exec, s[4:5]
	s_cbranch_vccnz .LBB0_578
	v_pk_mul_f32 v[34:35], v[20:21], v[34:35]
	v_pk_mul_f32 v[32:33], v[18:19], v[32:33]
	v_pk_mul_f32 v[30:31], v[24:25], v[30:31]
	v_pk_mul_f32 v[28:29], v[22:23], v[28:29]

; __device__ __forceinline__ u32x4 pack8(const f32x4 a, const f32x4 b) { u32x4 w; w.x = cvt_pk_bf16(a[0], a[1]); w.y = cvt_pk_bf16(a[2], a[3]); w.z = cvt_pk_bf16(b[0], b[1]); w.w = cvt_pk_bf16(b[2], b[3]); return w; }
; __device__ __forceinline__ float row_rstd(const float* ss, int row) {
;     const f32x4* q = (const f32x4*)(ss + (size_t)row * 16); const f32x4 s4 = (q[0] + q[1]) + (q[2] + q[3]);
;     return rsqrtf(((s4[0] + s4[1]) + (s4[2] + s4[3])) * (1.0f / D) + EPS);
;     __device__ __forceinline__ void operator()(const f32x4 (&acc)[2][2][4][2], const Unit& u, int wr, int wc, int fr, int fq) const {
;     ...
;                     __builtin_nontemporal_store(pack8(v[0], v[1]), (u32x4*)(base + (size_t)row * ld + col0 + bj * 128));
.LBB0_579:
	v_cvt_pk_bf16_f32 v22, v22, v23
	v_cvt_pk_bf16_f32 v23, v24, v25
	v_cvt_pk_bf16_f32 v24, v18, v19
	v_add_u32_e32 v18, 0xb0, v148
	s_mov_b64 s[20:21], -1
	s_and_b64 vcc, exec, s[8:9]
	v_ashrrev_i32_e32 v19, 31, v18
	v_cvt_pk_bf16_f32 v25, v20, v21
	global_store_dwordx4 v[26:27], v[22:25], off offset:256 sc1
	s_cbranch_vccnz .LBB0_581
	v_lshlrev_b64 v[20:21], 6, v[18:19]
	v_lshl_add_u64 v[32:33], s[80:81], 0, v[20:21]
	global_load_dwordx4 v[20:23], v[32:33], off
	global_load_dwordx4 v[24:27], v[32:33], off offset:16
	global_load_dwordx4 v[28:31], v[32:33], off offset:32
	s_nop 0
	global_load_dwordx4 v[32:35], v[32:33], off offset:48
	s_mov_b32 s8, 0x800000
	s_mov_b64 s[20:21], 0
	s_waitcnt vmcnt(0)
	v_pk_add_f32 v[22:23], v[22:23], v[26:27]
	v_pk_add_f32 v[20:21], v[20:21], v[24:25]
	v_pk_add_f32 v[24:25], v[30:31], v[34:35]
	v_pk_add_f32 v[26:27], v[28:29], v[32:33]
	v_pk_add_f32 v[22:23], v[22:23], v[24:25]
	v_pk_add_f32 v[20:21], v[20:21], v[26:27]
	s_nop 0
	v_pk_mov_b32 v[24:25], v[20:21], v[22:23] op_sel:[1,0]
	v_mov_b32_e32 v21, v23
	v_pk_add_f32 v[20:21], v[24:25], v[20:21]
	s_nop 0
	v_add_f32_e32 v20, v20, v21
	v_fmamk_f32 v20, v20, 0x3a800000, v208
	v_mul_f32_e32 v21, 0x4b800000, v20
	v_cmp_gt_f32_e32 vcc, s8, v20
	s_nop 1
	v_cndmask_b32_e32 v20, v20, v21, vcc
	v_rsq_f32_e32 v20, v20
	s_nop 0
	v_mul_f32_e32 v21, 0x45800000, v20
	v_cndmask_b32_e32 v20, v20, v21, vcc

;     __device__ __forceinline__ void operator()(const f32x4 (&acc)[2][2][4][2], const Unit& u, int wr, int wc, int fr, int fq) const {
;     ...
;                 const int row = row0 + ai * 128 + m * 16; const float rs = (u.pm == pm0) ? RS[row & 255] : row_rstd(ss, row);
; #pragma unroll
;                 for (int bj = 0; bj < 2; ++bj) {
;                     f32x4 v[2], e[2];
; #pragma unroll
;                     for (int n = 0; n < 2; ++n) { v[n] = acc[ai][bj][m][n] * rs; e[n] = v[n] * ((v[n] * v[n]) * c3 + c1); }
;                     if (kind != 0) {
; #pragma unroll
;                         for (int n = 0; n < 2; ++n)
; #pragma unroll
;                             for (int j = 0; j < 4; ++j) e[n][j] = __builtin_amdgcn_exp2f(e[n][j]);
; #pragma unroll
;                         for (int n = 0; n < 2; ++n) e[n] = e[n] + 1.0f;
; #pragma unroll
;                         for (int n = 0; n < 2; ++n)
; #pragma unroll
;                             for (int j = 0; j < 4; ++j) e[n][j] = __builtin_amdgcn_rcpf(e[n][j]);
;                         if (kind == 1) { v[0] = v[0] * e[0]; v[1] = v[1] * e[1]; } else { v[0] = e[0]; v[1] = e[1]; }
.LBB0_587:
	v_mad_u64_u32 v[10:11], s[8:9], v18, s13, 0
	v_mov_b32_e32 v18, v11
	v_mad_u64_u32 v[18:19], s[8:9], v19, s13, v[18:19]
	v_mov_b32_e32 v21, v20
	v_mov_b32_e32 v11, v18
	v_cvt_pk_bf16_f32 v14, v14, v15
	v_cvt_pk_bf16_f32 v15, v16, v17
	v_cvt_pk_bf16_f32 v16, v22, v23
	v_cvt_pk_bf16_f32 v17, v12, v13
	v_mov_b32_e32 v12, v20
	v_mov_b32_e32 v13, v20
	v_lshl_add_u64 v[10:11], v[10:11], 1, v[122:123]
	v_pk_mul_f32 v[8:9], v[8:9], v[12:13]
	v_pk_mul_f32 v[6:7], v[6:7], v[20:21]
	v_pk_mul_f32 v[4:5], v[4:5], v[12:13]
	s_and_b64 vcc, exec, s[6:7]
	v_pk_mul_f32 v[2:3], v[2:3], v[20:21]
	global_store_dwordx4 v[10:11], v[14:17], off sc1
	s_cbranch_vccnz .LBB0_591
	v_pk_mul_f32 v[12:13], v[8:9], v[8:9]
	v_pk_mul_f32 v[14:15], v[6:7], v[6:7]
	v_mov_b32_e32 v16, v146
	v_mov_b32_e32 v17, v146
	v_mov_b32_e32 v18, v144
	v_mov_b32_e32 v19, v144
	v_pk_mul_f32 v[20:21], v[4:5], v[4:5]
	v_pk_mul_f32 v[22:23], v[2:3], v[2:3]
	v_pk_fma_f32 v[12:13], v[18:19], v[12:13], v[16:17]
	v_pk_fma_f32 v[14:15], v[144:145], v[14:15], v[146:147]
	v_pk_fma_f32 v[16:17], v[18:19], v[20:21], v[16:17]
	v_pk_fma_f32 v[18:19], v[144:145], v[22:23], v[146:147]
	v_pk_mul_f32 v[12:13], v[8:9], v[12:13]
	v_pk_mul_f32 v[14:15], v[6:7], v[14:15]
	v_pk_mul_f32 v[16:17], v[4:5], v[16:17]
	v_pk_mul_f32 v[18:19], v[2:3], v[18:19]
	v_exp_f32_e32 v14, v14
	v_exp_f32_e32 v15, v15
	v_exp_f32_e32 v12, v12
	v_exp_f32_e32 v13, v13
	v_exp_f32_e32 v18, v18
	v_exp_f32_e32 v16, v16
	v_exp_f32_e32 v17, v17
	v_exp_f32_e32 v19, v19
	v_pk_add_f32 v[20:21], v[12:13], 1.0 op_sel_hi:[1,0]
	v_pk_add_f32 v[12:13], v[14:15], 1.0 op_sel_hi:[1,0]
	v_pk_add_f32 v[22:23], v[16:17], 1.0 op_sel_hi:[1,0]
	v_pk_add_f32 v[16:17], v[18:19], 1.0 op_sel_hi:[1,0]
	v_rcp_f32_e32 v12, v12
	v_rcp_f32_e32 v13, v13
	v_rcp_f32_e32 v14, v20
	v_rcp_f32_e32 v15, v21
	v_rcp_f32_e32 v16, v16
	v_rcp_f32_e32 v17, v17
	v_rcp_f32_e32 v18, v22
	v_rcp_f32_e32 v19, v23
	s_and_b64 vcc, exec, s[4:5]
	s_cbranch_vccnz .LBB0_590
	v_pk_mul_f32 v[18:19], v[4:5], v[18:19]
	v_pk_mul_f32 v[16:17], v[2:3], v[16:17]
	v_pk_mul_f32 v[14:15], v[8:9], v[14:15]
	v_pk_mul_f32 v[12:13], v[6:7], v[12:13]

; __device__ __forceinline__ u32x4 pack8(const f32x4 a, const f32x4 b) { u32x4 w; w.x = cvt_pk_bf16(a[0], a[1]); w.y = cvt_pk_bf16(a[2], a[3]); w.z = cvt_pk_bf16(b[0], b[1]); w.w = cvt_pk_bf16(b[2], b[3]); return w; }
; template <class Epi, class Sched, bool ALIGN_EPI = false, bool SP2 = false>
; __device__ __forceinline__ void gemm_phase(PG8_LAS unsigned char* lds, const Gemm g, const Sched& S, const Epi& E) {
;     ...
;         if constexpr (!Epi::AFTER_DRAIN) { E(acc, cur, wr, wc, fr, fq); S.done(cur); }
;         if (!has_next) break;
;     __device__ __forceinline__ void operator()(const f32x4 (&acc)[2][2][4][2], const Unit& u, int wr, int wc, int fr, int fq) const {
;     ...
;                     __builtin_nontemporal_store(pack8(v[0], v[1]), (u32x4*)(base + (size_t)row * ld + col0 + bj * 128));
.LBB0_591:
	s_andn2_b64 vcc, exec, s[2:3]
	s_mov_b64 s[2:3], -1
	v_cvt_pk_bf16_f32 v6, v6, v7
	v_cvt_pk_bf16_f32 v7, v8, v9
	v_cvt_pk_bf16_f32 v8, v2, v3
	v_cvt_pk_bf16_f32 v9, v4, v5
	global_store_dwordx4 v[10:11], v[6:9], off offset:256 sc1
	s_cbranch_vccnz .LBB0_488
	s_andn2_b64 vcc, exec, s[0:1]
	s_cbranch_vccnz .LBB0_487
	s_barrier
	s_branch .LBB0_487

; #define LAS __attribute__((address_space(3)))
; __device__ __forceinline__ unsigned cvt_pk_bf16(float lo, float hi) { unsigned r; asm volatile("v_cvt_pk_bf16_f32 %0, %1, %2" : "=v"(r) : "v"(lo), "v"(hi)); return r; }
; __device__ __forceinline__ float bflo(unsigned w) { return __uint_as_float(w << 16); }
; __device__ __forceinline__ float bfhi(unsigned w) { return __uint_as_float(w & 0xffff0000u); }
; template <int PASS> __device__ __forceinline__ void lru_wave_item(LAS unsigned char* lds, LAS unsigned char* vw, int b, int c, int h, const MixP& p, int lane, float (&Hrun)[8], bool cont) {
;     ...
;     const bf16_t* ub = p.P1 + (size_t)(b * SEQ) * P1W + PW + h * 128 + cg * 8;
; #pragma unroll 1
;     for (int st = 0; st < CT / 16; ++st) {
;         const int s0 = c * CT + 16 * st;
;         u32x4 ur[7];
;         {
;             const int sb = s0 + 4 * fq - 3;
; #pragma unroll
;             for (int r = 0; r < 7; ++r) ur[r] = *(const u32x4*)(ub + (size_t)max(sb + r, 0) * P1W);
;         }
;         if (s0 == 0 && fq == 0) {
; #pragma unroll
;             for (int r = 0; r < 3; ++r) ur[r] = (u32x4){0u, 0u, 0u, 0u};
;         }
; #pragma unroll
;         for (int jj = 0; jj < 4; ++jj) {
;             f32x2 o[4] = {bv[0], bv[1], bv[2], bv[3]};
; #pragma unroll
;             for (int k = 0; k < 4; ++k) { const u32x4 uk = ur[jj + k];
;                 o[0] = wv[k][0] * (f32x2){bflo(uk.x), bfhi(uk.x)} + o[0]; o[1] = wv[k][1] * (f32x2){bflo(uk.y), bfhi(uk.y)} + o[1];
;                 o[2] = wv[k][2] * (f32x2){bflo(uk.z), bfhi(uk.z)} + o[2]; o[3] = wv[k][3] * (f32x2){bflo(uk.w), bfhi(uk.w)} + o[3]; }
;             { u32x4 w; w.x = cvt_pk_bf16(o[0].x, o[0].y); w.y = cvt_pk_bf16(o[1].x, o[1].y); w.z = cvt_pk_bf16(o[2].x, o[2].y); w.w = cvt_pk_bf16(o[3].x, o[3].y);
;               *(LAS u32x4*)(vw + (4 * fq + jj) * WROW + cg * 16) = w; }
;         }
.LBB0_668:
	s_or_b32 s2, s19, s13
	v_add_u32_e32 v74, s2, v230
	v_cndmask_b32_e64 v50, 0, 1, s[28:29]
	v_max_i32_e32 v54, -1, v74
	v_cmp_ne_u32_e32 vcc, 1, v50
	v_max_i32_e32 v50, 0, v74
	v_add_u32_e32 v54, 1, v54
	v_or_b32_e32 v58, 2, v74
	v_mad_u64_u32 v[50:51], s[20:21], v50, s82, v[196:197]
	v_mad_u64_u32 v[54:55], s[20:21], v54, s82, v[196:197]
	v_max_i32_e32 v58, 0, v58
	global_load_dwordx4 v[50:53], v[50:51], off offset:1024
	v_mad_u64_u32 v[58:59], s[20:21], v58, s82, v[196:197]
	global_load_dwordx4 v[54:57], v[54:55], off offset:1024
	v_or_b32_e32 v62, s2, v229
	global_load_dwordx4 v[58:61], v[58:59], off offset:1024
	v_max_i32_e32 v62, 0, v62
	v_mad_u64_u32 v[62:63], s[20:21], v62, s82, v[196:197]
	global_load_dwordx4 v[62:65], v[62:63], off offset:1024
	v_max_i32_e32 v66, -4, v74
	v_add_u32_e32 v66, 4, v66
	v_mad_u64_u32 v[66:67], s[20:21], v66, s82, v[196:197]
	global_load_dwordx4 v[66:69], v[66:67], off offset:1024
	v_max_i32_e32 v70, -5, v74
	v_add_u32_e32 v70, 5, v70
	v_mad_u64_u32 v[70:71], s[20:21], v70, s82, v[196:197]
	global_load_dwordx4 v[70:73], v[70:71], off offset:1024
	v_max_i32_e32 v74, -6, v74
	v_add_u32_e32 v74, 6, v74
	v_mad_u64_u32 v[74:75], s[20:21], v74, s82, v[196:197]
	global_load_dwordx4 v[74:77], v[74:75], off offset:1024
	s_cmp_eq_u32 s2, 0
	s_cselect_b64 s[16:17], -1, 0
	s_and_b64 s[16:17], s[16:17], s[4:5]
	v_add_u32_e32 v138, v234, v231
	s_mov_b32 s19, 16
	s_mov_b64 s[28:29], 0
	s_and_b64 vcc, exec, vcc
	s_waitcnt vmcnt(5)
	v_cndmask_b32_e64 v81, v57, 0, s[16:17]
	v_cndmask_b32_e64 v57, v53, 0, s[16:17]
	v_cndmask_b32_e64 v53, v51, 0, s[16:17]
	v_cndmask_b32_e64 v51, v50, 0, s[16:17]
	s_waitcnt vmcnt(4)
	v_cndmask_b32_e64 v85, v59, 0, s[16:17]
	v_cndmask_b32_e64 v59, v54, 0, s[16:17]
	v_lshlrev_b32_e32 v50, 16, v51
	v_and_b32_e32 v51, 0xffff0000, v51
	v_cndmask_b32_e64 v89, v61, 0, s[16:17]
	v_cndmask_b32_e64 v83, v58, 0, s[16:17]
	v_cndmask_b32_e64 v61, v55, 0, s[16:17]
	v_cndmask_b32_e64 v55, v52, 0, s[16:17]
	s_waitcnt lgkmcnt(13)
	v_pk_fma_f32 v[50:51], v[10:11], v[50:51], v[42:43]
	v_lshlrev_b32_e32 v52, 16, v53
	v_and_b32_e32 v53, 0xffff0000, v53
	v_lshlrev_b32_e32 v58, 16, v59
	v_and_b32_e32 v59, 0xffff0000, v59
	v_cndmask_b32_e64 v87, v60, 0, s[16:17]
	v_cndmask_b32_e64 v79, v56, 0, s[16:17]
	v_pk_fma_f32 v[52:53], v[12:13], v[52:53], v[44:45]
	v_lshlrev_b32_e32 v54, 16, v55
	v_and_b32_e32 v55, 0xffff0000, v55
	v_lshlrev_b32_e32 v56, 16, v57
	v_and_b32_e32 v57, 0xffff0000, v57
	v_pk_fma_f32 v[50:51], v[18:19], v[58:59], v[50:51]
	v_lshlrev_b32_e32 v60, 16, v61
	v_and_b32_e32 v61, 0xffff0000, v61
	v_lshlrev_b32_e32 v82, 16, v83
	v_and_b32_e32 v83, 0xffff0000, v83
	s_waitcnt lgkmcnt(12)
	v_pk_fma_f32 v[54:55], v[14:15], v[54:55], v[46:47]
	v_pk_fma_f32 v[56:57], v[16:17], v[56:57], v[48:49]
	v_pk_fma_f32 v[52:53], v[20:21], v[60:61], v[52:53]
	v_lshlrev_b32_e32 v78, 16, v79
	v_and_b32_e32 v79, 0xffff0000, v79
	v_lshlrev_b32_e32 v80, 16, v81
	v_and_b32_e32 v81, 0xffff0000, v81
	v_pk_fma_f32 v[50:51], v[26:27], v[82:83], v[50:51]
	v_lshlrev_b32_e32 v84, 16, v85
	v_and_b32_e32 v85, 0xffff0000, v85
	s_waitcnt vmcnt(3)
	v_lshlrev_b32_e32 v90, 16, v62
	v_and_b32_e32 v91, 0xffff0000, v62
	v_pk_fma_f32 v[54:55], v[22:23], v[78:79], v[54:55]
	v_pk_fma_f32 v[56:57], v[24:25], v[80:81], v[56:57]
	v_pk_fma_f32 v[52:53], v[28:29], v[84:85], v[52:53]
	v_lshlrev_b32_e32 v86, 16, v87
	v_and_b32_e32 v87, 0xffff0000, v87
	v_lshlrev_b32_e32 v88, 16, v89
	v_and_b32_e32 v89, 0xffff0000, v89
	v_pk_fma_f32 v[50:51], v[34:35], v[90:91], v[50:51]
	v_lshlrev_b32_e32 v62, 16, v63
	v_and_b32_e32 v63, 0xffff0000, v63
	v_pk_fma_f32 v[54:55], v[30:31], v[86:87], v[54:55]
	v_pk_fma_f32 v[56:57], v[32:33], v[88:89], v[56:57]
	v_pk_fma_f32 v[52:53], v[36:37], v[62:63], v[52:53]
	v_lshlrev_b32_e32 v92, 16, v64
	v_and_b32_e32 v93, 0xffff0000, v64
	v_lshlrev_b32_e32 v64, 16, v65
	v_and_b32_e32 v65, 0xffff0000, v65
	v_cvt_pk_bf16_f32 v50, v50, v51
	v_cvt_pk_bf16_f32 v51, v52, v53
	v_pk_fma_f32 v[54:55], v[38:39], v[92:93], v[54:55]
	v_pk_fma_f32 v[56:57], v[40:41], v[64:65], v[56:57]
	v_cvt_pk_bf16_f32 v52, v54, v55
	v_pk_fma_f32 v[54:55], v[14:15], v[78:79], v[46:47]
	v_cvt_pk_bf16_f32 v53, v56, v57
	ds_write_b128 v247, v[50:53]
	v_pk_fma_f32 v[50:51], v[10:11], v[58:59], v[42:43]
	v_pk_fma_f32 v[52:53], v[12:13], v[60:61], v[44:45]
	v_pk_fma_f32 v[50:51], v[18:19], v[82:83], v[50:51]
	v_pk_fma_f32 v[56:57], v[16:17], v[80:81], v[48:49]
	v_pk_fma_f32 v[52:53], v[20:21], v[84:85], v[52:53]
	v_pk_fma_f32 v[50:51], v[26:27], v[90:91], v[50:51]
	s_waitcnt vmcnt(2)
	v_lshlrev_b32_e32 v58, 16, v66
	v_and_b32_e32 v59, 0xffff0000, v66
	v_pk_fma_f32 v[54:55], v[22:23], v[86:87], v[54:55]
	v_pk_fma_f32 v[56:57], v[24:25], v[88:89], v[56:57]
	v_pk_fma_f32 v[52:53], v[28:29], v[62:63], v[52:53]
	v_pk_fma_f32 v[50:51], v[34:35], v[58:59], v[50:51]
	v_lshlrev_b32_e32 v60, 16, v67
	v_and_b32_e32 v61, 0xffff0000, v67
	v_pk_fma_f32 v[54:55], v[30:31], v[92:93], v[54:55]
	v_pk_fma_f32 v[56:57], v[32:33], v[64:65], v[56:57]
	v_pk_fma_f32 v[52:53], v[36:37], v[60:61], v[52:53]
	v_lshlrev_b32_e32 v66, 16, v68
	v_and_b32_e32 v67, 0xffff0000, v68
	v_lshlrev_b32_e32 v68, 16, v69
	v_and_b32_e32 v69, 0xffff0000, v69
	v_cvt_pk_bf16_f32 v50, v50, v51
	v_cvt_pk_bf16_f32 v51, v52, v53
	v_pk_fma_f32 v[54:55], v[38:39], v[66:67], v[54:55]
	v_pk_fma_f32 v[56:57], v[40:41], v[68:69], v[56:57]
	v_cvt_pk_bf16_f32 v52, v54, v55
	v_pk_fma_f32 v[54:55], v[14:15], v[86:87], v[46:47]
	v_cvt_pk_bf16_f32 v53, v56, v57
	ds_write_b128 v247, v[50:53] offset:272
	v_pk_fma_f32 v[50:51], v[10:11], v[82:83], v[42:43]
	v_pk_fma_f32 v[52:53], v[12:13], v[84:85], v[44:45]
	v_pk_fma_f32 v[50:51], v[18:19], v[90:91], v[50:51]
	v_pk_fma_f32 v[56:57], v[16:17], v[88:89], v[48:49]
	v_pk_fma_f32 v[52:53], v[20:21], v[62:63], v[52:53]
	v_pk_fma_f32 v[50:51], v[26:27], v[58:59], v[50:51]
	s_waitcnt vmcnt(1)
; #define LAS __attribute__((address_space(3)))
; __device__ __forceinline__ float fsig2(float x) { return __builtin_amdgcn_rcpf(1.0f + __builtin_amdgcn_exp2f(-LOG2E * x)); }
; template <int PASS> __device__ __forceinline__ void lru_wave_item(LAS unsigned char* lds, LAS unsigned char* vw, int b, int c, int h, const MixP& p, int lane, float (&Hrun)[8], bool cont) {
;     ...
;         }
;         f32x4 aR[8], aI[8];
;         bf16x8 af[4];
;         {
; #pragma unroll
;             for (int kk = 0; kk < 4; ++kk) af[kk] = *(const LAS bf16x8*)(vw + fr * WROW + kk * 64 + fq * 16);
; #pragma unroll
;             for (int n = 0; n < 8; ++n) {
;                 aR[n] = (f32x4){0.f, 0.f, 0.f, 0.f}; aI[n] = (f32x4){0.f, 0.f, 0.f, 0.f};
; #pragma unroll
;                 for (int kk = 0; kk < 4; ++kk) {
;                     const bf16x8 ba = *(const LAS bf16x8*)(lds + WA_OFF + (16 * n + fr) * WROW + kk * 64 + fq * 16);
;                     const bf16x8 bx = *(const LAS bf16x8*)(lds + WX_OFF + (16 * n + fr) * WROW + kk * 64 + fq * 16);
;                     aR[n] = __builtin_amdgcn_mfma_f32_16x16x32_bf16(af[kk], ba, aR[n], 0, 0, 0);
;                     aI[n] = __builtin_amdgcn_mfma_f32_16x16x32_bf16(af[kk], bx, aI[n], 0, 0, 0);
;                 }
;             }
;     ...
;                 const float r = fsig2(aR[n][j] + pba[n]), ig = fsig2(aI[n][j] + pbx[n]);
;                 const float a = __builtin_amdgcn_exp2f(r * pk8[n]), mult = __builtin_amdgcn_sqrtf(fmaxf(1.0f - a * a, 0.f));
	v_lshlrev_b32_e32 v78, 16, v70
	v_and_b32_e32 v79, 0xffff0000, v70
	v_pk_fma_f32 v[54:55], v[22:23], v[92:93], v[54:55]
	v_pk_fma_f32 v[56:57], v[24:25], v[64:65], v[56:57]
	v_pk_fma_f32 v[52:53], v[28:29], v[60:61], v[52:53]
	v_pk_fma_f32 v[50:51], v[34:35], v[78:79], v[50:51]
	v_lshlrev_b32_e32 v70, 16, v71
	v_and_b32_e32 v71, 0xffff0000, v71
	v_pk_fma_f32 v[54:55], v[30:31], v[66:67], v[54:55]
	v_pk_fma_f32 v[56:57], v[32:33], v[68:69], v[56:57]
	v_pk_fma_f32 v[52:53], v[36:37], v[70:71], v[52:53]
	v_lshlrev_b32_e32 v80, 16, v72
	v_and_b32_e32 v81, 0xffff0000, v72
	v_lshlrev_b32_e32 v72, 16, v73
	v_and_b32_e32 v73, 0xffff0000, v73
	v_cvt_pk_bf16_f32 v50, v50, v51
	v_cvt_pk_bf16_f32 v51, v52, v53
	v_pk_fma_f32 v[54:55], v[38:39], v[80:81], v[54:55]
	v_pk_fma_f32 v[56:57], v[40:41], v[72:73], v[56:57]
	v_cvt_pk_bf16_f32 v52, v54, v55
	v_pk_fma_f32 v[54:55], v[14:15], v[92:93], v[46:47]
	v_cvt_pk_bf16_f32 v53, v56, v57
	ds_write_b128 v247, v[50:53] offset:544
	v_pk_fma_f32 v[50:51], v[10:11], v[90:91], v[42:43]
	v_pk_fma_f32 v[52:53], v[12:13], v[62:63], v[44:45]
	v_pk_fma_f32 v[50:51], v[18:19], v[58:59], v[50:51]
	v_pk_fma_f32 v[52:53], v[20:21], v[60:61], v[52:53]
	v_pk_fma_f32 v[50:51], v[26:27], v[78:79], v[50:51]
	s_waitcnt vmcnt(0)
	v_lshlrev_b32_e32 v58, 16, v74
	v_and_b32_e32 v59, 0xffff0000, v74
	v_pk_fma_f32 v[56:57], v[16:17], v[64:65], v[48:49]
	v_pk_fma_f32 v[54:55], v[22:23], v[66:67], v[54:55]
	v_pk_fma_f32 v[52:53], v[28:29], v[70:71], v[52:53]
	v_pk_fma_f32 v[50:51], v[34:35], v[58:59], v[50:51]
	v_lshlrev_b32_e32 v58, 16, v75
	v_and_b32_e32 v59, 0xffff0000, v75
	v_pk_fma_f32 v[56:57], v[24:25], v[68:69], v[56:57]
	v_pk_fma_f32 v[54:55], v[30:31], v[80:81], v[54:55]
	v_pk_fma_f32 v[52:53], v[36:37], v[58:59], v[52:53]
	v_lshlrev_b32_e32 v58, 16, v76
	v_and_b32_e32 v59, 0xffff0000, v76
	v_pk_fma_f32 v[56:57], v[32:33], v[72:73], v[56:57]
	v_pk_fma_f32 v[54:55], v[38:39], v[58:59], v[54:55]
	v_lshlrev_b32_e32 v58, 16, v77
	v_and_b32_e32 v59, 0xffff0000, v77
	v_cvt_pk_bf16_f32 v50, v50, v51
	v_pk_fma_f32 v[56:57], v[40:41], v[58:59], v[56:57]
	v_cvt_pk_bf16_f32 v51, v52, v53
	v_cvt_pk_bf16_f32 v52, v54, v55
	v_add_u32_e32 v74, v234, v235
	v_cvt_pk_bf16_f32 v53, v56, v57
	ds_write_b128 v247, v[50:53] offset:816
	v_add_u32_e32 v50, v232, v233
	ds_read_b128 v[110:113], v50
	ds_read_b128 v[82:85], v50 offset:64
	ds_read_b128 v[54:57], v50 offset:128
	ds_read_b128 v[50:53], v50 offset:192
	ds_read_b128 v[58:61], v138
	ds_read_b128 v[62:65], v138 offset:34816
	ds_read_b128 v[66:69], v138 offset:64
	ds_read_b128 v[70:73], v138 offset:34880
	s_waitcnt lgkmcnt(3)
	v_mfma_f32_16x16x32_bf16 v[58:61], v[110:113], v[58:61], 0
	s_waitcnt lgkmcnt(2)
	v_mfma_f32_16x16x32_bf16 v[62:65], v[110:113], v[62:65], 0
	s_waitcnt lgkmcnt(1)
	v_mfma_f32_16x16x32_bf16 v[58:61], v[82:85], v[66:69], v[58:61]
	s_waitcnt lgkmcnt(0)
	v_mfma_f32_16x16x32_bf16 v[62:65], v[82:85], v[70:73], v[62:65]
	ds_read_b128 v[66:69], v138 offset:128
	ds_read_b128 v[70:73], v138 offset:34944
	s_waitcnt lgkmcnt(1)
	v_mfma_f32_16x16x32_bf16 v[58:61], v[54:57], v[66:69], v[58:61]
	s_waitcnt lgkmcnt(0)
	v_mfma_f32_16x16x32_bf16 v[62:65], v[54:57], v[70:73], v[62:65]
	ds_read_b128 v[66:69], v138 offset:192
	ds_read_b128 v[70:73], v138 offset:35008
	s_waitcnt lgkmcnt(1)
	v_mfma_f32_16x16x32_bf16 v[126:129], v[50:53], v[66:69], v[58:61]
	s_waitcnt lgkmcnt(0)
	v_mfma_f32_16x16x32_bf16 v[122:125], v[50:53], v[70:73], v[62:65]
	s_nop 0
	ds_read_b128 v[58:61], v138 offset:4352
	s_nop 0
	ds_read_b128 v[62:65], v138 offset:39168
	ds_read_b128 v[66:69], v138 offset:4416
	ds_read_b128 v[70:73], v138 offset:39232
	v_add_f32_e32 v126, v170, v126
	s_waitcnt lgkmcnt(3)
	v_mfma_f32_16x16x32_bf16 v[58:61], v[110:113], v[58:61], 0
	v_add_f32_e32 v127, v170, v127
	v_mul_f32_e32 v126, 0xbfb8aa3b, v126
	v_mul_f32_e32 v127, 0xbfb8aa3b, v127
	s_waitcnt lgkmcnt(2)
	v_mfma_f32_16x16x32_bf16 v[62:65], v[110:113], v[62:65], 0
	v_exp_f32_e32 v126, v126
	v_exp_f32_e32 v127, v127
	v_add_f32_e32 v122, v174, v122
	s_waitcnt lgkmcnt(1)
	v_mfma_f32_16x16x32_bf16 v[58:61], v[82:85], v[66:69], v[58:61]
	v_add_f32_e32 v126, 1.0, v126
	v_add_f32_e32 v127, 1.0, v127
	v_rcp_f32_e32 v126, v126
	s_waitcnt lgkmcnt(0)
	v_mfma_f32_16x16x32_bf16 v[62:65], v[82:85], v[70:73], v[62:65]
	ds_read_b128 v[66:69], v138 offset:4480
	ds_read_b128 v[70:73], v138 offset:39296
	v_rcp_f32_e32 v127, v127
	v_mul_f32_e32 v126, v176, v126
	s_waitcnt lgkmcnt(1)
	v_mfma_f32_16x16x32_bf16 v[58:61], v[54:57], v[66:69], v[58:61]
	v_add_f32_e32 v123, v174, v123
	v_mul_f32_e32 v127, v176, v127
	v_mul_f32_e32 v122, 0xbfb8aa3b, v122
	s_waitcnt lgkmcnt(0)
	v_mfma_f32_16x16x32_bf16 v[62:65], v[54:57], v[70:73], v[62:65]
	ds_read_b128 v[66:69], v138 offset:4544
	ds_read_b128 v[70:73], v138 offset:39360
	v_mul_f32_e32 v123, 0xbfb8aa3b, v123
	v_exp_f32_e32 v122, v122
	s_waitcnt lgkmcnt(1)
	v_mfma_f32_16x16x32_bf16 v[118:121], v[50:53], v[66:69], v[58:61]
	v_exp_f32_e32 v123, v123
	v_add_f32_e32 v122, 1.0, v122
	v_rcp_f32_e32 v122, v122
	s_waitcnt lgkmcnt(0)
	v_mfma_f32_16x16x32_bf16 v[114:117], v[50:53], v[70:73], v[62:65]
	ds_read_b128 v[58:61], v138 offset:8704
	s_nop 1
	ds_read_b128 v[62:65], v138 offset:43520
	ds_read_b128 v[66:69], v138 offset:8768
	ds_read_b128 v[70:73], v138 offset:43584
	v_add_f32_e32 v123, 1.0, v123
	s_waitcnt lgkmcnt(3)
	v_mfma_f32_16x16x32_bf16 v[58:61], v[110:113], v[58:61], 0
	v_rcp_f32_e32 v123, v123
	v_add_f32_e32 v124, v174, v124
	v_add_f32_e32 v125, v174, v125
	s_waitcnt lgkmcnt(2)
	v_mfma_f32_16x16x32_bf16 v[62:65], v[110:113], v[62:65], 0
	v_mul_f32_e32 v124, 0xbfb8aa3b, v124
	v_mul_f32_e32 v125, 0xbfb8aa3b, v125
	v_exp_f32_e32 v124, v124
	s_waitcnt lgkmcnt(1)
; #define LAS __attribute__((address_space(3)))
; __device__ __forceinline__ float fsig2(float x) { return __builtin_amdgcn_rcpf(1.0f + __builtin_amdgcn_exp2f(-LOG2E * x)); }
; template <int PASS> __device__ __forceinline__ void lru_wave_item(LAS unsigned char* lds, LAS unsigned char* vw, int b, int c, int h, const MixP& p, int lane, float (&Hrun)[8], bool cont) {
;     ...
;             for (int n = 0; n < 8; ++n) {
;                 aR[n] = (f32x4){0.f, 0.f, 0.f, 0.f}; aI[n] = (f32x4){0.f, 0.f, 0.f, 0.f};
; #pragma unroll
;                 for (int kk = 0; kk < 4; ++kk) {
;                     const bf16x8 ba = *(const LAS bf16x8*)(lds + WA_OFF + (16 * n + fr) * WROW + kk * 64 + fq * 16);
;                     const bf16x8 bx = *(const LAS bf16x8*)(lds + WX_OFF + (16 * n + fr) * WROW + kk * 64 + fq * 16);
;                     aR[n] = __builtin_amdgcn_mfma_f32_16x16x32_bf16(af[kk], ba, aR[n], 0, 0, 0);
;                     aI[n] = __builtin_amdgcn_mfma_f32_16x16x32_bf16(af[kk], bx, aI[n], 0, 0, 0);
;                 }
;             }
;         }
; #pragma unroll
;         for (int n = 0; n < 8; ++n) {
;             const f32x4 aVn = __builtin_amdgcn_mfma_f32_16x16x32_bf16(af[n >> 1], idf[n & 1], (f32x4){0.f, 0.f, 0.f, 0.f}, 0, 0, 0);
;             float av[4], bxv[4];
; #pragma unroll
;             for (int j = 0; j < 4; ++j) {
;                 const float r = fsig2(aR[n][j] + pba[n]), ig = fsig2(aI[n][j] + pbx[n]);
;                 const float a = __builtin_amdgcn_exp2f(r * pk8[n]), mult = __builtin_amdgcn_sqrtf(fmaxf(1.0f - a * a, 0.f));
	v_mfma_f32_16x16x32_bf16 v[58:61], v[82:85], v[66:69], v[58:61]
	v_exp_f32_e32 v125, v125
	v_add_f32_e32 v118, v171, v118
	v_add_f32_e32 v119, v171, v119
	s_waitcnt lgkmcnt(0)
	v_mfma_f32_16x16x32_bf16 v[62:65], v[82:85], v[70:73], v[62:65]
	ds_read_b128 v[66:69], v138 offset:8832
	ds_read_b128 v[70:73], v138 offset:43648
	v_add_f32_e32 v124, 1.0, v124
	v_add_f32_e32 v125, 1.0, v125
	s_waitcnt lgkmcnt(1)
	v_mfma_f32_16x16x32_bf16 v[58:61], v[54:57], v[66:69], v[58:61]
	v_mul_f32_e32 v118, 0xbfb8aa3b, v118
	v_mul_f32_e32 v119, 0xbfb8aa3b, v119
	v_rcp_f32_e32 v124, v124
	s_waitcnt lgkmcnt(0)
	v_mfma_f32_16x16x32_bf16 v[62:65], v[54:57], v[70:73], v[62:65]
	ds_read_b128 v[66:69], v138 offset:8896
	ds_read_b128 v[70:73], v138 offset:43712
	v_exp_f32_e32 v118, v118
	v_exp_f32_e32 v119, v119
	s_waitcnt lgkmcnt(1)
	v_mfma_f32_16x16x32_bf16 v[106:109], v[50:53], v[66:69], v[58:61]
	v_add_f32_e32 v118, 1.0, v118
	v_add_f32_e32 v119, 1.0, v119
	v_rcp_f32_e32 v118, v118
	s_waitcnt lgkmcnt(0)
	v_mfma_f32_16x16x32_bf16 v[102:105], v[50:53], v[70:73], v[62:65]
	ds_read_b128 v[58:61], v74
	s_nop 1
	ds_read_b128 v[62:65], v74 offset:34816
	ds_read_b128 v[66:69], v74 offset:64
	ds_read_b128 v[70:73], v74 offset:34880
	v_rcp_f32_e32 v119, v119
	s_waitcnt lgkmcnt(3)
	v_mfma_f32_16x16x32_bf16 v[58:61], v[110:113], v[58:61], 0
	v_add_f32_e32 v114, v175, v114
	v_mul_f32_e32 v118, v177, v118
	v_add_f32_e32 v115, v175, v115
	s_waitcnt lgkmcnt(2)
	v_mfma_f32_16x16x32_bf16 v[62:65], v[110:113], v[62:65], 0
	v_mul_f32_e32 v119, v177, v119
	v_mul_f32_e32 v114, 0xbfb8aa3b, v114
	v_mul_f32_e32 v115, 0xbfb8aa3b, v115
	s_waitcnt lgkmcnt(1)
	v_mfma_f32_16x16x32_bf16 v[58:61], v[82:85], v[66:69], v[58:61]
	v_exp_f32_e32 v114, v114
	v_exp_f32_e32 v115, v115
	v_add_f32_e32 v106, v178, v106
	s_waitcnt lgkmcnt(0)
	v_mfma_f32_16x16x32_bf16 v[62:65], v[82:85], v[70:73], v[62:65]
	ds_read_b128 v[66:69], v74 offset:128
	ds_read_b128 v[70:73], v74 offset:34944
	v_add_f32_e32 v114, 1.0, v114
	v_add_f32_e32 v115, 1.0, v115
	s_waitcnt lgkmcnt(1)
	v_mfma_f32_16x16x32_bf16 v[58:61], v[54:57], v[66:69], v[58:61]
	v_rcp_f32_e32 v114, v114
	v_rcp_f32_e32 v115, v115
	v_add_f32_e32 v107, v178, v107
	s_waitcnt lgkmcnt(0)
	v_mfma_f32_16x16x32_bf16 v[62:65], v[54:57], v[70:73], v[62:65]
	ds_read_b128 v[66:69], v74 offset:192
	ds_read_b128 v[70:73], v74 offset:35008
	v_mul_f32_e32 v106, 0xbfb8aa3b, v106
	v_mul_f32_e32 v107, 0xbfb8aa3b, v107
	s_waitcnt lgkmcnt(1)
	v_mfma_f32_16x16x32_bf16 v[90:93], v[50:53], v[66:69], v[58:61]
	v_exp_f32_e32 v106, v106
	v_exp_f32_e32 v107, v107
	v_add_f32_e32 v102, v180, v102
	s_waitcnt lgkmcnt(0)
	v_mfma_f32_16x16x32_bf16 v[86:89], v[50:53], v[70:73], v[62:65]
	ds_read_b128 v[58:61], v138 offset:17408
	s_nop 1
	ds_read_b128 v[62:65], v138 offset:52224
	ds_read_b128 v[66:69], v138 offset:17472
	ds_read_b128 v[70:73], v138 offset:52288
	v_add_f32_e32 v106, 1.0, v106
	s_waitcnt lgkmcnt(3)
	v_mfma_f32_16x16x32_bf16 v[58:61], v[110:113], v[58:61], 0
	v_add_f32_e32 v107, 1.0, v107
	v_rcp_f32_e32 v106, v106
	v_rcp_f32_e32 v107, v107
	s_waitcnt lgkmcnt(2)
	v_mfma_f32_16x16x32_bf16 v[62:65], v[110:113], v[62:65], 0
	v_add_f32_e32 v103, v180, v103
	v_mul_f32_e32 v106, v182, v106
	v_mul_f32_e32 v107, v182, v107
	s_waitcnt lgkmcnt(1)
	v_mfma_f32_16x16x32_bf16 v[58:61], v[82:85], v[66:69], v[58:61]
	v_mul_f32_e32 v102, 0xbfb8aa3b, v102
	v_mul_f32_e32 v103, 0xbfb8aa3b, v103
	v_exp_f32_e32 v102, v102
	s_waitcnt lgkmcnt(0)
	v_mfma_f32_16x16x32_bf16 v[62:65], v[82:85], v[70:73], v[62:65]
	ds_read_b128 v[66:69], v138 offset:17536
	ds_read_b128 v[70:73], v138 offset:52352
	v_exp_f32_e32 v103, v103
	v_add_f32_e32 v102, 1.0, v102
	s_waitcnt lgkmcnt(1)
	v_mfma_f32_16x16x32_bf16 v[58:61], v[54:57], v[66:69], v[58:61]
	v_add_f32_e32 v103, 1.0, v103
	v_rcp_f32_e32 v102, v102
	v_rcp_f32_e32 v103, v103
	s_waitcnt lgkmcnt(0)
	v_mfma_f32_16x16x32_bf16 v[62:65], v[54:57], v[70:73], v[62:65]
	ds_read_b128 v[66:69], v138 offset:17600
	ds_read_b128 v[70:73], v138 offset:52416
	v_add_f32_e32 v104, v180, v104
	v_add_f32_e32 v105, v180, v105
	s_waitcnt lgkmcnt(1)
	v_mfma_f32_16x16x32_bf16 v[78:81], v[50:53], v[66:69], v[58:61]
	v_mul_f32_e32 v104, 0xbfb8aa3b, v104
	v_mul_f32_e32 v105, 0xbfb8aa3b, v105
	v_exp_f32_e32 v104, v104
	s_waitcnt lgkmcnt(0)
	v_mfma_f32_16x16x32_bf16 v[74:77], v[50:53], v[70:73], v[62:65]
	ds_read_b128 v[58:61], v138 offset:21760
	s_nop 1
	ds_read_b128 v[62:65], v138 offset:56576
	ds_read_b128 v[66:69], v138 offset:21824
	ds_read_b128 v[70:73], v138 offset:56640
	v_exp_f32_e32 v105, v105
	s_waitcnt lgkmcnt(3)
	v_mfma_f32_16x16x32_bf16 v[58:61], v[110:113], v[58:61], 0
	v_add_f32_e32 v104, 1.0, v104
	v_add_f32_e32 v105, 1.0, v105
	v_rcp_f32_e32 v104, v104
	s_waitcnt lgkmcnt(2)
	v_mfma_f32_16x16x32_bf16 v[62:65], v[110:113], v[62:65], 0
	v_add_f32_e32 v90, v179, v90
	v_add_f32_e32 v91, v179, v91
	v_mul_f32_e32 v90, 0xbfb8aa3b, v90
	s_waitcnt lgkmcnt(1)
	v_mfma_f32_16x16x32_bf16 v[58:61], v[82:85], v[66:69], v[58:61]
	v_mul_f32_e32 v91, 0xbfb8aa3b, v91
	v_exp_f32_e32 v90, v90
	v_exp_f32_e32 v91, v91
	s_waitcnt lgkmcnt(0)
	v_mfma_f32_16x16x32_bf16 v[62:65], v[82:85], v[70:73], v[62:65]
	ds_read_b128 v[66:69], v138 offset:21888
	ds_read_b128 v[70:73], v138 offset:56704
	v_add_f32_e32 v90, 1.0, v90
	v_add_f32_e32 v91, 1.0, v91
	s_waitcnt lgkmcnt(1)
	v_mfma_f32_16x16x32_bf16 v[58:61], v[54:57], v[66:69], v[58:61]
	ds_read_b128 v[66:69], v138 offset:21952
	ds_read_b128 v[94:97], v138 offset:56768
	v_rcp_f32_e32 v90, v90
	v_rcp_f32_e32 v91, v91
	s_waitcnt lgkmcnt(2)
	v_mfma_f32_16x16x32_bf16 v[62:65], v[54:57], v[70:73], v[62:65]
	v_add_f32_e32 v86, v181, v86
	v_mul_f32_e32 v90, v183, v90
	v_add_f32_e32 v87, v181, v87
	s_waitcnt lgkmcnt(1)
; __device__ __forceinline__ float fsig2(float x) { return __builtin_amdgcn_rcpf(1.0f + __builtin_amdgcn_exp2f(-LOG2E * x)); }
; template <int PASS> __device__ __forceinline__ void lru_wave_item(LAS unsigned char* lds, LAS unsigned char* vw, int b, int c, int h, const MixP& p, int lane, float (&Hrun)[8], bool cont) {
;     ...
;         for (int n = 0; n < 8; ++n) {
;             const f32x4 aVn = __builtin_amdgcn_mfma_f32_16x16x32_bf16(af[n >> 1], idf[n & 1], (f32x4){0.f, 0.f, 0.f, 0.f}, 0, 0, 0);
;             float av[4], bxv[4];
; #pragma unroll
;             for (int j = 0; j < 4; ++j) {
;                 const float r = fsig2(aR[n][j] + pba[n]), ig = fsig2(aI[n][j] + pbx[n]);
;                 const float a = __builtin_amdgcn_exp2f(r * pk8[n]), mult = __builtin_amdgcn_sqrtf(fmaxf(1.0f - a * a, 0.f));
;                 av[j] = a; bxv[j] = mult * ig * aVn[j];
;             }
;             const float H0 = bxv[0], H1 = av[1] * H0 + bxv[1], H2 = av[2] * H1 + bxv[2], H3 = av[3] * H2 + bxv[3];
;             const float A0 = av[0], A1 = av[1] * A0, A2 = av[2] * A1, A3 = av[3] * A2;
;             float At[4], Ht[4];
; #pragma unroll
;             for (int q = 0; q < 4; ++q) { At[q] = __shfl(A3, fr + 16 * q); Ht[q] = __shfl(H3, fr + 16 * q); }
;             const float c0 = Hrun[n], c1 = At[0] * c0 + Ht[0], c2 = At[1] * c1 + Ht[1], c3 = At[2] * c2 + Ht[2], c4 = At[3] * c3 + Ht[3];
	v_mfma_f32_16x16x32_bf16 v[70:73], v[50:53], v[66:69], v[58:61]
	v_mul_f32_e32 v91, v183, v91
	v_mul_f32_e32 v86, 0xbfb8aa3b, v86
	v_mul_f32_e32 v87, 0xbfb8aa3b, v87
	s_waitcnt lgkmcnt(0)
	v_mfma_f32_16x16x32_bf16 v[66:69], v[50:53], v[94:97], v[62:65]
	ds_read_b128 v[58:61], v138 offset:26112
	s_nop 1
	ds_read_b128 v[62:65], v138 offset:60928
	ds_read_b128 v[94:97], v138 offset:26176
	ds_read_b128 v[98:101], v138 offset:60992
	v_exp_f32_e32 v86, v86
	s_waitcnt lgkmcnt(3)
	v_mfma_f32_16x16x32_bf16 v[58:61], v[110:113], v[58:61], 0
	v_exp_f32_e32 v87, v87
	v_add_f32_e32 v86, 1.0, v86
	v_rcp_f32_e32 v86, v86
	s_waitcnt lgkmcnt(2)
	v_mfma_f32_16x16x32_bf16 v[62:65], v[110:113], v[62:65], 0
	v_add_f32_e32 v87, 1.0, v87
	v_rcp_f32_e32 v87, v87
	v_add_f32_e32 v78, v184, v78
	s_waitcnt lgkmcnt(1)
	v_mfma_f32_16x16x32_bf16 v[58:61], v[82:85], v[94:97], v[58:61]
	v_add_f32_e32 v79, v184, v79
	v_mul_f32_e32 v78, 0xbfb8aa3b, v78
	v_mul_f32_e32 v79, 0xbfb8aa3b, v79
	s_waitcnt lgkmcnt(0)
	v_mfma_f32_16x16x32_bf16 v[62:65], v[82:85], v[98:101], v[62:65]
	ds_read_b128 v[94:97], v138 offset:26240
	ds_read_b128 v[98:101], v138 offset:61056
	v_exp_f32_e32 v78, v78
	v_exp_f32_e32 v79, v79
	s_waitcnt lgkmcnt(1)
	v_mfma_f32_16x16x32_bf16 v[58:61], v[54:57], v[94:97], v[58:61]
	v_add_f32_e32 v78, 1.0, v78
	v_add_f32_e32 v79, 1.0, v79
	v_rcp_f32_e32 v78, v78
	s_waitcnt lgkmcnt(0)
	v_mfma_f32_16x16x32_bf16 v[94:97], v[54:57], v[98:101], v[62:65]
	s_nop 2
	ds_read_b128 v[62:65], v138 offset:26304
	ds_read_b128 v[98:101], v138 offset:61120
	v_rcp_f32_e32 v79, v79
	v_add_f32_e32 v74, v186, v74
	s_waitcnt lgkmcnt(1)
	v_mfma_f32_16x16x32_bf16 v[62:65], v[50:53], v[62:65], v[58:61]
	v_mul_f32_e32 v78, v188, v78
	v_add_f32_e32 v75, v186, v75
	v_mul_f32_e32 v79, v188, v79
	s_waitcnt lgkmcnt(0)
	v_mfma_f32_16x16x32_bf16 v[58:61], v[50:53], v[98:101], v[94:97]
	v_mul_f32_e32 v74, 0xbfb8aa3b, v74
	v_mul_f32_e32 v75, 0xbfb8aa3b, v75
	v_exp_f32_e32 v74, v74
	v_add_u32_e32 v94, v234, v236
	ds_read_b128 v[96:99], v94
	ds_read_b128 v[198:201], v94 offset:34816
	ds_read_b128 v[202:205], v94 offset:64
	ds_read_b128 v[138:141], v94 offset:34880
	s_waitcnt lgkmcnt(3)
	v_mfma_f32_16x16x32_bf16 v[96:99], v[110:113], v[96:99], 0
	v_exp_f32_e32 v75, v75
	v_add_f32_e32 v74, 1.0, v74
	v_rcp_f32_e32 v74, v74
	s_waitcnt lgkmcnt(2)
	v_mfma_f32_16x16x32_bf16 v[198:201], v[110:113], v[198:201], 0
	v_add_f32_e32 v75, 1.0, v75
	v_rcp_f32_e32 v75, v75
	v_add_f32_e32 v76, v186, v76
	s_waitcnt lgkmcnt(1)
	v_mfma_f32_16x16x32_bf16 v[96:99], v[82:85], v[202:205], v[96:99]
	v_add_f32_e32 v77, v186, v77
	v_mul_f32_e32 v76, 0xbfb8aa3b, v76
	v_mul_f32_e32 v77, 0xbfb8aa3b, v77
	s_waitcnt lgkmcnt(0)
	v_mfma_f32_16x16x32_bf16 v[138:141], v[82:85], v[138:141], v[198:201]
	s_nop 2
	ds_read_b128 v[198:201], v94 offset:128
	ds_read_b128 v[202:205], v94 offset:34944
	v_exp_f32_e32 v76, v76
	v_exp_f32_e32 v77, v77
	s_waitcnt lgkmcnt(1)
	v_mfma_f32_16x16x32_bf16 v[96:99], v[54:57], v[198:201], v[96:99]
	v_add_f32_e32 v76, 1.0, v76
	v_add_f32_e32 v77, 1.0, v77
	v_rcp_f32_e32 v76, v76
	s_waitcnt lgkmcnt(0)
	v_mfma_f32_16x16x32_bf16 v[138:141], v[54:57], v[202:205], v[138:141]
	ds_read_b128 v[198:201], v94 offset:192
	ds_read_b128 v[202:205], v94 offset:35008
	v_add_f32_e32 v70, v185, v70
	v_add_f32_e32 v71, v185, v71
	s_waitcnt lgkmcnt(1)
	v_mfma_f32_16x16x32_bf16 v[98:101], v[50:53], v[198:201], v[96:99]
	v_exp_f32_e32 v198, v126
	v_exp_f32_e32 v199, v127
	v_mul_f32_e32 v70, 0xbfb8aa3b, v70
	s_waitcnt lgkmcnt(0)
	v_mfma_f32_16x16x32_bf16 v[94:97], v[50:53], v[202:205], v[138:141]
	v_fma_f32 v126, -v198, v198, 1.0
	v_fma_f32 v127, -v199, v199, 1.0
	v_max_f32_e32 v126, 0, v126
	v_max_f32_e32 v127, 0, v127
	v_sqrt_f32_e32 v126, v126
	v_sqrt_f32_e32 v127, v127
	v_and_or_b32 v138, v213, 64, v137
	v_lshlrev_b32_e32 v151, 2, v138
	v_mfma_f32_16x16x32_bf16 v[138:141], v[110:113], v[2:5], 0
	v_mul_f32_e64 v122, v122, v126
	v_mul_f32_e64 v123, v123, v127
	v_add_f32_e32 v126, v170, v128
	v_mul_f32_e32 v126, 0xbfb8aa3b, v126
	v_exp_f32_e32 v126, v126
	v_rcp_f32_e32 v128, v125
	s_nop 1
	v_pk_mul_f32 v[122:123], v[122:123], v[138:139]
	v_mfma_f32_16x16x32_bf16 v[110:113], v[110:113], v[6:9], 0
	v_add_f32_e32 v126, 1.0, v126
	v_rcp_f32_e32 v126, v126
	v_fmac_f32_e32 v123, v199, v122
	v_mul_f32_e32 v71, 0xbfb8aa3b, v71
	v_exp_f32_e32 v70, v70
	v_mul_f32_e32 v126, v176, v126
	v_exp_f32_e32 v127, v126
	v_add_f32_e32 v126, v170, v129
	v_mul_f32_e32 v126, 0xbfb8aa3b, v126
	v_exp_f32_e32 v126, v126
	v_fma_f32 v122, -v127, v127, 1.0
	v_max_f32_e32 v122, 0, v122
	v_exp_f32_e32 v71, v71
	v_add_f32_e32 v126, 1.0, v126
	v_rcp_f32_e32 v126, v126
	v_add_f32_e32 v70, 1.0, v70
	v_add_f32_e32 v71, 1.0, v71
	v_rcp_f32_e32 v70, v70
	v_mul_f32_e32 v125, v176, v126
	v_sqrt_f32_e32 v126, v122
	v_exp_f32_e32 v139, v125
	v_mov_b32_e32 v125, v123
	v_rcp_f32_e32 v71, v71
	v_pk_mul_f32 v[122:123], v[124:125], v[126:127]
	v_exp_f32_e32 v124, v119
	v_fmac_f32_e32 v123, v122, v140
	v_fma_f32 v122, -v139, v139, 1.0
	v_max_f32_e32 v122, 0, v122
	v_sqrt_f32_e32 v138, v122
	v_mul_f32_e32 v122, v199, v198
	v_mul_f32_e32 v122, v127, v122
	v_mul_f32_e32 v122, v139, v122
	v_mov_b32_e32 v129, v123
	ds_bpermute_b32 v123, v151, v122
	ds_bpermute_b32 v127, v151, v122 offset:64
	ds_bpermute_b32 v199, v151, v122 offset:128
	ds_bpermute_b32 v203, v151, v122 offset:192
	v_exp_f32_e32 v122, v118
	v_fma_f32 v119, -v124, v124, 1.0
	v_max_f32_e32 v119, 0, v119
	v_sqrt_f32_e32 v119, v119
	v_fma_f32 v118, -v122, v122, 1.0
	v_max_f32_e32 v118, 0, v118
	v_sqrt_f32_e32 v118, v118
	v_pk_mul_f32 v[204:205], v[128:129], v[138:139]
	v_add_f32_e32 v66, v187, v66
	v_fmac_f32_e32 v205, v204, v141
; __device__ __forceinline__ float fsig2(float x) { return __builtin_amdgcn_rcpf(1.0f + __builtin_amdgcn_exp2f(-LOG2E * x)); }
; template <int PASS> __device__ __forceinline__ void lru_wave_item(LAS unsigned char* lds, LAS unsigned char* vw, int b, int c, int h, const MixP& p, int lane, float (&Hrun)[8], bool cont) {
;     ...
;         for (int n = 0; n < 8; ++n) {
;             const f32x4 aVn = __builtin_amdgcn_mfma_f32_16x16x32_bf16(af[n >> 1], idf[n & 1], (f32x4){0.f, 0.f, 0.f, 0.f}, 0, 0, 0);
;             float av[4], bxv[4];
; #pragma unroll
;             for (int j = 0; j < 4; ++j) {
;                 const float r = fsig2(aR[n][j] + pba[n]), ig = fsig2(aI[n][j] + pbx[n]);
;                 const float a = __builtin_amdgcn_exp2f(r * pk8[n]), mult = __builtin_amdgcn_sqrtf(fmaxf(1.0f - a * a, 0.f));
;                 av[j] = a; bxv[j] = mult * ig * aVn[j];
;             }
;             const float H0 = bxv[0], H1 = av[1] * H0 + bxv[1], H2 = av[2] * H1 + bxv[2], H3 = av[3] * H2 + bxv[3];
;             const float A0 = av[0], A1 = av[1] * A0, A2 = av[2] * A1, A3 = av[3] * A2;
;             float At[4], Ht[4];
; #pragma unroll
;             for (int q = 0; q < 4; ++q) { At[q] = __shfl(A3, fr + 16 * q); Ht[q] = __shfl(H3, fr + 16 * q); }
;             const float c0 = Hrun[n], c1 = At[0] * c0 + Ht[0], c2 = At[1] * c1 + Ht[1], c3 = At[2] * c2 + Ht[2], c4 = At[3] * c3 + Ht[3];
;             Hrun[n] = c4;
;             if (PASS == 1) Arun[n] *= (At[0] * At[1]) * (At[2] * At[3]);
	v_pk_mul_f32 v[114:115], v[114:115], v[118:119]
	ds_bpermute_b32 v125, v151, v205
	v_pk_mul_f32 v[110:111], v[114:115], v[110:111]
	v_add_f32_e32 v114, v171, v120
	v_mul_f32_e32 v114, 0xbfb8aa3b, v114
	v_exp_f32_e32 v114, v114
	v_fmac_f32_e32 v111, v124, v110
	ds_bpermute_b32 v129, v151, v205 offset:64
	ds_bpermute_b32 v201, v151, v205 offset:128
	v_add_f32_e32 v114, 1.0, v114
	v_rcp_f32_e32 v115, v114
	v_add_f32_e32 v114, v175, v116
	v_mul_f32_e32 v114, 0xbfb8aa3b, v114
	v_exp_f32_e32 v114, v114
	v_mul_f32_e32 v115, v177, v115
	v_exp_f32_e32 v119, v115
	v_add_f32_e32 v115, v171, v121
	v_mul_f32_e32 v115, 0xbfb8aa3b, v115
	v_exp_f32_e32 v115, v115
	v_fma_f32 v110, -v119, v119, 1.0
	v_add_f32_e32 v114, 1.0, v114
	v_max_f32_e32 v110, 0, v110
	v_add_f32_e32 v115, 1.0, v115
	v_rcp_f32_e32 v115, v115
	v_rcp_f32_e32 v114, v114
	v_sqrt_f32_e32 v118, v110
	v_add_f32_e32 v116, v175, v117
	v_mul_f32_e32 v115, v177, v115
	v_exp_f32_e32 v121, v115
	v_mov_b32_e32 v115, v111
	v_pk_mul_f32 v[110:111], v[114:115], v[118:119]
	v_exp_f32_e32 v114, v106
	v_exp_f32_e32 v115, v107
	v_mul_f32_e32 v116, 0xbfb8aa3b, v116
	v_exp_f32_e32 v116, v116
	v_fma_f32 v106, -v114, v114, 1.0
	v_fma_f32 v107, -v115, v115, 1.0
	v_max_f32_e32 v106, 0, v106
	v_max_f32_e32 v107, 0, v107
	v_sqrt_f32_e32 v106, v106
	v_sqrt_f32_e32 v107, v107
	v_fmac_f32_e32 v111, v110, v112
	v_fma_f32 v110, -v121, v121, 1.0
	v_add_f32_e32 v116, 1.0, v116
	v_max_f32_e32 v110, 0, v110
	v_rcp_f32_e32 v116, v116
	v_sqrt_f32_e32 v120, v110
	v_pk_mul_f32 v[102:103], v[102:103], v[106:107]
	v_add_f32_e32 v106, v178, v108
	v_mul_f32_e32 v106, 0xbfb8aa3b, v106
	v_mov_b32_e32 v117, v111
	v_exp_f32_e32 v106, v106
	v_pk_mul_f32 v[110:111], v[116:117], v[120:121]
	ds_bpermute_b32 v205, v151, v205 offset:192
	v_fmac_f32_e32 v111, v110, v113
	v_mul_f32_e32 v110, v124, v122
	v_mul_f32_e32 v110, v119, v110
	v_mul_f32_e32 v110, v121, v110
	v_add_f32_e32 v106, 1.0, v106
	ds_bpermute_b32 v122, v151, v110
	ds_bpermute_b32 v126, v151, v110 offset:64
	ds_bpermute_b32 v198, v151, v110 offset:128
	ds_bpermute_b32 v202, v151, v110 offset:192
	v_rcp_f32_e32 v106, v106
	ds_bpermute_b32 v124, v151, v111
	ds_bpermute_b32 v128, v151, v111 offset:64
	ds_bpermute_b32 v200, v151, v111 offset:128
	ds_bpermute_b32 v204, v151, v111 offset:192
	v_mul_f32_e32 v106, v182, v106
	s_waitcnt lgkmcnt(6)
	v_pk_mul_f32 v[110:111], v[122:123], v[126:127]
	s_waitcnt lgkmcnt(4)
	v_pk_mul_f32 v[112:113], v[198:199], v[202:203]
	v_exp_f32_e32 v107, v106
	v_add_f32_e32 v106, v178, v109
	v_pk_mul_f32 v[110:111], v[110:111], v[112:113]
	s_waitcnt lgkmcnt(3)
	v_pk_fma_f32 v[112:113], v[172:173], v[122:123], v[124:125]
	v_mul_f32_e32 v106, 0xbfb8aa3b, v106
	s_waitcnt lgkmcnt(2)
	v_pk_fma_f32 v[112:113], v[112:113], v[126:127], v[128:129]
	v_exp_f32_e32 v106, v106
	s_waitcnt lgkmcnt(1)
	v_pk_fma_f32 v[112:113], v[112:113], v[198:199], v[200:201]
	v_pk_mul_f32 v[162:163], v[162:163], v[110:111]
	s_waitcnt lgkmcnt(0)
	v_pk_fma_f32 v[172:173], v[112:113], v[202:203], v[204:205]
	v_mfma_f32_16x16x32_bf16 v[110:113], v[82:85], v[2:5], 0
	v_add_f32_e32 v106, 1.0, v106
	v_rcp_f32_e32 v106, v106
	v_rcp_f32_e32 v108, v105
	v_mfma_f32_16x16x32_bf16 v[82:85], v[82:85], v[6:9], 0
	v_mul_f32_e32 v70, v189, v70
	s_nop 2
	v_pk_mul_f32 v[102:103], v[102:103], v[110:111]
	v_mul_f32_e32 v105, v182, v106
	v_fmac_f32_e32 v103, v115, v102
	v_fma_f32 v102, -v107, v107, 1.0
	v_max_f32_e32 v102, 0, v102
	v_sqrt_f32_e32 v106, v102
	v_exp_f32_e32 v111, v105
	v_mov_b32_e32 v105, v103
	v_add_f32_e32 v67, v187, v67
	v_pk_mul_f32 v[102:103], v[104:105], v[106:107]
	v_mul_f32_e32 v71, v189, v71
	v_fmac_f32_e32 v103, v102, v112
	v_fma_f32 v102, -v111, v111, 1.0
	v_max_f32_e32 v102, 0, v102
	v_sqrt_f32_e32 v110, v102
	v_mov_b32_e32 v109, v103
	v_mul_f32_e32 v66, 0xbfb8aa3b, v66
	v_mul_f32_e32 v67, 0xbfb8aa3b, v67
	v_pk_mul_f32 v[102:103], v[108:109], v[110:111]
	v_exp_f32_e32 v66, v66
	v_fmac_f32_e32 v103, v102, v113
	v_mul_f32_e32 v102, v115, v114
	v_mul_f32_e32 v102, v107, v102
	v_mul_f32_e32 v105, v111, v102
	ds_bpermute_b32 v102, v151, v105
	ds_bpermute_b32 v104, v151, v103
	ds_bpermute_b32 v106, v151, v105 offset:64
	ds_bpermute_b32 v108, v151, v103 offset:64
	ds_bpermute_b32 v110, v151, v105 offset:128
	ds_bpermute_b32 v112, v151, v103 offset:128
	ds_bpermute_b32 v114, v151, v105 offset:192
	ds_bpermute_b32 v116, v151, v103 offset:192
	v_exp_f32_e32 v103, v90
	v_exp_f32_e32 v105, v91
	v_exp_f32_e32 v67, v67
	v_add_f32_e32 v66, 1.0, v66
	v_fma_f32 v90, -v103, v103, 1.0
	v_fma_f32 v91, -v105, v105, 1.0
	v_max_f32_e32 v90, 0, v90
	v_max_f32_e32 v91, 0, v91
	v_sqrt_f32_e32 v90, v90
	v_sqrt_f32_e32 v91, v91
	v_add_f32_e32 v67, 1.0, v67
	v_rcp_f32_e32 v66, v66
	v_rcp_f32_e32 v67, v67
	v_pk_mul_f32 v[86:87], v[86:87], v[90:91]
	v_add_f32_e32 v62, v190, v62
	v_pk_mul_f32 v[82:83], v[86:87], v[82:83]
	v_add_f32_e32 v86, v179, v92
	v_mul_f32_e32 v86, 0xbfb8aa3b, v86
	v_exp_f32_e32 v86, v86
	v_fmac_f32_e32 v83, v105, v82
	v_add_f32_e32 v63, v190, v63
	v_mul_f32_e32 v62, 0xbfb8aa3b, v62
	v_add_f32_e32 v86, 1.0, v86
	v_rcp_f32_e32 v87, v86
	v_add_f32_e32 v86, v181, v88
	v_mul_f32_e32 v86, 0xbfb8aa3b, v86
	v_exp_f32_e32 v86, v86
	v_mul_f32_e32 v87, v183, v87
	v_exp_f32_e32 v91, v87
	v_add_f32_e32 v87, v179, v93
	v_mul_f32_e32 v87, 0xbfb8aa3b, v87
	v_exp_f32_e32 v87, v87
	v_fma_f32 v82, -v91, v91, 1.0
	v_add_f32_e32 v86, 1.0, v86
	v_max_f32_e32 v82, 0, v82
	v_add_f32_e32 v87, 1.0, v87
	v_rcp_f32_e32 v87, v87
	v_rcp_f32_e32 v86, v86
	v_sqrt_f32_e32 v90, v82
	v_add_f32_e32 v88, v181, v89
	v_mul_f32_e32 v87, v183, v87
	v_exp_f32_e32 v93, v87
	v_mov_b32_e32 v87, v83
	v_pk_mul_f32 v[82:83], v[86:87], v[90:91]
	v_exp_f32_e32 v86, v78
	v_exp_f32_e32 v87, v79
	v_mul_f32_e32 v88, 0xbfb8aa3b, v88
	v_exp_f32_e32 v88, v88
	v_fma_f32 v78, -v86, v86, 1.0
	v_fma_f32 v79, -v87, v87, 1.0
	v_max_f32_e32 v78, 0, v78
	v_max_f32_e32 v79, 0, v79
	v_sqrt_f32_e32 v78, v78
	v_sqrt_f32_e32 v79, v79
	v_fmac_f32_e32 v83, v82, v84
	v_fma_f32 v82, -v93, v93, 1.0
	v_add_f32_e32 v88, 1.0, v88
	v_max_f32_e32 v82, 0, v82
	v_rcp_f32_e32 v88, v88
	v_sqrt_f32_e32 v92, v82
	v_pk_mul_f32 v[74:75], v[74:75], v[78:79]
	v_add_f32_e32 v78, v184, v80
	v_mul_f32_e32 v78, 0xbfb8aa3b, v78
	v_mov_b32_e32 v89, v83
	v_exp_f32_e32 v78, v78
	v_pk_mul_f32 v[82:83], v[88:89], v[92:93]
	v_rcp_f32_e32 v80, v77
	v_fmac_f32_e32 v83, v82, v85
	v_mul_f32_e32 v82, v105, v103
	v_mul_f32_e32 v82, v91, v82
	v_mul_f32_e32 v82, v93, v82
	v_add_f32_e32 v78, 1.0, v78
	ds_bpermute_b32 v103, v151, v82
	ds_bpermute_b32 v107, v151, v82 offset:64
	ds_bpermute_b32 v111, v151, v82 offset:128
	ds_bpermute_b32 v115, v151, v82 offset:192
	v_rcp_f32_e32 v78, v78
	ds_bpermute_b32 v105, v151, v83
	ds_bpermute_b32 v109, v151, v83 offset:64
	ds_bpermute_b32 v113, v151, v83 offset:128
	ds_bpermute_b32 v117, v151, v83 offset:192
	v_mul_f32_e32 v78, v188, v78
	s_waitcnt lgkmcnt(6)
; __device__ __forceinline__ float fsig2(float x) { return __builtin_amdgcn_rcpf(1.0f + __builtin_amdgcn_exp2f(-LOG2E * x)); }
; template <int PASS> __device__ __forceinline__ void lru_wave_item(LAS unsigned char* lds, LAS unsigned char* vw, int b, int c, int h, const MixP& p, int lane, float (&Hrun)[8], bool cont) {
;     ...
;         for (int n = 0; n < 8; ++n) {
;             const f32x4 aVn = __builtin_amdgcn_mfma_f32_16x16x32_bf16(af[n >> 1], idf[n & 1], (f32x4){0.f, 0.f, 0.f, 0.f}, 0, 0, 0);
;             float av[4], bxv[4];
; #pragma unroll
;             for (int j = 0; j < 4; ++j) {
;                 const float r = fsig2(aR[n][j] + pba[n]), ig = fsig2(aI[n][j] + pbx[n]);
;                 const float a = __builtin_amdgcn_exp2f(r * pk8[n]), mult = __builtin_amdgcn_sqrtf(fmaxf(1.0f - a * a, 0.f));
;                 av[j] = a; bxv[j] = mult * ig * aVn[j];
;             }
;             const float H0 = bxv[0], H1 = av[1] * H0 + bxv[1], H2 = av[2] * H1 + bxv[2], H3 = av[3] * H2 + bxv[3];
;             const float A0 = av[0], A1 = av[1] * A0, A2 = av[2] * A1, A3 = av[3] * A2;
;             float At[4], Ht[4];
; #pragma unroll
;             for (int q = 0; q < 4; ++q) { At[q] = __shfl(A3, fr + 16 * q); Ht[q] = __shfl(H3, fr + 16 * q); }
;             const float c0 = Hrun[n], c1 = At[0] * c0 + Ht[0], c2 = At[1] * c1 + Ht[1], c3 = At[2] * c2 + Ht[2], c4 = At[3] * c3 + Ht[3];
;             Hrun[n] = c4;
;             if (PASS == 1) Arun[n] *= (At[0] * At[1]) * (At[2] * At[3]);
	v_pk_mul_f32 v[82:83], v[102:103], v[106:107]
	s_waitcnt lgkmcnt(4)
	v_pk_mul_f32 v[84:85], v[110:111], v[114:115]
	v_exp_f32_e32 v79, v78
	v_add_f32_e32 v78, v184, v81
	v_pk_mul_f32 v[82:83], v[82:83], v[84:85]
	s_waitcnt lgkmcnt(3)
	v_pk_fma_f32 v[84:85], v[166:167], v[102:103], v[104:105]
	v_mul_f32_e32 v78, 0xbfb8aa3b, v78
	s_waitcnt lgkmcnt(2)
	v_pk_fma_f32 v[84:85], v[84:85], v[106:107], v[108:109]
	v_exp_f32_e32 v78, v78
	s_waitcnt lgkmcnt(1)
	v_pk_fma_f32 v[84:85], v[84:85], v[110:111], v[112:113]
	v_pk_mul_f32 v[168:169], v[168:169], v[82:83]
	s_waitcnt lgkmcnt(0)
	v_pk_fma_f32 v[166:167], v[84:85], v[114:115], v[116:117]
	v_mfma_f32_16x16x32_bf16 v[82:85], v[54:57], v[2:5], 0
	v_add_f32_e32 v78, 1.0, v78
	v_rcp_f32_e32 v78, v78
	v_mul_f32_e32 v63, 0xbfb8aa3b, v63
	v_mfma_f32_16x16x32_bf16 v[54:57], v[54:57], v[6:9], 0
	v_exp_f32_e32 v62, v62
	s_nop 2
	v_pk_mul_f32 v[74:75], v[74:75], v[82:83]
	v_mul_f32_e32 v77, v188, v78
	v_fmac_f32_e32 v75, v87, v74
	v_fma_f32 v74, -v79, v79, 1.0
	v_max_f32_e32 v74, 0, v74
	v_sqrt_f32_e32 v78, v74
	v_exp_f32_e32 v83, v77
	v_mov_b32_e32 v77, v75
	v_exp_f32_e32 v63, v63
	v_pk_mul_f32 v[74:75], v[76:77], v[78:79]
	v_add_f32_e32 v62, 1.0, v62
	v_fmac_f32_e32 v75, v74, v84
	v_fma_f32 v74, -v83, v83, 1.0
	v_max_f32_e32 v74, 0, v74
	v_sqrt_f32_e32 v82, v74
	v_mov_b32_e32 v81, v75
	v_add_f32_e32 v63, 1.0, v63
	v_rcp_f32_e32 v62, v62
	v_pk_mul_f32 v[74:75], v[80:81], v[82:83]
	v_rcp_f32_e32 v63, v63
	v_fmac_f32_e32 v75, v74, v85
	v_mul_f32_e32 v74, v87, v86
	v_mul_f32_e32 v74, v79, v74
	v_mul_f32_e32 v77, v83, v74
	ds_bpermute_b32 v74, v151, v77
	ds_bpermute_b32 v76, v151, v75
	ds_bpermute_b32 v78, v151, v77 offset:64
	ds_bpermute_b32 v80, v151, v75 offset:64
	ds_bpermute_b32 v82, v151, v77 offset:128
	ds_bpermute_b32 v84, v151, v75 offset:128
	ds_bpermute_b32 v86, v151, v77 offset:192
	ds_bpermute_b32 v88, v151, v75 offset:192
	v_exp_f32_e32 v75, v70
	v_exp_f32_e32 v77, v71
	v_add_f32_e32 v58, v192, v58
	v_mul_f32_e32 v62, v194, v62
	v_fma_f32 v70, -v75, v75, 1.0
	v_fma_f32 v71, -v77, v77, 1.0
	v_max_f32_e32 v70, 0, v70
	v_max_f32_e32 v71, 0, v71
	v_sqrt_f32_e32 v70, v70
	v_sqrt_f32_e32 v71, v71
	v_add_f32_e32 v59, v192, v59
	v_mul_f32_e32 v63, v194, v63
	v_mul_f32_e32 v58, 0xbfb8aa3b, v58
	v_pk_mul_f32 v[66:67], v[66:67], v[70:71]
	v_mul_f32_e32 v59, 0xbfb8aa3b, v59
	v_pk_mul_f32 v[54:55], v[66:67], v[54:55]
	v_add_f32_e32 v66, v185, v72
	v_mul_f32_e32 v66, 0xbfb8aa3b, v66
	v_exp_f32_e32 v66, v66
	v_fmac_f32_e32 v55, v77, v54
	v_exp_f32_e32 v58, v58
	v_exp_f32_e32 v59, v59
	v_add_f32_e32 v66, 1.0, v66
	v_rcp_f32_e32 v67, v66
	v_add_f32_e32 v66, v187, v68
	v_mul_f32_e32 v66, 0xbfb8aa3b, v66
	v_exp_f32_e32 v66, v66
	v_mul_f32_e32 v67, v189, v67
	v_exp_f32_e32 v71, v67
	v_add_f32_e32 v67, v185, v73
	v_mul_f32_e32 v67, 0xbfb8aa3b, v67
	v_exp_f32_e32 v67, v67
	v_fma_f32 v54, -v71, v71, 1.0
	v_add_f32_e32 v66, 1.0, v66
	v_max_f32_e32 v54, 0, v54
	v_add_f32_e32 v67, 1.0, v67
	v_rcp_f32_e32 v67, v67
	v_rcp_f32_e32 v66, v66
	v_add_f32_e32 v68, v187, v69
	v_sqrt_f32_e32 v70, v54
	v_mul_f32_e32 v67, v189, v67
	v_mul_f32_e32 v68, 0xbfb8aa3b, v68
	v_exp_f32_e32 v73, v67
	v_exp_f32_e32 v68, v68
	v_mov_b32_e32 v67, v55
	v_pk_mul_f32 v[54:55], v[66:67], v[70:71]
	v_exp_f32_e32 v66, v62
	v_fmac_f32_e32 v55, v54, v56
	v_fma_f32 v54, -v73, v73, 1.0
	v_add_f32_e32 v68, 1.0, v68
	v_max_f32_e32 v54, 0, v54
	v_rcp_f32_e32 v68, v68
	v_sqrt_f32_e32 v72, v54
	v_mov_b32_e32 v69, v55
	v_exp_f32_e32 v67, v63
	v_fma_f32 v62, -v66, v66, 1.0
	v_pk_mul_f32 v[54:55], v[68:69], v[72:73]
	v_add_f32_e32 v58, 1.0, v58
	v_fmac_f32_e32 v55, v54, v57
	v_mul_f32_e32 v54, v77, v75
	v_mul_f32_e32 v54, v71, v54
	v_mul_f32_e32 v54, v73, v54
	ds_bpermute_b32 v75, v151, v54
	ds_bpermute_b32 v79, v151, v54 offset:64
	ds_bpermute_b32 v83, v151, v54 offset:128
	ds_bpermute_b32 v87, v151, v54 offset:192
	ds_bpermute_b32 v77, v151, v55
	ds_bpermute_b32 v81, v151, v55 offset:64
	ds_bpermute_b32 v85, v151, v55 offset:128
	ds_bpermute_b32 v89, v151, v55 offset:192
	s_waitcnt lgkmcnt(6)
	v_pk_mul_f32 v[54:55], v[74:75], v[78:79]
	s_waitcnt lgkmcnt(4)
	v_pk_mul_f32 v[56:57], v[82:83], v[86:87]
	v_fma_f32 v63, -v67, v67, 1.0
	v_pk_mul_f32 v[54:55], v[54:55], v[56:57]
	s_waitcnt lgkmcnt(3)
	v_pk_fma_f32 v[56:57], v[160:161], v[74:75], v[76:77]
	v_max_f32_e32 v62, 0, v62
	s_waitcnt lgkmcnt(2)
	v_pk_fma_f32 v[56:57], v[56:57], v[78:79], v[80:81]
	v_add_f32_e32 v59, 1.0, v59
	v_max_f32_e32 v63, 0, v63
	s_waitcnt lgkmcnt(1)
	v_pk_fma_f32 v[56:57], v[56:57], v[82:83], v[84:85]
	v_rcp_f32_e32 v58, v58
	v_sqrt_f32_e32 v62, v62
	v_rcp_f32_e32 v59, v59
	v_sqrt_f32_e32 v63, v63
	s_waitcnt lgkmcnt(0)
; __device__ __forceinline__ float fsig2(float x) { return __builtin_amdgcn_rcpf(1.0f + __builtin_amdgcn_exp2f(-LOG2E * x)); }
; template <int PASS> __device__ __forceinline__ void lru_wave_item(LAS unsigned char* lds, LAS unsigned char* vw, int b, int c, int h, const MixP& p, int lane, float (&Hrun)[8], bool cont) {
;     ...
;         for (int n = 0; n < 8; ++n) {
;             const f32x4 aVn = __builtin_amdgcn_mfma_f32_16x16x32_bf16(af[n >> 1], idf[n & 1], (f32x4){0.f, 0.f, 0.f, 0.f}, 0, 0, 0);
;             float av[4], bxv[4];
; #pragma unroll
;             for (int j = 0; j < 4; ++j) {
;                 const float r = fsig2(aR[n][j] + pba[n]), ig = fsig2(aI[n][j] + pbx[n]);
;                 const float a = __builtin_amdgcn_exp2f(r * pk8[n]), mult = __builtin_amdgcn_sqrtf(fmaxf(1.0f - a * a, 0.f));
;                 av[j] = a; bxv[j] = mult * ig * aVn[j];
;             }
;             const float H0 = bxv[0], H1 = av[1] * H0 + bxv[1], H2 = av[2] * H1 + bxv[2], H3 = av[3] * H2 + bxv[3];
;             const float A0 = av[0], A1 = av[1] * A0, A2 = av[2] * A1, A3 = av[3] * A2;
;             float At[4], Ht[4];
; #pragma unroll
;             for (int q = 0; q < 4; ++q) { At[q] = __shfl(A3, fr + 16 * q); Ht[q] = __shfl(H3, fr + 16 * q); }
;             const float c0 = Hrun[n], c1 = At[0] * c0 + Ht[0], c2 = At[1] * c1 + Ht[1], c3 = At[2] * c2 + Ht[2], c4 = At[3] * c3 + Ht[3];
;             Hrun[n] = c4;
;             if (PASS == 1) Arun[n] *= (At[0] * At[1]) * (At[2] * At[3]);
;     ...
;     if (PASS == 1 && fq == 0) {
; #pragma unroll
;         for (int n = 0; n < 8; ++n) *(f32x2*)(p.summ + (((size_t)b * NCH + c) * LW + h * 128 + 16 * n + fr) * 2) = (f32x2){Arun[n], Hrun[n]};
;     }
	v_pk_fma_f32 v[160:161], v[56:57], v[86:87], v[88:89]
	v_pk_mul_f32 v[164:165], v[164:165], v[54:55]
	v_mfma_f32_16x16x32_bf16 v[54:57], v[50:53], v[2:5], 0
	v_mul_f32_e64 v58, v58, v62
	v_mul_f32_e64 v59, v59, v63
	v_mfma_f32_16x16x32_bf16 v[50:53], v[50:53], v[6:9], 0
	s_nop 4
	v_mul_f32_e64 v54, v58, v54
	v_mul_f32_e64 v55, v59, v55
	v_add_f32_e32 v58, v190, v64
	v_mul_f32_e32 v58, 0xbfb8aa3b, v58
	v_exp_f32_e32 v58, v58
	v_fmac_f32_e32 v55, v67, v54
	v_add_f32_e32 v58, 1.0, v58
	v_rcp_f32_e32 v59, v58
	v_add_f32_e32 v58, v192, v60
	v_mul_f32_e32 v58, 0xbfb8aa3b, v58
	v_exp_f32_e32 v58, v58
	v_mul_f32_e32 v59, v194, v59
	v_exp_f32_e32 v63, v59
	v_add_f32_e32 v59, v190, v65
	v_mul_f32_e32 v59, 0xbfb8aa3b, v59
	v_exp_f32_e32 v59, v59
	v_fma_f32 v54, -v63, v63, 1.0
	v_add_f32_e32 v58, 1.0, v58
	v_max_f32_e32 v54, 0, v54
	v_add_f32_e32 v59, 1.0, v59
	v_rcp_f32_e32 v59, v59
	v_rcp_f32_e32 v58, v58
	v_add_f32_e32 v60, v192, v61
	v_sqrt_f32_e32 v62, v54
	v_mul_f32_e32 v59, v194, v59
	v_mul_f32_e32 v60, 0xbfb8aa3b, v60
	v_exp_f32_e32 v65, v59
	v_exp_f32_e32 v60, v60
	v_mov_b32_e32 v59, v55
	v_pk_mul_f32 v[54:55], v[58:59], v[62:63]
	v_add_f32_e32 v59, v193, v95
	v_fmac_f32_e32 v55, v54, v56
	v_fma_f32 v54, -v65, v65, 1.0
	v_add_f32_e32 v60, 1.0, v60
	v_max_f32_e32 v54, 0, v54
	v_rcp_f32_e32 v60, v60
	v_sqrt_f32_e32 v64, v54
	v_mov_b32_e32 v61, v55
	v_mul_f32_e32 v59, 0xbfb8aa3b, v59
	v_exp_f32_e32 v59, v59
	v_pk_mul_f32 v[54:55], v[60:61], v[64:65]
	v_add_f32_e32 v61, v193, v96
	v_fmac_f32_e32 v55, v54, v57
	ds_bpermute_b32 v56, v151, v55
	ds_bpermute_b32 v60, v151, v55 offset:64
	ds_bpermute_b32 v64, v151, v55 offset:128
	ds_bpermute_b32 v68, v151, v55 offset:192
	v_add_f32_e32 v55, v191, v98
	v_mul_f32_e32 v55, 0xbfb8aa3b, v55
	v_exp_f32_e32 v55, v55
	v_mul_f32_e32 v54, v67, v66
	v_mul_f32_e32 v54, v63, v54
	v_mul_f32_e32 v57, v65, v54
	v_add_f32_e32 v55, 1.0, v55
	v_rcp_f32_e32 v55, v55
	ds_bpermute_b32 v54, v151, v57
	ds_bpermute_b32 v58, v151, v57 offset:64
	ds_bpermute_b32 v62, v151, v57 offset:128
	ds_bpermute_b32 v66, v151, v57 offset:192
	v_add_f32_e32 v57, v193, v94
	v_mul_f32_e32 v57, 0xbfb8aa3b, v57
	v_exp_f32_e32 v57, v57
	v_mul_f32_e32 v55, v195, v55
	v_exp_f32_e32 v55, v55
	v_add_f32_e32 v59, 1.0, v59
	v_add_f32_e32 v57, 1.0, v57
	v_rcp_f32_e32 v70, v57
	v_fma_f32 v57, -v55, v55, 1.0
	v_max_f32_e32 v57, 0, v57
	v_sqrt_f32_e32 v72, v57
	v_add_f32_e32 v57, v191, v99
	v_mul_f32_e32 v57, 0xbfb8aa3b, v57
	v_exp_f32_e32 v57, v57
	v_rcp_f32_e32 v71, v59
	v_mul_f32_e32 v61, 0xbfb8aa3b, v61
	v_exp_f32_e32 v61, v61
	v_add_f32_e32 v57, 1.0, v57
	v_rcp_f32_e32 v57, v57
	v_add_f32_e32 v61, 1.0, v61
	v_mul_f32_e32 v57, v195, v57
	v_exp_f32_e32 v57, v57
	s_nop 0
	v_fma_f32 v59, -v57, v57, 1.0
	v_max_f32_e32 v59, 0, v59
	v_sqrt_f32_e32 v73, v59
	v_add_f32_e32 v59, v191, v100
	v_mul_f32_e32 v59, 0xbfb8aa3b, v59
	v_exp_f32_e32 v59, v59
	v_pk_mul_f32 v[70:71], v[70:71], v[72:73]
	v_add_f32_e32 v59, 1.0, v59
	v_rcp_f32_e32 v59, v59
	v_pk_mul_f32 v[50:51], v[70:71], v[50:51]
	v_rcp_f32_e32 v70, v61
	v_fmac_f32_e32 v51, v57, v50
	v_mul_f32_e32 v59, v195, v59
	v_exp_f32_e32 v73, v59
	v_add_f32_e32 v59, v191, v101
	v_mul_f32_e32 v59, 0xbfb8aa3b, v59
	v_exp_f32_e32 v59, v59
	v_fma_f32 v50, -v73, v73, 1.0
	v_max_f32_e32 v50, 0, v50
	v_add_f32_e32 v61, v193, v97
	v_add_f32_e32 v59, 1.0, v59
	v_rcp_f32_e32 v59, v59
	v_sqrt_f32_e32 v72, v50
	v_mul_f32_e32 v61, 0xbfb8aa3b, v61
	v_exp_f32_e32 v61, v61
	v_mul_f32_e32 v59, v195, v59
	v_exp_f32_e32 v77, v59
	v_mov_b32_e32 v71, v51
	v_pk_mul_f32 v[50:51], v[70:71], v[72:73]
	v_add_f32_e32 v61, 1.0, v61
	v_fmac_f32_e32 v51, v50, v52
	v_fma_f32 v50, -v77, v77, 1.0
	v_max_f32_e32 v50, 0, v50
	v_rcp_f32_e32 v74, v61
	v_sqrt_f32_e32 v76, v50
	v_mov_b32_e32 v75, v51
	v_pk_mul_f32 v[50:51], v[74:75], v[76:77]
	s_nop 0
	v_fmac_f32_e32 v51, v50, v53
	v_mul_f32_e32 v50, v57, v55
	v_mul_f32_e32 v50, v73, v50
	v_mul_f32_e32 v50, v77, v50
	ds_bpermute_b32 v55, v151, v50
	ds_bpermute_b32 v59, v151, v50 offset:64
	ds_bpermute_b32 v63, v151, v50 offset:128
	ds_bpermute_b32 v67, v151, v50 offset:192
	ds_bpermute_b32 v57, v151, v51
	ds_bpermute_b32 v61, v151, v51 offset:64
	ds_bpermute_b32 v65, v151, v51 offset:128
	ds_bpermute_b32 v69, v151, v51 offset:192
	s_waitcnt lgkmcnt(6)
	v_pk_mul_f32 v[50:51], v[54:55], v[58:59]
	s_waitcnt lgkmcnt(4)
	v_pk_mul_f32 v[52:53], v[62:63], v[66:67]
	s_nop 0
	v_pk_mul_f32 v[50:51], v[50:51], v[52:53]
	s_waitcnt lgkmcnt(3)
	v_pk_fma_f32 v[52:53], v[156:157], v[54:55], v[56:57]
	v_pk_mul_f32 v[158:159], v[158:159], v[50:51]
	s_waitcnt lgkmcnt(2)
	v_pk_fma_f32 v[52:53], v[52:53], v[58:59], v[60:61]
	s_waitcnt lgkmcnt(1)
	v_pk_fma_f32 v[52:53], v[52:53], v[62:63], v[64:65]
	s_waitcnt lgkmcnt(0)
	v_pk_fma_f32 v[156:157], v[52:53], v[66:67], v[68:69]
	s_cbranch_vccz .LBB0_668
	s_and_saveexec_b64 s[28:29], s[4:5]
	s_cbranch_execz .LBB0_666
	s_ashr_i32 s59, s58, 31
	s_lshl_b64 s[16:17], s[58:59], 6
	s_ashr_i32 s2, s11, 31
	s_add_u32 s3, s16, s11
	s_addc_u32 s2, s17, s2
	s_mulk_i32 s2, 0x500
	v_mad_u64_u32 v[10:11], s[16:17], s3, v217, v[152:153]
	v_add_u32_e32 v11, s2, v11
	v_mov_b32_e32 v12, v163
	v_mov_b32_e32 v13, v173
	v_lshl_add_u64 v[10:11], v[10:11], 3, s[94:95]
	global_store_dwordx2 v[10:11], v[12:13], off sc1
	v_mov_b32_e32 v12, v168
	v_mov_b32_e32 v13, v166
	global_store_dwordx2 v[10:11], v[12:13], off offset:256 sc1
	v_mov_b32_e32 v12, v164
	v_mov_b32_e32 v13, v160
	v_mov_b32_e32 v163, v172
	v_mov_b32_e32 v166, v169
	global_store_dwordx2 v[10:11], v[12:13], off offset:512 sc1
	v_mov_b32_e32 v160, v165
	v_mov_b32_e32 v12, v158
	v_mov_b32_e32 v13, v156
	v_mov_b32_e32 v156, v159
	global_store_dwordx2 v[10:11], v[162:163], off offset:128 sc1
	global_store_dwordx2 v[10:11], v[166:167], off offset:384 sc1
	global_store_dwordx2 v[10:11], v[160:161], off offset:640 sc1
	global_store_dwordx2 v[10:11], v[12:13], off offset:768 sc1
	global_store_dwordx2 v[10:11], v[156:157], off offset:896 sc1
	s_branch .LBB0_666

; #define LAS __attribute__((address_space(3)))
; __device__ __forceinline__ unsigned cvt_pk_bf16(float lo, float hi) { unsigned r; asm volatile("v_cvt_pk_bf16_f32 %0, %1, %2" : "=v"(r) : "v"(lo), "v"(hi)); return r; }
; __device__ __forceinline__ void pool_items(LAS unsigned char* lds, LAS unsigned char* vw, int g, int wi, int nw, const MixP& p, int lane) {
;     ...
;             bf16x8 af[4];
; #pragma unroll
;             for (int kk = 0; kk < 4; ++kk) af[kk] = *(const LAS bf16x8*)(vw + fr * WROW + kk * 64 + fq * 16);
;             f32x4 acc[8];
; #pragma unroll
;             for (int n = 0; n < 8; ++n) { acc[n] = (f32x4){0.f, 0.f, 0.f, 0.f};
; #pragma unroll
;                 for (int kk = 0; kk < 4; ++kk) acc[n] = __builtin_amdgcn_mfma_f32_16x16x32_bf16(af[kk], *(const LAS bf16x8*)(lds + WP_OFF + (16 * n + fr) * WROW + kk * 64 + fq * 16), acc[n], 0, 0, 0); }
; #pragma unroll
;             for (int n = 0; n < 8; ++n)
; #pragma unroll
;                 for (int jj = 0; jj < 4; jj += 2) { const unsigned w = cvt_pk_bf16((acc[n][jj] + pb[n]) * ps[n], (acc[n][jj + 1] + pb[n]) * ps[n]);
;                     *(LAS unsigned short*)(vw + (4 * fq + jj) * WROW + (16 * n + fr) * 2) = (unsigned short)(w & 0xffffu);
;                     *(LAS unsigned short*)(vw + (4 * fq + jj + 1) * WROW + (16 * n + fr) * 2) = (unsigned short)(w >> 16); }
.LBB0_676:
	ds_write_b128 v248, v[10:13]
	v_add_u32_e32 v10, v232, v233
	v_add_u32_e32 v60, v240, v231
	ds_read_b128 v[26:29], v10
	ds_read_b128 v[22:25], v10 offset:64
	ds_read_b128 v[18:21], v10 offset:128
	ds_read_b128 v[14:17], v10 offset:192
	ds_read_b128 v[10:13], v60
	ds_read_b128 v[32:35], v60 offset:64
	s_waitcnt lgkmcnt(1)
	v_mfma_f32_16x16x32_bf16 v[10:13], v[26:29], v[10:13], 0
	ds_read_b128 v[36:39], v60 offset:4416
	v_add_u32_e32 v48, v240, v235
	s_or_b32 s2, s55, s28
	s_waitcnt lgkmcnt(1)
	v_mfma_f32_16x16x32_bf16 v[10:13], v[22:25], v[32:35], v[10:13]
	ds_read_b128 v[32:35], v60 offset:128
	ds_read_b128 v[40:43], v60 offset:8768
	s_mov_b32 s10, 16
	s_waitcnt lgkmcnt(1)
	v_mfma_f32_16x16x32_bf16 v[10:13], v[18:21], v[32:35], v[10:13]
	ds_read_b128 v[32:35], v60 offset:192
	s_mov_b64 s[8:9], 0
	s_and_b64 vcc, exec, s[58:59]
	s_waitcnt lgkmcnt(0)
	v_mfma_f32_16x16x32_bf16 v[10:13], v[14:17], v[32:35], v[10:13]
	ds_read_b128 v[32:35], v60 offset:4352
	ds_read_b128 v[44:47], v48 offset:64
	ds_read_b128 v[52:55], v60 offset:21824
	s_waitcnt lgkmcnt(2)
	v_mfma_f32_16x16x32_bf16 v[32:35], v[26:29], v[32:35], 0
	s_waitcnt vmcnt(15)
	s_nop 1
	v_add_f32_e32 v10, v62, v10
	s_waitcnt vmcnt(7)
	v_mul_f32_e32 v10, v70, v10
	v_add_f32_e32 v11, v62, v11
	v_mfma_f32_16x16x32_bf16 v[32:35], v[22:25], v[36:39], v[32:35]
	ds_read_b128 v[36:39], v60 offset:4480
	v_mul_f32_e32 v11, v70, v11
	ds_read_b128 v[56:59], v60 offset:26176
	s_waitcnt lgkmcnt(1)
	v_mfma_f32_16x16x32_bf16 v[32:35], v[18:21], v[36:39], v[32:35]
	ds_read_b128 v[36:39], v60 offset:4544
	s_waitcnt lgkmcnt(0)
	v_mfma_f32_16x16x32_bf16 v[32:35], v[14:17], v[36:39], v[32:35]
	ds_read_b128 v[36:39], v60 offset:8704
	s_waitcnt lgkmcnt(0)
	v_mfma_f32_16x16x32_bf16 v[36:39], v[26:29], v[36:39], 0
	v_mfma_f32_16x16x32_bf16 v[36:39], v[22:25], v[40:43], v[36:39]
	ds_read_b128 v[40:43], v60 offset:8832
	s_waitcnt lgkmcnt(0)
	v_mfma_f32_16x16x32_bf16 v[36:39], v[18:21], v[40:43], v[36:39]
	ds_read_b128 v[40:43], v60 offset:8896
	s_waitcnt lgkmcnt(0)
	v_mfma_f32_16x16x32_bf16 v[36:39], v[14:17], v[40:43], v[36:39]
	ds_read_b128 v[40:43], v48
	s_waitcnt lgkmcnt(0)
	v_mfma_f32_16x16x32_bf16 v[40:43], v[26:29], v[40:43], 0
	v_mfma_f32_16x16x32_bf16 v[40:43], v[22:25], v[44:47], v[40:43]
	ds_read_b128 v[44:47], v48 offset:128
	s_waitcnt lgkmcnt(0)
	v_mfma_f32_16x16x32_bf16 v[40:43], v[18:21], v[44:47], v[40:43]
	ds_read_b128 v[44:47], v48 offset:192
	ds_read_b128 v[48:51], v60 offset:17472
	s_waitcnt lgkmcnt(1)
	v_mfma_f32_16x16x32_bf16 v[40:43], v[14:17], v[44:47], v[40:43]
	ds_read_b128 v[44:47], v60 offset:17408
	s_waitcnt lgkmcnt(0)
	v_mfma_f32_16x16x32_bf16 v[44:47], v[26:29], v[44:47], 0
	v_mfma_f32_16x16x32_bf16 v[44:47], v[22:25], v[48:51], v[44:47]
	ds_read_b128 v[48:51], v60 offset:17536
	s_waitcnt lgkmcnt(0)
	v_mfma_f32_16x16x32_bf16 v[44:47], v[18:21], v[48:51], v[44:47]
	ds_read_b128 v[48:51], v60 offset:17600
	s_waitcnt lgkmcnt(0)
	v_mfma_f32_16x16x32_bf16 v[44:47], v[14:17], v[48:51], v[44:47]
	ds_read_b128 v[48:51], v60 offset:21760
	s_waitcnt lgkmcnt(0)
	v_mfma_f32_16x16x32_bf16 v[48:51], v[26:29], v[48:51], 0
	v_mfma_f32_16x16x32_bf16 v[48:51], v[22:25], v[52:55], v[48:51]
	ds_read_b128 v[52:55], v60 offset:21888
	s_waitcnt lgkmcnt(0)
	v_mfma_f32_16x16x32_bf16 v[48:51], v[18:21], v[52:55], v[48:51]
	ds_read_b128 v[52:55], v60 offset:21952
	s_waitcnt lgkmcnt(0)
	v_mfma_f32_16x16x32_bf16 v[48:51], v[14:17], v[52:55], v[48:51]
	ds_read_b128 v[52:55], v60 offset:26112
	s_waitcnt lgkmcnt(0)
	v_mfma_f32_16x16x32_bf16 v[52:55], v[26:29], v[52:55], 0
	v_mfma_f32_16x16x32_bf16 v[52:55], v[22:25], v[56:59], v[52:55]
	ds_read_b128 v[56:59], v60 offset:26240
	s_waitcnt lgkmcnt(0)
	v_mfma_f32_16x16x32_bf16 v[52:55], v[18:21], v[56:59], v[52:55]
	ds_read_b128 v[56:59], v60 offset:26304
	v_add_u32_e32 v60, v240, v236
	s_waitcnt lgkmcnt(0)
	v_mfma_f32_16x16x32_bf16 v[52:55], v[14:17], v[56:59], v[52:55]
	ds_read_b128 v[56:59], v60
	s_waitcnt lgkmcnt(0)
	v_mfma_f32_16x16x32_bf16 v[26:29], v[26:29], v[56:59], 0
	ds_read_b128 v[56:59], v60 offset:64
	s_waitcnt lgkmcnt(0)
	v_mfma_f32_16x16x32_bf16 v[22:25], v[22:25], v[56:59], v[26:29]
	s_nop 4
	ds_read_b128 v[26:29], v60 offset:128
	s_waitcnt lgkmcnt(0)
	v_mfma_f32_16x16x32_bf16 v[18:21], v[18:21], v[26:29], v[22:25]
	s_nop 2
	ds_read_b128 v[22:25], v60 offset:192
	v_cvt_pk_bf16_f32 v10, v10, v11
	ds_write_b16 v249, v10
	ds_write_b16_d16_hi v249, v10 offset:272
	v_add_f32_e32 v10, v62, v12
	v_mul_f32_e32 v10, v70, v10
	v_add_f32_e32 v11, v62, v13
	v_mul_f32_e32 v11, v70, v11
	v_cvt_pk_bf16_f32 v10, v10, v11
	ds_write_b16 v249, v10 offset:544
	ds_write_b16_d16_hi v249, v10 offset:816
	v_add_f32_e32 v10, v63, v32
	s_waitcnt vmcnt(6)
; #define LAS __attribute__((address_space(3)))
; __device__ __forceinline__ unsigned cvt_pk_bf16(float lo, float hi) { unsigned r; asm volatile("v_cvt_pk_bf16_f32 %0, %1, %2" : "=v"(r) : "v"(lo), "v"(hi)); return r; }
; __device__ __forceinline__ void pool_items(LAS unsigned char* lds, LAS unsigned char* vw, int g, int wi, int nw, const MixP& p, int lane) {
;     ...
;                 for (int jj = 0; jj < 4; jj += 2) { const unsigned w = cvt_pk_bf16((acc[n][jj] + pb[n]) * ps[n], (acc[n][jj + 1] + pb[n]) * ps[n]);
;                     *(LAS unsigned short*)(vw + (4 * fq + jj) * WROW + (16 * n + fr) * 2) = (unsigned short)(w & 0xffffu);
;                     *(LAS unsigned short*)(vw + (4 * fq + jj + 1) * WROW + (16 * n + fr) * 2) = (unsigned short)(w >> 16); }
; #pragma unroll
;             for (int i = 0; i < 4; ++i) { const int t = fq + 4 * i;
;                 *(u32x4*)(p.mixed + (size_t)(b * SEQ + s0 + t) * PW + g * 128 + cg * 8) = *(const LAS u32x4*)(vw + t * WROW + cg * 16); }
	v_mul_f32_e32 v10, v71, v10
	v_add_f32_e32 v11, v63, v33
	v_mul_f32_e32 v11, v71, v11
	v_cvt_pk_bf16_f32 v10, v10, v11
	ds_write_b16 v249, v10 offset:32
	ds_write_b16_d16_hi v249, v10 offset:304
	v_add_f32_e32 v10, v63, v34
	v_mul_f32_e32 v10, v71, v10
	v_add_f32_e32 v11, v63, v35
	v_mul_f32_e32 v11, v71, v11
	v_cvt_pk_bf16_f32 v10, v10, v11
	ds_write_b16 v249, v10 offset:576
	ds_write_b16_d16_hi v249, v10 offset:848
	v_add_f32_e32 v10, v64, v36
	s_waitcnt vmcnt(5)
	v_mul_f32_e32 v10, v72, v10
	v_add_f32_e32 v11, v64, v37
	v_mul_f32_e32 v11, v72, v11
	v_cvt_pk_bf16_f32 v10, v10, v11
	ds_write_b16 v249, v10 offset:64
	ds_write_b16_d16_hi v249, v10 offset:336
	v_add_f32_e32 v10, v64, v38
	v_mul_f32_e32 v10, v72, v10
	v_add_f32_e32 v11, v64, v39
	v_mul_f32_e32 v11, v72, v11
	v_cvt_pk_bf16_f32 v10, v10, v11
	ds_write_b16 v249, v10 offset:608
	ds_write_b16_d16_hi v249, v10 offset:880
	v_add_f32_e32 v10, v65, v40
	s_waitcnt vmcnt(4)
	v_mul_f32_e32 v10, v73, v10
	v_add_f32_e32 v11, v65, v41
	v_mul_f32_e32 v11, v73, v11
	v_cvt_pk_bf16_f32 v10, v10, v11
	ds_write_b16 v249, v10 offset:96
	ds_write_b16_d16_hi v249, v10 offset:368
	v_add_f32_e32 v10, v65, v42
	v_mul_f32_e32 v10, v73, v10
	v_add_f32_e32 v11, v65, v43
	v_mul_f32_e32 v11, v73, v11
	v_cvt_pk_bf16_f32 v10, v10, v11
	ds_write_b16 v249, v10 offset:640
	ds_write_b16_d16_hi v249, v10 offset:912
	v_add_f32_e32 v10, v66, v44
	s_waitcnt vmcnt(3)
	v_mul_f32_e32 v10, v74, v10
	v_add_f32_e32 v11, v66, v45
	v_mul_f32_e32 v11, v74, v11
	v_cvt_pk_bf16_f32 v10, v10, v11
	ds_write_b16 v249, v10 offset:128
	ds_write_b16_d16_hi v249, v10 offset:400
	v_add_f32_e32 v10, v66, v46
	v_mul_f32_e32 v10, v74, v10
	v_add_f32_e32 v11, v66, v47
	v_mul_f32_e32 v11, v74, v11
	v_cvt_pk_bf16_f32 v10, v10, v11
	ds_write_b16 v249, v10 offset:672
	ds_write_b16_d16_hi v249, v10 offset:944
	v_add_f32_e32 v10, v67, v48
	s_waitcnt vmcnt(2)
	v_mul_f32_e32 v10, v75, v10
	v_add_f32_e32 v11, v67, v49
	v_mul_f32_e32 v11, v75, v11
	v_cvt_pk_bf16_f32 v10, v10, v11
	ds_write_b16 v249, v10 offset:160
	ds_write_b16_d16_hi v249, v10 offset:432
	v_add_f32_e32 v10, v67, v50
	v_mul_f32_e32 v10, v75, v10
	v_add_f32_e32 v11, v67, v51
	v_mul_f32_e32 v11, v75, v11
	v_cvt_pk_bf16_f32 v10, v10, v11
	ds_write_b16 v249, v10 offset:704
	ds_write_b16_d16_hi v249, v10 offset:976
	v_add_f32_e32 v10, v68, v52
	s_waitcnt vmcnt(1)
	v_mul_f32_e32 v10, v76, v10
	v_add_f32_e32 v11, v68, v53
	s_waitcnt lgkmcnt(14)
	v_mfma_f32_16x16x32_bf16 v[14:17], v[14:17], v[22:25], v[18:21]
	v_mul_f32_e32 v11, v76, v11
	v_cvt_pk_bf16_f32 v10, v10, v11
	ds_write_b16 v249, v10 offset:192
	ds_write_b16_d16_hi v249, v10 offset:464
	v_add_f32_e32 v10, v68, v54
	v_mul_f32_e32 v10, v76, v10
	v_add_f32_e32 v11, v68, v55
	v_mul_f32_e32 v11, v76, v11
	v_cvt_pk_bf16_f32 v10, v10, v11
	ds_write_b16 v249, v10 offset:736
	ds_write_b16_d16_hi v249, v10 offset:1008
	v_add_f32_e32 v10, v69, v14
	s_waitcnt vmcnt(0)
	v_mul_f32_e32 v10, v77, v10
	v_add_f32_e32 v11, v69, v15
	v_mul_f32_e32 v11, v77, v11
	v_cvt_pk_bf16_f32 v10, v10, v11
	ds_write_b16 v249, v10 offset:224
	ds_write_b16_d16_hi v249, v10 offset:496
	v_add_f32_e32 v10, v69, v16
	v_mul_f32_e32 v10, v77, v10
	v_add_f32_e32 v11, v69, v17
	v_mul_f32_e32 v11, v77, v11
	v_cvt_pk_bf16_f32 v10, v10, v11
	ds_write_b16 v249, v10 offset:768
	ds_write_b16_d16_hi v249, v10 offset:1040
	ds_read_b128 v[10:13], v250
	v_or_b32_e32 v14, s2, v223
	v_ashrrev_i32_e32 v15, 31, v14
	v_lshlrev_b64 v[14:15], 10, v[14:15]
	v_lshl_add_u64 v[14:15], v[146:147], 0, v[14:15]
	s_waitcnt lgkmcnt(0)
	global_store_dwordx4 v[14:15], v[10:13], off sc1
	ds_read_b128 v[10:13], v250 offset:1088
	v_or_b32_e32 v14, s2, v241
	v_ashrrev_i32_e32 v15, 31, v14
	v_lshlrev_b64 v[14:15], 10, v[14:15]
	v_lshl_add_u64 v[14:15], v[146:147], 0, v[14:15]
	s_waitcnt lgkmcnt(0)
	global_store_dwordx4 v[14:15], v[10:13], off sc1
	ds_read_b128 v[10:13], v250 offset:2176
	v_or_b32_e32 v14, s2, v242
	v_ashrrev_i32_e32 v15, 31, v14
	v_lshlrev_b64 v[14:15], 10, v[14:15]
	v_lshl_add_u64 v[14:15], v[146:147], 0, v[14:15]
	s_waitcnt lgkmcnt(0)
	global_store_dwordx4 v[14:15], v[10:13], off sc1
	ds_read_b128 v[10:13], v250 offset:3264
	v_or_b32_e32 v14, s2, v243
	v_ashrrev_i32_e32 v15, 31, v14
	v_lshlrev_b64 v[14:15], 10, v[14:15]
	v_lshl_add_u64 v[14:15], v[146:147], 0, v[14:15]
	s_waitcnt lgkmcnt(0)
	global_store_dwordx4 v[14:15], v[10:13], off sc1
	s_cbranch_vccnz .LBB0_674

; #define LAS __attribute__((address_space(3)))
; __device__ __forceinline__ unsigned cvt_pk_bf16(float lo, float hi) { unsigned r; asm volatile("v_cvt_pk_bf16_f32 %0, %1, %2" : "=v"(r) : "v"(lo), "v"(hi)); return r; }
; __device__ __forceinline__ void tr_item32(const float* W, int K, int N, bf16_t* WT, const float* gsc, bool swz, LAS float* scr, int item, int lane) {
;     ...
;     for (int hf = 0; hf < 2; ++hf)
; #pragma unroll
;         for (int i = 0; i < 4; ++i) v[hf][i] = *(const f32x4*)(W + (size_t)(k0 + kr + 8 * i) * N + n0 + 32 * hf + 4 * n4);
;     if (gsc) {
; #pragma unroll
;         for (int i = 0; i < 4; ++i) { const float gg = gsc[k0 + kr + 8 * i]; v[0][i] = v[0][i] * gg; v[1][i] = v[1][i] * gg; }
;     }
;     const int c = lane & 3;
; #pragma unroll
;     for (int hf = 0; hf < 2; ++hf) {
; #pragma unroll
;         for (int i = 0; i < 4; ++i)
; #pragma unroll
;             for (int e = 0; e < 4; ++e) scr[(kr + 8 * i) * 33 + 4 * n4 + e] = v[hf][i][e];
;         asm volatile("s_waitcnt lgkmcnt(0)" ::: "memory");
; #pragma unroll
;         for (int j = 0; j < 2; ++j) { const int n = (lane >> 2) + 16 * j; const LAS float* sp = scr + (8 * c) * 33 + n;
;             u32x4 o; o.x = cvt_pk_bf16(sp[0 * 33], sp[1 * 33]); o.y = cvt_pk_bf16(sp[2 * 33], sp[3 * 33]); o.z = cvt_pk_bf16(sp[4 * 33], sp[5 * 33]); o.w = cvt_pk_bf16(sp[6 * 33], sp[7 * 33]);
;             *(u32x4*)(WT + (size_t)(rbase + 32 * hf + n) * K + k0 + 8 * c) = o; }
;         asm volatile("s_waitcnt lgkmcnt(0)" ::: "memory");
;     }
; __device__ __forceinline__ void convert_dynamic(const Args& a, int l, bf16_t* slot, LAS float* scr, unsigned* counter, int lane) {
;     ...
;         unsigned it = 0u; if (lane == 0) it = __hip_atomic_fetch_add(counter, 4u, __ATOMIC_RELAXED, __HIP_MEMORY_SCOPE_AGENT);
;         it = (unsigned)__builtin_amdgcn_readfirstlane((int)it);
;         if (it >= (unsigned)J_LAYER) break;
;         for (unsigned u = 0; u < 4u && it + u < (unsigned)J_LAYER; ++u) convert_item(a, l, slot, scr, (int)(it + u), lane);
;     }
.LBB0_697:
	s_waitcnt vmcnt(7)
	ds_write2_b32 v251, v38, v39 offset1:1
	ds_write2_b32 v251, v40, v41 offset0:2 offset1:3
	v_add_u32_e32 v39, 0x428, v251
	v_add_u32_e32 v38, 0x420, v251
	s_waitcnt vmcnt(5)
	ds_write2_b32 v39, v36, v37 offset1:1
	v_add_u32_e32 v36, 0x840, v251
	v_add_u32_e32 v37, 0x848, v251
	v_add_u32_e32 v40, 0xc60, v251
	v_add_u32_e32 v41, 0xc68, v251
	ds_write2_b32 v38, v34, v35 offset1:1
	s_waitcnt vmcnt(3)
	ds_write2_b32 v36, v30, v31 offset1:1
	ds_write2_b32 v37, v32, v33 offset1:1
	s_waitcnt vmcnt(1)
	ds_write2_b32 v40, v26, v27 offset1:1
	ds_write2_b32 v41, v28, v29 offset1:1
	s_waitcnt lgkmcnt(0)
	ds_read2_b32 v[26:27], v226 offset1:33
	s_waitcnt lgkmcnt(0)
	v_cvt_pk_bf16_f32 v26, v26, v27
	ds_read2_b32 v[28:29], v226 offset0:66 offset1:99
	s_waitcnt lgkmcnt(0)
	v_cvt_pk_bf16_f32 v27, v28, v29
	ds_read2_b32 v[28:29], v226 offset0:132 offset1:165
	s_lshl_b32 s2, s23, 1
	s_waitcnt lgkmcnt(0)
	v_cvt_pk_bf16_f32 v28, v28, v29
	ds_read2_b32 v[30:31], v226 offset0:198 offset1:231
	s_add_u32 s10, s10, s2
	v_add_u32_e32 v34, s21, v237
	s_addc_u32 s11, s11, 0
	v_mov_b32_e32 v151, v1
	s_waitcnt lgkmcnt(0)
	v_cvt_pk_bf16_f32 v29, v30, v31
	v_ashrrev_i32_e32 v30, 31, v34
	v_lshl_add_u64 v[32:33], s[10:11], 0, v[150:151]
	v_mul_lo_u32 v42, s8, v30
	v_mul_lo_u32 v43, s9, v34
	v_mad_u64_u32 v[34:35], s[10:11], s8, v34, 0
	v_add3_u32 v35, v35, v42, v43
	v_lshl_add_u64 v[34:35], v[34:35], 1, v[32:33]
	ds_read2_b32 v[30:31], v226 offset0:16 offset1:49
	global_store_dwordx4 v[34:35], v[26:29], off sc1
	s_add_i32 s2, s21, 32
	s_waitcnt lgkmcnt(0)
	v_cvt_pk_bf16_f32 v26, v30, v31
	ds_read2_b32 v[28:29], v226 offset0:82 offset1:115
	s_waitcnt lgkmcnt(0)
	v_cvt_pk_bf16_f32 v27, v28, v29
	ds_read2_b32 v[28:29], v226 offset0:148 offset1:181
	s_waitcnt lgkmcnt(0)
	v_cvt_pk_bf16_f32 v28, v28, v29
	ds_read2_b32 v[30:31], v226 offset0:214 offset1:247
	s_waitcnt lgkmcnt(0)
	v_cvt_pk_bf16_f32 v29, v30, v31
	v_add_u32_e32 v30, s21, v245
	v_ashrrev_i32_e32 v31, 31, v30
	v_mul_lo_u32 v34, s8, v31
	v_mul_lo_u32 v35, s9, v30
	v_mad_u64_u32 v[30:31], s[10:11], s8, v30, 0
	v_add3_u32 v31, v31, v34, v35
	v_lshl_add_u64 v[30:31], v[30:31], 1, v[32:33]
	global_store_dwordx4 v[30:31], v[26:29], off sc1
	s_waitcnt lgkmcnt(0)
	ds_write2_b32 v251, v22, v23 offset1:1
	ds_write2_b32 v251, v24, v25 offset0:2 offset1:3
	ds_write2_b32 v38, v18, v19 offset1:1
	ds_write2_b32 v39, v20, v21 offset1:1
	ds_write2_b32 v36, v14, v15 offset1:1
	ds_write2_b32 v37, v16, v17 offset1:1
	s_waitcnt vmcnt(2)
	ds_write2_b32 v40, v10, v11 offset1:1
	ds_write2_b32 v41, v12, v13 offset1:1
	s_waitcnt lgkmcnt(0)
	ds_read2_b32 v[10:11], v226 offset1:33
	s_waitcnt lgkmcnt(0)
	v_cvt_pk_bf16_f32 v10, v10, v11
	ds_read2_b32 v[12:13], v226 offset0:66 offset1:99
	s_waitcnt lgkmcnt(0)
	v_cvt_pk_bf16_f32 v11, v12, v13
	ds_read2_b32 v[12:13], v226 offset0:132 offset1:165
	s_waitcnt lgkmcnt(0)
	v_cvt_pk_bf16_f32 v12, v12, v13
	ds_read2_b32 v[14:15], v226 offset0:198 offset1:231
	v_add_u32_e32 v16, s2, v237
	s_waitcnt lgkmcnt(0)
	v_cvt_pk_bf16_f32 v13, v14, v15
	v_ashrrev_i32_e32 v14, 31, v16
	v_mul_lo_u32 v18, s8, v14
	v_mul_lo_u32 v19, s9, v16
	v_mad_u64_u32 v[16:17], s[10:11], s8, v16, 0
	v_add3_u32 v17, v17, v18, v19
	v_lshl_add_u64 v[16:17], v[16:17], 1, v[32:33]
	ds_read2_b32 v[14:15], v226 offset0:16 offset1:49
	global_store_dwordx4 v[16:17], v[10:13], off sc1
	s_waitcnt lgkmcnt(0)
	s_nop 0
	v_cvt_pk_bf16_f32 v10, v14, v15
	ds_read2_b32 v[12:13], v226 offset0:82 offset1:115
	s_waitcnt lgkmcnt(0)
	v_cvt_pk_bf16_f32 v11, v12, v13
	ds_read2_b32 v[12:13], v226 offset0:148 offset1:181
	s_waitcnt lgkmcnt(0)
	v_cvt_pk_bf16_f32 v12, v12, v13
	ds_read2_b32 v[14:15], v226 offset0:214 offset1:247
	s_waitcnt lgkmcnt(0)
	v_cvt_pk_bf16_f32 v13, v14, v15
	v_add_u32_e32 v14, s2, v245
	v_ashrrev_i32_e32 v15, 31, v14
	v_mul_lo_u32 v16, s8, v15
	v_mul_lo_u32 v17, s9, v14
	v_mad_u64_u32 v[14:15], s[8:9], s8, v14, 0
	s_add_i32 s2, s55, 1
	v_add3_u32 v15, v15, v16, v17
	s_cmp_lt_u32 s55, 3
	v_lshl_add_u64 v[14:15], v[14:15], 1, v[32:33]
	s_cselect_b64 s[8:9], -1, 0
	s_add_i32 s20, s20, 1
	global_store_dwordx4 v[14:15], v[10:13], off sc1
	s_cmpk_lt_u32 s20, 0x3140
	s_waitcnt lgkmcnt(0)
	s_cselect_b64 s[10:11], -1, 0
	s_and_b64 s[8:9], s[8:9], s[10:11]
	s_andn2_b64 vcc, exec, s[8:9]
	s_mov_b32 s55, s2
	s_cbranch_vccnz .LBB0_689

; #define LAS __attribute__((address_space(3)))
; __device__ __forceinline__ unsigned cvt_pk_bf16(float lo, float hi) { unsigned r; asm volatile("v_cvt_pk_bf16_f32 %0, %1, %2" : "=v"(r) : "v"(lo), "v"(hi)); return r; }
; __device__ __forceinline__ float bflo(unsigned w) { return __uint_as_float(w << 16); }
; __device__ __forceinline__ float bfhi(unsigned w) { return __uint_as_float(w & 0xffff0000u); }
; template <int PASS> __device__ __forceinline__ void lru_wave_item(LAS unsigned char* lds, LAS unsigned char* vw, int b, int c, int h, const MixP& p, int lane, float (&Hrun)[8], bool cont) {
;     ...
;         {
;             const int sb = s0 + 4 * fq - 3;
; #pragma unroll
;             for (int r = 0; r < 7; ++r) ur[r] = *(const u32x4*)(ub + (size_t)max(sb + r, 0) * P1W);
;         }
;         if (s0 == 0 && fq == 0) {
; #pragma unroll
;             for (int r = 0; r < 3; ++r) ur[r] = (u32x4){0u, 0u, 0u, 0u};
;         }
; #pragma unroll
;         for (int jj = 0; jj < 4; ++jj) {
;             f32x2 o[4] = {bv[0], bv[1], bv[2], bv[3]};
; #pragma unroll
;             for (int k = 0; k < 4; ++k) { const u32x4 uk = ur[jj + k];
;                 o[0] = wv[k][0] * (f32x2){bflo(uk.x), bfhi(uk.x)} + o[0]; o[1] = wv[k][1] * (f32x2){bflo(uk.y), bfhi(uk.y)} + o[1];
;                 o[2] = wv[k][2] * (f32x2){bflo(uk.z), bfhi(uk.z)} + o[2]; o[3] = wv[k][3] * (f32x2){bflo(uk.w), bfhi(uk.w)} + o[3]; }
;             { u32x4 w; w.x = cvt_pk_bf16(o[0].x, o[0].y); w.y = cvt_pk_bf16(o[1].x, o[1].y); w.z = cvt_pk_bf16(o[2].x, o[2].y); w.w = cvt_pk_bf16(o[3].x, o[3].y);
;               *(LAS u32x4*)(vw + (4 * fq + jj) * WROW + cg * 16) = w; }
;         }
.LBB0_818:
	s_or_b32 s22, s19, s11
	v_add_u32_e32 v0, s22, v224
	v_max_i32_e32 v2, 0, v0
	v_mad_u64_u32 v[2:3], s[20:21], v2, s82, v[182:183]
	global_load_dwordx4 v[74:77], v[2:3], off offset:1024
	v_max_i32_e32 v2, -1, v0
	v_add_u32_e32 v2, 1, v2
	v_mad_u64_u32 v[2:3], s[20:21], v2, s82, v[182:183]
	global_load_dwordx4 v[78:81], v[2:3], off offset:1024
	v_or_b32_e32 v2, 2, v0
	v_max_i32_e32 v2, 0, v2
	v_mad_u64_u32 v[2:3], s[20:21], v2, s82, v[182:183]
	global_load_dwordx4 v[82:85], v[2:3], off offset:1024
	v_or_b32_e32 v2, s22, v223
	v_max_i32_e32 v2, 0, v2
	v_mad_u64_u32 v[2:3], s[20:21], v2, s82, v[182:183]
	global_load_dwordx4 v[70:73], v[2:3], off offset:1024
	v_max_i32_e32 v2, -4, v0
	v_add_u32_e32 v2, 4, v2
	v_mad_u64_u32 v[2:3], s[20:21], v2, s82, v[182:183]
	global_load_dwordx4 v[66:69], v[2:3], off offset:1024
	v_max_i32_e32 v2, -5, v0
	v_add_u32_e32 v2, 5, v2
	v_mad_u64_u32 v[2:3], s[20:21], v2, s82, v[182:183]
	global_load_dwordx4 v[6:9], v[2:3], off offset:1024
	v_max_i32_e32 v0, -6, v0
	v_add_u32_e32 v0, 6, v0
	v_mad_u64_u32 v[2:3], s[20:21], v0, s82, v[182:183]
	global_load_dwordx4 v[2:5], v[2:3], off offset:1024
	s_cmp_eq_u32 s22, 0
	s_cselect_b64 s[20:21], -1, 0
	s_and_b64 s[20:21], s[20:21], s[4:5]
	s_or_b32 s19, s19, s18
	s_and_b64 vcc, exec, s[12:13]
	s_mov_b64 s[12:13], 0
	s_waitcnt vmcnt(6)
	v_cndmask_b32_e64 v0, v77, 0, s[20:21]
	v_cndmask_b32_e64 v77, v75, 0, s[20:21]
	v_cndmask_b32_e64 v75, v74, 0, s[20:21]
	v_cndmask_b32_e64 v86, v76, 0, s[20:21]
	v_lshlrev_b32_e32 v74, 16, v75
	s_waitcnt vmcnt(5)
	v_cndmask_b32_e64 v89, v79, 0, s[20:21]
	v_cndmask_b32_e64 v91, v78, 0, s[20:21]
	v_and_b32_e32 v75, 0xffff0000, v75
	v_lshlrev_b32_e32 v76, 16, v77
	v_and_b32_e32 v77, 0xffff0000, v77
	v_cndmask_b32_e64 v88, v81, 0, s[20:21]
	v_cndmask_b32_e64 v87, v80, 0, s[20:21]
	s_waitcnt vmcnt(4)
	v_cndmask_b32_e64 v102, v83, 0, s[20:21]
	v_cndmask_b32_e64 v98, v82, 0, s[20:21]
	s_waitcnt lgkmcnt(13)
	v_pk_fma_f32 v[74:75], v[26:27], v[74:75], v[58:59]
	v_pk_fma_f32 v[76:77], v[28:29], v[76:77], v[60:61]
	v_lshlrev_b32_e32 v78, 16, v86
	v_and_b32_e32 v79, 0xffff0000, v86
	v_lshlrev_b32_e32 v80, 16, v0
	v_and_b32_e32 v81, 0xffff0000, v0
	v_lshlrev_b32_e32 v90, 16, v91
	v_and_b32_e32 v91, 0xffff0000, v91
	v_lshlrev_b32_e32 v92, 16, v89
	v_and_b32_e32 v93, 0xffff0000, v89
	v_cndmask_b32_e64 v100, v85, 0, s[20:21]
	v_cndmask_b32_e64 v101, v84, 0, s[20:21]
	s_waitcnt lgkmcnt(12)
	v_pk_fma_f32 v[78:79], v[30:31], v[78:79], v[62:63]
	v_pk_fma_f32 v[80:81], v[32:33], v[80:81], v[64:65]
	v_pk_fma_f32 v[82:83], v[34:35], v[90:91], v[74:75]
	v_pk_fma_f32 v[84:85], v[36:37], v[92:93], v[76:77]
	v_lshlrev_b32_e32 v94, 16, v87
	v_and_b32_e32 v95, 0xffff0000, v87
	v_lshlrev_b32_e32 v96, 16, v88
	v_and_b32_e32 v97, 0xffff0000, v88
	v_lshlrev_b32_e32 v74, 16, v98
	v_and_b32_e32 v75, 0xffff0000, v98
	v_lshlrev_b32_e32 v76, 16, v102
	v_and_b32_e32 v77, 0xffff0000, v102
	v_pk_fma_f32 v[86:87], v[38:39], v[94:95], v[78:79]
	v_pk_fma_f32 v[88:89], v[40:41], v[96:97], v[80:81]
	v_pk_fma_f32 v[98:99], v[42:43], v[74:75], v[82:83]
	v_pk_fma_f32 v[84:85], v[44:45], v[76:77], v[84:85]
	v_lshlrev_b32_e32 v78, 16, v101
	v_and_b32_e32 v79, 0xffff0000, v101
	v_lshlrev_b32_e32 v80, 16, v100
	v_and_b32_e32 v81, 0xffff0000, v100
	s_waitcnt vmcnt(3)
	v_lshlrev_b32_e32 v82, 16, v70
	v_and_b32_e32 v83, 0xffff0000, v70
	v_lshlrev_b32_e32 v70, 16, v71
	v_and_b32_e32 v71, 0xffff0000, v71
	v_pk_fma_f32 v[86:87], v[46:47], v[78:79], v[86:87]
	v_pk_fma_f32 v[88:89], v[48:49], v[80:81], v[88:89]
	v_pk_fma_f32 v[100:101], v[52:53], v[70:71], v[84:85]
	v_lshlrev_b32_e32 v84, 16, v72
	v_and_b32_e32 v85, 0xffff0000, v72
	v_lshlrev_b32_e32 v72, 16, v73
	v_and_b32_e32 v73, 0xffff0000, v73
	v_pk_fma_f32 v[98:99], v[50:51], v[82:83], v[98:99]
	v_pk_fma_f32 v[102:103], v[54:55], v[84:85], v[86:87]
	v_pk_fma_f32 v[104:105], v[56:57], v[72:73], v[88:89]
	v_cvt_pk_bf16_f32 v86, v98, v99
	v_cvt_pk_bf16_f32 v87, v100, v101
	v_cvt_pk_bf16_f32 v88, v102, v103
	s_waitcnt vmcnt(2)
	v_lshlrev_b32_e32 v98, 16, v68
	v_cvt_pk_bf16_f32 v89, v104, v105
	ds_write_b128 v229, v[86:89]
	v_pk_fma_f32 v[86:87], v[26:27], v[90:91], v[58:59]
	v_pk_fma_f32 v[88:89], v[28:29], v[92:93], v[60:61]
	v_pk_fma_f32 v[90:91], v[30:31], v[94:95], v[62:63]
	v_pk_fma_f32 v[92:93], v[32:33], v[96:97], v[64:65]
	v_pk_fma_f32 v[86:87], v[34:35], v[74:75], v[86:87]
	v_pk_fma_f32 v[88:89], v[36:37], v[76:77], v[88:89]
	v_pk_fma_f32 v[90:91], v[38:39], v[78:79], v[90:91]
	v_pk_fma_f32 v[92:93], v[40:41], v[80:81], v[92:93]
	v_pk_fma_f32 v[86:87], v[42:43], v[82:83], v[86:87]
	v_pk_fma_f32 v[88:89], v[44:45], v[70:71], v[88:89]
	v_pk_fma_f32 v[90:91], v[46:47], v[84:85], v[90:91]
	v_pk_fma_f32 v[92:93], v[48:49], v[72:73], v[92:93]
	v_lshlrev_b32_e32 v94, 16, v66
	v_and_b32_e32 v95, 0xffff0000, v66
	v_lshlrev_b32_e32 v96, 16, v67
	v_and_b32_e32 v97, 0xffff0000, v67
	v_and_b32_e32 v99, 0xffff0000, v68
	v_lshlrev_b32_e32 v100, 16, v69
	v_and_b32_e32 v101, 0xffff0000, v69
	v_pk_fma_f32 v[86:87], v[50:51], v[94:95], v[86:87]
	v_pk_fma_f32 v[88:89], v[52:53], v[96:97], v[88:89]
	v_pk_fma_f32 v[90:91], v[54:55], v[98:99], v[90:91]
	v_pk_fma_f32 v[92:93], v[56:57], v[100:101], v[92:93]
	v_cvt_pk_bf16_f32 v66, v86, v87
	v_cvt_pk_bf16_f32 v67, v88, v89
	v_cvt_pk_bf16_f32 v68, v90, v91
	s_waitcnt vmcnt(1)
; #define LAS __attribute__((address_space(3)))
; __device__ __forceinline__ unsigned cvt_pk_bf16(float lo, float hi) { unsigned r; asm volatile("v_cvt_pk_bf16_f32 %0, %1, %2" : "=v"(r) : "v"(lo), "v"(hi)); return r; }
; __device__ __forceinline__ float bflo(unsigned w) { return __uint_as_float(w << 16); }
; __device__ __forceinline__ float bfhi(unsigned w) { return __uint_as_float(w & 0xffff0000u); }
; template <int PASS> __device__ __forceinline__ void lru_wave_item(LAS unsigned char* lds, LAS unsigned char* vw, int b, int c, int h, const MixP& p, int lane, float (&Hrun)[8], bool cont) {
;     ...
;             for (int k = 0; k < 4; ++k) { const u32x4 uk = ur[jj + k];
;                 o[0] = wv[k][0] * (f32x2){bflo(uk.x), bfhi(uk.x)} + o[0]; o[1] = wv[k][1] * (f32x2){bflo(uk.y), bfhi(uk.y)} + o[1];
;                 o[2] = wv[k][2] * (f32x2){bflo(uk.z), bfhi(uk.z)} + o[2]; o[3] = wv[k][3] * (f32x2){bflo(uk.w), bfhi(uk.w)} + o[3]; }
;             { u32x4 w; w.x = cvt_pk_bf16(o[0].x, o[0].y); w.y = cvt_pk_bf16(o[1].x, o[1].y); w.z = cvt_pk_bf16(o[2].x, o[2].y); w.w = cvt_pk_bf16(o[3].x, o[3].y);
;               *(LAS u32x4*)(vw + (4 * fq + jj) * WROW + cg * 16) = w; }
;         }
;         f32x4 aR[8], aI[8];
;         bf16x8 af[4];
;         {
; #pragma unroll
;             for (int kk = 0; kk < 4; ++kk) af[kk] = *(const LAS bf16x8*)(vw + fr * WROW + kk * 64 + fq * 16);
; #pragma unroll
;             for (int n = 0; n < 8; ++n) {
;                 aR[n] = (f32x4){0.f, 0.f, 0.f, 0.f}; aI[n] = (f32x4){0.f, 0.f, 0.f, 0.f};
; #pragma unroll
;                 for (int kk = 0; kk < 4; ++kk) {
;                     const bf16x8 ba = *(const LAS bf16x8*)(lds + WA_OFF + (16 * n + fr) * WROW + kk * 64 + fq * 16);
;                     const bf16x8 bx = *(const LAS bf16x8*)(lds + WX_OFF + (16 * n + fr) * WROW + kk * 64 + fq * 16);
;                     aR[n] = __builtin_amdgcn_mfma_f32_16x16x32_bf16(af[kk], ba, aR[n], 0, 0, 0);
;                     aI[n] = __builtin_amdgcn_mfma_f32_16x16x32_bf16(af[kk], bx, aI[n], 0, 0, 0);
;                 }
;             }
;     ...
;                 const float r = fsig2(aR[n][j] + pba[n]), ig = fsig2(aI[n][j] + pbx[n]);
;                 const float a = __builtin_amdgcn_exp2f(r * pk8[n]), mult = __builtin_amdgcn_sqrtf(fmaxf(1.0f - a * a, 0.f));
	v_lshlrev_b32_e32 v86, 16, v8
	v_cvt_pk_bf16_f32 v69, v92, v93
	ds_write_b128 v229, v[66:69] offset:272
	v_pk_fma_f32 v[66:67], v[26:27], v[74:75], v[58:59]
	v_pk_fma_f32 v[68:69], v[28:29], v[76:77], v[60:61]
	v_pk_fma_f32 v[74:75], v[30:31], v[78:79], v[62:63]
	v_pk_fma_f32 v[76:77], v[32:33], v[80:81], v[64:65]
	v_pk_fma_f32 v[66:67], v[34:35], v[82:83], v[66:67]
	v_pk_fma_f32 v[68:69], v[36:37], v[70:71], v[68:69]
	v_pk_fma_f32 v[74:75], v[38:39], v[84:85], v[74:75]
	v_pk_fma_f32 v[76:77], v[40:41], v[72:73], v[76:77]
	v_pk_fma_f32 v[66:67], v[42:43], v[94:95], v[66:67]
	v_pk_fma_f32 v[68:69], v[44:45], v[96:97], v[68:69]
	v_pk_fma_f32 v[74:75], v[46:47], v[98:99], v[74:75]
	v_pk_fma_f32 v[76:77], v[48:49], v[100:101], v[76:77]
	v_lshlrev_b32_e32 v78, 16, v6
	v_and_b32_e32 v79, 0xffff0000, v6
	v_lshlrev_b32_e32 v80, 16, v7
	v_and_b32_e32 v81, 0xffff0000, v7
	v_and_b32_e32 v87, 0xffff0000, v8
	v_lshlrev_b32_e32 v88, 16, v9
	v_and_b32_e32 v89, 0xffff0000, v9
	v_pk_fma_f32 v[66:67], v[50:51], v[78:79], v[66:67]
	v_pk_fma_f32 v[68:69], v[52:53], v[80:81], v[68:69]
	v_pk_fma_f32 v[74:75], v[54:55], v[86:87], v[74:75]
	v_pk_fma_f32 v[76:77], v[56:57], v[88:89], v[76:77]
	v_cvt_pk_bf16_f32 v6, v66, v67
	v_cvt_pk_bf16_f32 v7, v68, v69
	v_cvt_pk_bf16_f32 v8, v74, v75
	v_pk_fma_f32 v[66:67], v[30:31], v[84:85], v[62:63]
	v_cvt_pk_bf16_f32 v9, v76, v77
	ds_write_b128 v229, v[6:9] offset:544
	v_pk_fma_f32 v[6:7], v[26:27], v[82:83], v[58:59]
	v_pk_fma_f32 v[8:9], v[28:29], v[70:71], v[60:61]
	v_pk_fma_f32 v[68:69], v[32:33], v[72:73], v[64:65]
	v_pk_fma_f32 v[6:7], v[34:35], v[94:95], v[6:7]
	v_pk_fma_f32 v[8:9], v[36:37], v[96:97], v[8:9]
	v_pk_fma_f32 v[66:67], v[38:39], v[98:99], v[66:67]
	v_pk_fma_f32 v[68:69], v[40:41], v[100:101], v[68:69]
	v_pk_fma_f32 v[6:7], v[42:43], v[78:79], v[6:7]
	v_pk_fma_f32 v[8:9], v[44:45], v[80:81], v[8:9]
	v_pk_fma_f32 v[70:71], v[46:47], v[86:87], v[66:67]
	v_pk_fma_f32 v[66:67], v[48:49], v[88:89], v[68:69]
	s_waitcnt vmcnt(0)
	v_lshlrev_b32_e32 v68, 16, v2
	v_and_b32_e32 v69, 0xffff0000, v2
	v_lshlrev_b32_e32 v2, 16, v3
	v_and_b32_e32 v3, 0xffff0000, v3
	v_pk_fma_f32 v[6:7], v[50:51], v[68:69], v[6:7]
	v_pk_fma_f32 v[2:3], v[52:53], v[2:3], v[8:9]
	v_lshlrev_b32_e32 v8, 16, v4
	v_and_b32_e32 v9, 0xffff0000, v4
	v_lshlrev_b32_e32 v4, 16, v5
	v_and_b32_e32 v5, 0xffff0000, v5
	v_pk_fma_f32 v[8:9], v[54:55], v[8:9], v[70:71]
	v_pk_fma_f32 v[66:67], v[56:57], v[4:5], v[66:67]
	v_cvt_pk_bf16_f32 v4, v6, v7
	v_cvt_pk_bf16_f32 v5, v2, v3
	v_cvt_pk_bf16_f32 v6, v8, v9
	v_and_or_b32 v0, v213, 64, v202
	v_cvt_pk_bf16_f32 v7, v66, v67
	ds_write_b128 v229, v[4:7] offset:816
	ds_read_b128 v[118:121], v230
	ds_read_b128 v[90:93], v230 offset:64
	ds_read_b128 v[6:9], v230 offset:128
	ds_read_b128 v[2:5], v230 offset:192
	ds_read_b128 v[66:69], v231
	ds_read_b128 v[70:73], v231 offset:34816
	ds_read_b128 v[74:77], v231 offset:64
	ds_read_b128 v[78:81], v231 offset:34880
	s_waitcnt lgkmcnt(3)
	v_mfma_f32_16x16x32_bf16 v[66:69], v[118:121], v[66:69], 0
	v_lshlrev_b32_e32 v0, 2, v0
	s_waitcnt lgkmcnt(2)
	v_mfma_f32_16x16x32_bf16 v[70:73], v[118:121], v[70:73], 0
	s_waitcnt lgkmcnt(1)
	v_mfma_f32_16x16x32_bf16 v[66:69], v[90:93], v[74:77], v[66:69]
	s_waitcnt lgkmcnt(0)
	v_mfma_f32_16x16x32_bf16 v[70:73], v[90:93], v[78:81], v[70:73]
	ds_read_b128 v[74:77], v231 offset:128
	ds_read_b128 v[78:81], v231 offset:34944
	s_waitcnt lgkmcnt(1)
	v_mfma_f32_16x16x32_bf16 v[66:69], v[6:9], v[74:77], v[66:69]
	s_waitcnt lgkmcnt(0)
	v_mfma_f32_16x16x32_bf16 v[70:73], v[6:9], v[78:81], v[70:73]
	ds_read_b128 v[74:77], v231 offset:192
	ds_read_b128 v[78:81], v231 offset:35008
	s_waitcnt lgkmcnt(1)
	v_mfma_f32_16x16x32_bf16 v[134:137], v[2:5], v[74:77], v[66:69]
	s_waitcnt lgkmcnt(0)
	v_mfma_f32_16x16x32_bf16 v[130:133], v[2:5], v[78:81], v[70:73]
	s_nop 0
	ds_read_b128 v[66:69], v231 offset:4352
	s_nop 0
	ds_read_b128 v[70:73], v231 offset:39168
	ds_read_b128 v[74:77], v231 offset:4416
	ds_read_b128 v[78:81], v231 offset:39232
	v_add_f32_e32 v134, v158, v134
	s_waitcnt lgkmcnt(3)
	v_mfma_f32_16x16x32_bf16 v[66:69], v[118:121], v[66:69], 0
	v_add_f32_e32 v135, v158, v135
	v_mul_f32_e32 v134, 0xbfb8aa3b, v134
	v_mul_f32_e32 v135, 0xbfb8aa3b, v135
	s_waitcnt lgkmcnt(2)
	v_mfma_f32_16x16x32_bf16 v[70:73], v[118:121], v[70:73], 0
	v_exp_f32_e32 v134, v134
	v_exp_f32_e32 v135, v135
	v_add_f32_e32 v130, v160, v130
	s_waitcnt lgkmcnt(1)
	v_mfma_f32_16x16x32_bf16 v[66:69], v[90:93], v[74:77], v[66:69]
	v_add_f32_e32 v134, 1.0, v134
	v_add_f32_e32 v135, 1.0, v135
	v_rcp_f32_e32 v134, v134
	s_waitcnt lgkmcnt(0)
	v_mfma_f32_16x16x32_bf16 v[70:73], v[90:93], v[78:81], v[70:73]
	ds_read_b128 v[74:77], v231 offset:4480
	ds_read_b128 v[78:81], v231 offset:39296
	v_rcp_f32_e32 v135, v135
	v_mul_f32_e32 v134, v162, v134
	s_waitcnt lgkmcnt(1)
	v_mfma_f32_16x16x32_bf16 v[66:69], v[6:9], v[74:77], v[66:69]
	v_add_f32_e32 v131, v160, v131
	v_mul_f32_e32 v135, v162, v135
	v_mul_f32_e32 v130, 0xbfb8aa3b, v130
	s_waitcnt lgkmcnt(0)
	v_mfma_f32_16x16x32_bf16 v[70:73], v[6:9], v[78:81], v[70:73]
	ds_read_b128 v[74:77], v231 offset:4544
	ds_read_b128 v[78:81], v231 offset:39360
	v_exp_f32_e32 v236, v134
	v_mul_f32_e32 v131, 0xbfb8aa3b, v131
	s_waitcnt lgkmcnt(1)
	v_mfma_f32_16x16x32_bf16 v[126:129], v[2:5], v[74:77], v[66:69]
	v_exp_f32_e32 v130, v130
	v_exp_f32_e32 v131, v131
	v_fma_f32 v134, -v236, v236, 1.0
	s_waitcnt lgkmcnt(0)
	v_mfma_f32_16x16x32_bf16 v[122:125], v[2:5], v[78:81], v[70:73]
	ds_read_b128 v[66:69], v231 offset:8704
	s_nop 1
	ds_read_b128 v[70:73], v231 offset:43520
	ds_read_b128 v[74:77], v231 offset:8768
	ds_read_b128 v[78:81], v231 offset:43584
	v_add_f32_e32 v130, 1.0, v130
	s_waitcnt lgkmcnt(3)
; #define LAS __attribute__((address_space(3)))
; __device__ __forceinline__ float fsig2(float x) { return __builtin_amdgcn_rcpf(1.0f + __builtin_amdgcn_exp2f(-LOG2E * x)); }
; template <int PASS> __device__ __forceinline__ void lru_wave_item(LAS unsigned char* lds, LAS unsigned char* vw, int b, int c, int h, const MixP& p, int lane, float (&Hrun)[8], bool cont) {
;     ...
;             for (int n = 0; n < 8; ++n) {
;                 aR[n] = (f32x4){0.f, 0.f, 0.f, 0.f}; aI[n] = (f32x4){0.f, 0.f, 0.f, 0.f};
; #pragma unroll
;                 for (int kk = 0; kk < 4; ++kk) {
;                     const bf16x8 ba = *(const LAS bf16x8*)(lds + WA_OFF + (16 * n + fr) * WROW + kk * 64 + fq * 16);
;                     const bf16x8 bx = *(const LAS bf16x8*)(lds + WX_OFF + (16 * n + fr) * WROW + kk * 64 + fq * 16);
;                     aR[n] = __builtin_amdgcn_mfma_f32_16x16x32_bf16(af[kk], ba, aR[n], 0, 0, 0);
;                     aI[n] = __builtin_amdgcn_mfma_f32_16x16x32_bf16(af[kk], bx, aI[n], 0, 0, 0);
;                 }
;             }
;         }
; #pragma unroll
;         for (int n = 0; n < 8; ++n) {
;             const f32x4 aVn = __builtin_amdgcn_mfma_f32_16x16x32_bf16(af[n >> 1], idf[n & 1], (f32x4){0.f, 0.f, 0.f, 0.f}, 0, 0, 0);
;             float av[4], bxv[4];
; #pragma unroll
;             for (int j = 0; j < 4; ++j) {
;                 const float r = fsig2(aR[n][j] + pba[n]), ig = fsig2(aI[n][j] + pbx[n]);
;                 const float a = __builtin_amdgcn_exp2f(r * pk8[n]), mult = __builtin_amdgcn_sqrtf(fmaxf(1.0f - a * a, 0.f));
	v_mfma_f32_16x16x32_bf16 v[66:69], v[118:121], v[66:69], 0
	v_max_f32_e32 v134, 0, v134
	v_add_f32_e32 v131, 1.0, v131
	v_rcp_f32_e32 v130, v130
	s_waitcnt lgkmcnt(2)
	v_mfma_f32_16x16x32_bf16 v[70:73], v[118:121], v[70:73], 0
	v_sqrt_f32_e32 v134, v134
	v_rcp_f32_e32 v131, v131
	v_add_f32_e32 v133, v160, v133
	s_waitcnt lgkmcnt(1)
	v_mfma_f32_16x16x32_bf16 v[66:69], v[90:93], v[74:77], v[66:69]
	v_mul_f32_e32 v133, 0xbfb8aa3b, v133
	v_exp_f32_e32 v133, v133
	v_add_f32_e32 v132, v160, v132
	s_waitcnt lgkmcnt(0)
	v_mfma_f32_16x16x32_bf16 v[70:73], v[90:93], v[78:81], v[70:73]
	ds_read_b128 v[74:77], v231 offset:8832
	ds_read_b128 v[78:81], v231 offset:43648
	v_mul_f32_e32 v132, 0xbfb8aa3b, v132
	v_exp_f32_e32 v132, v132
	s_waitcnt lgkmcnt(1)
	v_mfma_f32_16x16x32_bf16 v[66:69], v[6:9], v[74:77], v[66:69]
	v_add_f32_e32 v133, 1.0, v133
	v_add_f32_e32 v132, 1.0, v132
	v_rcp_f32_e32 v132, v132
	s_waitcnt lgkmcnt(0)
	v_mfma_f32_16x16x32_bf16 v[70:73], v[6:9], v[78:81], v[70:73]
	ds_read_b128 v[74:77], v231 offset:8896
	ds_read_b128 v[78:81], v231 offset:43712
	s_waitcnt lgkmcnt(1)
	v_mfma_f32_16x16x32_bf16 v[114:117], v[2:5], v[74:77], v[66:69]
	s_waitcnt lgkmcnt(0)
	v_mfma_f32_16x16x32_bf16 v[110:113], v[2:5], v[78:81], v[70:73]
	s_nop 0
	ds_read_b128 v[66:69], v232
	s_nop 0
	ds_read_b128 v[70:73], v232 offset:34816
	ds_read_b128 v[74:77], v232 offset:64
	ds_read_b128 v[78:81], v232 offset:34880
	s_waitcnt lgkmcnt(3)
	v_mfma_f32_16x16x32_bf16 v[66:69], v[118:121], v[66:69], 0
	s_waitcnt lgkmcnt(2)
	v_mfma_f32_16x16x32_bf16 v[70:73], v[118:121], v[70:73], 0
	s_waitcnt lgkmcnt(1)
	v_mfma_f32_16x16x32_bf16 v[66:69], v[90:93], v[74:77], v[66:69]
	s_waitcnt lgkmcnt(0)
	v_mfma_f32_16x16x32_bf16 v[70:73], v[90:93], v[78:81], v[70:73]
	ds_read_b128 v[74:77], v232 offset:128
	ds_read_b128 v[78:81], v232 offset:34944
	s_waitcnt lgkmcnt(1)
	v_mfma_f32_16x16x32_bf16 v[66:69], v[6:9], v[74:77], v[66:69]
	s_waitcnt lgkmcnt(0)
	v_mfma_f32_16x16x32_bf16 v[70:73], v[6:9], v[78:81], v[70:73]
	ds_read_b128 v[74:77], v232 offset:192
	ds_read_b128 v[78:81], v232 offset:35008
	s_waitcnt lgkmcnt(1)
	v_mfma_f32_16x16x32_bf16 v[106:109], v[2:5], v[74:77], v[66:69]
	s_waitcnt lgkmcnt(0)
	v_mfma_f32_16x16x32_bf16 v[102:105], v[2:5], v[78:81], v[70:73]
	s_nop 0
	ds_read_b128 v[66:69], v231 offset:17408
	s_nop 0
	ds_read_b128 v[70:73], v231 offset:52224
	ds_read_b128 v[74:77], v231 offset:17472
	ds_read_b128 v[78:81], v231 offset:52288
	s_waitcnt lgkmcnt(3)
	v_mfma_f32_16x16x32_bf16 v[66:69], v[118:121], v[66:69], 0
	s_waitcnt lgkmcnt(2)
	v_mfma_f32_16x16x32_bf16 v[70:73], v[118:121], v[70:73], 0
	s_waitcnt lgkmcnt(1)
	v_mfma_f32_16x16x32_bf16 v[66:69], v[90:93], v[74:77], v[66:69]
	s_waitcnt lgkmcnt(0)
	v_mfma_f32_16x16x32_bf16 v[70:73], v[90:93], v[78:81], v[70:73]
	ds_read_b128 v[74:77], v231 offset:17536
	ds_read_b128 v[78:81], v231 offset:52352
	s_waitcnt lgkmcnt(1)
	v_mfma_f32_16x16x32_bf16 v[66:69], v[6:9], v[74:77], v[66:69]
	s_waitcnt lgkmcnt(0)
	v_mfma_f32_16x16x32_bf16 v[70:73], v[6:9], v[78:81], v[70:73]
	ds_read_b128 v[74:77], v231 offset:17600
	ds_read_b128 v[78:81], v231 offset:52416
	s_waitcnt lgkmcnt(1)
	v_mfma_f32_16x16x32_bf16 v[98:101], v[2:5], v[74:77], v[66:69]
	s_waitcnt lgkmcnt(0)
	v_mfma_f32_16x16x32_bf16 v[94:97], v[2:5], v[78:81], v[70:73]
	s_nop 0
	ds_read_b128 v[66:69], v231 offset:21760
	s_nop 0
	ds_read_b128 v[70:73], v231 offset:56576
	ds_read_b128 v[74:77], v231 offset:21824
	ds_read_b128 v[78:81], v231 offset:56640
	s_waitcnt lgkmcnt(3)
	v_mfma_f32_16x16x32_bf16 v[66:69], v[118:121], v[66:69], 0
	s_waitcnt lgkmcnt(2)
	v_mfma_f32_16x16x32_bf16 v[70:73], v[118:121], v[70:73], 0
	s_waitcnt lgkmcnt(1)
	v_mfma_f32_16x16x32_bf16 v[66:69], v[90:93], v[74:77], v[66:69]
	s_waitcnt lgkmcnt(0)
	v_mfma_f32_16x16x32_bf16 v[70:73], v[90:93], v[78:81], v[70:73]
	ds_read_b128 v[74:77], v231 offset:21888
	ds_read_b128 v[78:81], v231 offset:56704
	s_waitcnt lgkmcnt(1)
	v_mfma_f32_16x16x32_bf16 v[66:69], v[6:9], v[74:77], v[66:69]
	s_waitcnt lgkmcnt(0)
	v_mfma_f32_16x16x32_bf16 v[70:73], v[6:9], v[78:81], v[70:73]
	ds_read_b128 v[74:77], v231 offset:21952
	ds_read_b128 v[78:81], v231 offset:56768
	s_waitcnt lgkmcnt(1)
	v_mfma_f32_16x16x32_bf16 v[86:89], v[2:5], v[74:77], v[66:69]
	s_waitcnt lgkmcnt(0)
	v_mfma_f32_16x16x32_bf16 v[82:85], v[2:5], v[78:81], v[70:73]
	s_nop 0
	ds_read_b128 v[66:69], v231 offset:26112
	s_nop 0
	ds_read_b128 v[70:73], v231 offset:60928
	ds_read_b128 v[74:77], v231 offset:26176
	ds_read_b128 v[78:81], v231 offset:60992
	v_add_f32_e32 v86, v171, v86
	s_waitcnt lgkmcnt(3)
	v_mfma_f32_16x16x32_bf16 v[66:69], v[118:121], v[66:69], 0
	v_add_f32_e32 v87, v171, v87
	v_mul_f32_e32 v86, 0xbfb8aa3b, v86
	v_mul_f32_e32 v87, 0xbfb8aa3b, v87
	s_waitcnt lgkmcnt(2)
	v_mfma_f32_16x16x32_bf16 v[70:73], v[118:121], v[70:73], 0
	v_exp_f32_e32 v86, v86
	v_exp_f32_e32 v87, v87
	v_add_f32_e32 v82, v173, v82
	s_waitcnt lgkmcnt(1)
	v_mfma_f32_16x16x32_bf16 v[66:69], v[90:93], v[74:77], v[66:69]
	v_add_f32_e32 v86, 1.0, v86
	v_add_f32_e32 v87, 1.0, v87
	v_rcp_f32_e32 v86, v86
	s_waitcnt lgkmcnt(0)
	v_mfma_f32_16x16x32_bf16 v[70:73], v[90:93], v[78:81], v[70:73]
	ds_read_b128 v[74:77], v231 offset:26240
	ds_read_b128 v[78:81], v231 offset:61056
	v_rcp_f32_e32 v87, v87
	v_mul_f32_e32 v86, v175, v86
	s_waitcnt lgkmcnt(1)
	v_mfma_f32_16x16x32_bf16 v[66:69], v[6:9], v[74:77], v[66:69]
	ds_read_b128 v[74:77], v231 offset:26304
	ds_read_b128 v[138:141], v231 offset:61120
	v_add_f32_e32 v83, v173, v83
	v_mul_f32_e32 v87, v175, v87
	s_waitcnt lgkmcnt(2)
	v_mfma_f32_16x16x32_bf16 v[70:73], v[6:9], v[78:81], v[70:73]
	v_mul_f32_e32 v82, 0xbfb8aa3b, v82
	v_mul_f32_e32 v83, 0xbfb8aa3b, v83
	v_exp_f32_e32 v82, v82
	s_waitcnt lgkmcnt(1)
; __device__ __forceinline__ float fsig2(float x) { return __builtin_amdgcn_rcpf(1.0f + __builtin_amdgcn_exp2f(-LOG2E * x)); }
; template <int PASS> __device__ __forceinline__ void lru_wave_item(LAS unsigned char* lds, LAS unsigned char* vw, int b, int c, int h, const MixP& p, int lane, float (&Hrun)[8], bool cont) {
;     ...
;         for (int n = 0; n < 8; ++n) {
;             const f32x4 aVn = __builtin_amdgcn_mfma_f32_16x16x32_bf16(af[n >> 1], idf[n & 1], (f32x4){0.f, 0.f, 0.f, 0.f}, 0, 0, 0);
;             float av[4], bxv[4];
; #pragma unroll
;             for (int j = 0; j < 4; ++j) {
;                 const float r = fsig2(aR[n][j] + pba[n]), ig = fsig2(aI[n][j] + pbx[n]);
;                 const float a = __builtin_amdgcn_exp2f(r * pk8[n]), mult = __builtin_amdgcn_sqrtf(fmaxf(1.0f - a * a, 0.f));
;                 av[j] = a; bxv[j] = mult * ig * aVn[j];
;             }
;             const float H0 = bxv[0], H1 = av[1] * H0 + bxv[1], H2 = av[2] * H1 + bxv[2], H3 = av[3] * H2 + bxv[3];
;             const float A0 = av[0], A1 = av[1] * A0, A2 = av[2] * A1, A3 = av[3] * A2;
;             float At[4], Ht[4];
; #pragma unroll
;             for (int q = 0; q < 4; ++q) { At[q] = __shfl(A3, fr + 16 * q); Ht[q] = __shfl(H3, fr + 16 * q); }
;             const float c0 = Hrun[n], c1 = At[0] * c0 + Ht[0], c2 = At[1] * c1 + Ht[1], c3 = At[2] * c2 + Ht[2], c4 = At[3] * c3 + Ht[3];
;             Hrun[n] = c4;
;             if (PASS == 1) Arun[n] *= (At[0] * At[1]) * (At[2] * At[3]);
	v_mfma_f32_16x16x32_bf16 v[78:81], v[2:5], v[74:77], v[66:69]
	v_exp_f32_e32 v83, v83
	v_add_f32_e32 v85, v173, v85
	v_add_f32_e32 v82, 1.0, v82
	s_waitcnt lgkmcnt(0)
	v_mfma_f32_16x16x32_bf16 v[74:77], v[2:5], v[138:141], v[70:73]
	ds_read_b128 v[66:69], v233
	s_nop 1
	ds_read_b128 v[70:73], v233 offset:34816
	ds_read_b128 v[138:141], v233 offset:64
	ds_read_b128 v[184:187], v233 offset:34880
	v_add_f32_e32 v83, 1.0, v83
	s_waitcnt lgkmcnt(3)
	v_mfma_f32_16x16x32_bf16 v[66:69], v[118:121], v[66:69], 0
	v_rcp_f32_e32 v82, v82
	v_rcp_f32_e32 v83, v83
	v_mul_f32_e32 v85, 0xbfb8aa3b, v85
	s_waitcnt lgkmcnt(2)
	v_mfma_f32_16x16x32_bf16 v[70:73], v[118:121], v[70:73], 0
	v_exp_f32_e32 v85, v85
	s_nop 0
	v_add_f32_e32 v85, 1.0, v85
	s_waitcnt lgkmcnt(1)
	v_mfma_f32_16x16x32_bf16 v[66:69], v[90:93], v[138:141], v[66:69]
	s_waitcnt lgkmcnt(0)
	v_mfma_f32_16x16x32_bf16 v[70:73], v[90:93], v[184:187], v[70:73]
	ds_read_b128 v[138:141], v233 offset:128
	ds_read_b128 v[184:187], v233 offset:34944
	s_waitcnt lgkmcnt(1)
	v_mfma_f32_16x16x32_bf16 v[66:69], v[6:9], v[138:141], v[66:69]
	s_waitcnt lgkmcnt(0)
	v_mfma_f32_16x16x32_bf16 v[138:141], v[6:9], v[184:187], v[70:73]
	s_nop 2
	ds_read_b128 v[70:73], v233 offset:192
	ds_read_b128 v[184:187], v233 offset:35008
	s_waitcnt lgkmcnt(1)
	v_mfma_f32_16x16x32_bf16 v[70:73], v[2:5], v[70:73], v[66:69]
	s_waitcnt lgkmcnt(0)
	v_mfma_f32_16x16x32_bf16 v[66:69], v[2:5], v[184:187], v[138:141]
	v_exp_f32_e32 v186, v135
	s_nop 0
	v_fma_f32 v135, -v186, v186, 1.0
	v_max_f32_e32 v135, 0, v135
	v_sqrt_f32_e32 v135, v135
	v_mfma_f32_16x16x32_bf16 v[138:141], v[118:121], v[18:21], 0
	s_nop 1
	v_add_f32_e32 v66, v179, v66
	v_add_f32_e32 v67, v179, v67
	v_pk_mul_f32 v[130:131], v[130:131], v[134:135]
	v_add_f32_e32 v134, v158, v136
	v_mul_f32_e32 v134, 0xbfb8aa3b, v134
	v_exp_f32_e32 v134, v134
	v_pk_mul_f32 v[130:131], v[130:131], v[138:139]
	v_rcp_f32_e32 v136, v133
	v_mul_f32_e32 v66, 0xbfb8aa3b, v66
	v_add_f32_e32 v134, 1.0, v134
	v_rcp_f32_e32 v134, v134
	v_mul_f32_e32 v67, 0xbfb8aa3b, v67
	v_exp_f32_e32 v66, v66
	v_exp_f32_e32 v67, v67
	v_mul_f32_e32 v134, v162, v134
	v_exp_f32_e32 v139, v134
	v_add_f32_e32 v134, v158, v137
	v_mul_f32_e32 v134, 0xbfb8aa3b, v134
	v_exp_f32_e32 v134, v134
	v_add_f32_e32 v66, 1.0, v66
	v_add_f32_e32 v67, 1.0, v67
	v_rcp_f32_e32 v66, v66
	v_add_f32_e32 v134, 1.0, v134
	v_rcp_f32_e32 v134, v134
	v_rcp_f32_e32 v67, v67
	v_add_f32_e32 v69, v179, v69
	v_mul_f32_e32 v69, 0xbfb8aa3b, v69
	v_mul_f32_e32 v133, v162, v134
	v_exp_f32_e32 v185, v133
	v_fma_f32 v133, v186, v130, v131
	v_fma_f32 v131, -v139, v139, 1.0
	v_max_f32_e32 v131, 0, v131
	v_sqrt_f32_e32 v138, v131
	v_fma_f32 v131, -v185, v185, 1.0
	v_max_f32_e32 v131, 0, v131
	v_sqrt_f32_e32 v184, v131
	v_pk_mul_f32 v[134:135], v[132:133], v[138:139]
	v_mul_f32_e32 v131, v186, v236
	v_fmac_f32_e32 v135, v134, v140
	v_mov_b32_e32 v137, v135
	v_pk_mul_f32 v[136:137], v[136:137], v[184:185]
	v_mul_f32_e32 v132, v139, v131
	v_fmac_f32_e32 v137, v136, v141
	v_mfma_f32_16x16x32_bf16 v[138:141], v[118:121], v[22:25], 0
	v_add_f32_e32 v118, v159, v126
	v_mul_f32_e32 v118, 0xbfb8aa3b, v118
	v_exp_f32_e32 v118, v118
	v_mul_f32_e32 v134, v185, v132
	ds_bpermute_b32 v188, v0, v134
	ds_bpermute_b32 v192, v0, v137
	v_add_f32_e32 v118, 1.0, v118
	v_rcp_f32_e32 v119, v118
	v_add_f32_e32 v118, v161, v122
	v_mul_f32_e32 v118, 0xbfb8aa3b, v118
	v_exp_f32_e32 v118, v118
	v_mul_f32_e32 v119, v163, v119
	v_exp_f32_e32 v136, v119
	v_add_f32_e32 v122, v161, v125
	v_add_f32_e32 v118, 1.0, v118
	v_rcp_f32_e32 v118, v118
	v_fma_f32 v119, -v136, v136, 1.0
	v_max_f32_e32 v119, 0, v119
	v_sqrt_f32_e32 v120, v119
	v_add_f32_e32 v119, v159, v127
	v_mul_f32_e32 v119, 0xbfb8aa3b, v119
	v_exp_f32_e32 v119, v119
	v_mul_f32_e32 v122, 0xbfb8aa3b, v122
	v_exp_f32_e32 v122, v122
	ds_bpermute_b32 v190, v0, v134 offset:64
	v_add_f32_e32 v119, 1.0, v119
	v_rcp_f32_e32 v121, v119
	v_add_f32_e32 v119, v161, v123
	v_mul_f32_e32 v119, 0xbfb8aa3b, v119
	v_exp_f32_e32 v119, v119
	v_mul_f32_e32 v121, v163, v121
	v_exp_f32_e32 v185, v121
	v_add_f32_e32 v122, 1.0, v122
	v_add_f32_e32 v119, 1.0, v119
	v_rcp_f32_e32 v119, v119
	v_fma_f32 v121, -v185, v185, 1.0
	v_max_f32_e32 v121, 0, v121
	v_sqrt_f32_e32 v121, v121
	ds_bpermute_b32 v196, v0, v137 offset:64
	ds_bpermute_b32 v194, v0, v134 offset:128
	ds_bpermute_b32 v198, v0, v137 offset:128
	v_pk_mul_f32 v[118:119], v[118:119], v[120:121]
	v_add_f32_e32 v120, v159, v128
	v_mul_f32_e32 v120, 0xbfb8aa3b, v120
	v_exp_f32_e32 v120, v120
	v_pk_mul_f32 v[118:119], v[118:119], v[138:139]
	ds_bpermute_b32 v186, v0, v137 offset:192
	v_exp_f32_e32 v69, v69
	v_add_f32_e32 v120, 1.0, v120
	v_rcp_f32_e32 v121, v120
	v_add_f32_e32 v120, v161, v124
	v_mul_f32_e32 v120, 0xbfb8aa3b, v120
	v_exp_f32_e32 v120, v120
	v_mul_f32_e32 v121, v163, v121
	v_exp_f32_e32 v127, v121
	v_add_f32_e32 v121, v159, v129
	v_mul_f32_e32 v121, 0xbfb8aa3b, v121
	v_exp_f32_e32 v121, v121
	v_add_f32_e32 v120, 1.0, v120
	v_rcp_f32_e32 v120, v120
	v_rcp_f32_e32 v124, v122
	v_add_f32_e32 v121, 1.0, v121
	v_rcp_f32_e32 v121, v121
	v_add_f32_e32 v69, 1.0, v69
	ds_bpermute_b32 v184, v0, v134 offset:192
	v_mul_f32_e32 v121, v163, v121
	v_exp_f32_e32 v129, v121
	v_fma_f32 v121, v185, v118, v119
	v_fma_f32 v119, -v127, v127, 1.0
	v_max_f32_e32 v119, 0, v119
	v_sqrt_f32_e32 v126, v119
	v_fma_f32 v119, -v129, v129, 1.0
	v_max_f32_e32 v119, 0, v119
	v_sqrt_f32_e32 v128, v119
	v_pk_mul_f32 v[122:123], v[120:121], v[126:127]
	v_mul_f32_e32 v119, v185, v136
	v_fmac_f32_e32 v123, v122, v140
	v_mov_b32_e32 v125, v123
	v_pk_mul_f32 v[124:125], v[124:125], v[128:129]
	v_mul_f32_e32 v120, v127, v119
	v_fmac_f32_e32 v125, v124, v141
	v_mul_f32_e32 v122, v129, v120
	ds_bpermute_b32 v189, v0, v122
	ds_bpermute_b32 v193, v0, v125
	ds_bpermute_b32 v191, v0, v122 offset:64
	ds_bpermute_b32 v197, v0, v125 offset:64
	ds_bpermute_b32 v195, v0, v122 offset:128
	ds_bpermute_b32 v199, v0, v125 offset:128
	s_waitcnt lgkmcnt(4)
; template <int PASS> __device__ __forceinline__ void lru_wave_item(LAS unsigned char* lds, LAS unsigned char* vw, int b, int c, int h, const MixP& p, int lane, float (&Hrun)[8], bool cont) {
;     ...
;             for (int q = 0; q < 4; ++q) { At[q] = __shfl(A3, fr + 16 * q); Ht[q] = __shfl(H3, fr + 16 * q); }
;             const float c0 = Hrun[n], c1 = At[0] * c0 + Ht[0], c2 = At[1] * c1 + Ht[1], c3 = At[2] * c2 + Ht[2], c4 = At[3] * c3 + Ht[3];
;             Hrun[n] = c4;
;             if (PASS == 1) Arun[n] *= (At[0] * At[1]) * (At[2] * At[3]);
;             if (PASS == 2) {
;                 const float cin = fq == 0 ? c0 : (fq == 1 ? c1 : (fq == 2 ? c2 : c3));
;                 aR[n][0] = H0 + A0 * cin; aR[n][1] = H1 + A1 * cin; aR[n][2] = H2 + A2 * cin; aR[n][3] = H3 + A3 * cin;
;             }
	v_pk_fma_f32 v[128:129], v[10:11], v[188:189], v[192:193]
	ds_bpermute_b32 v187, v0, v125 offset:192
	s_waitcnt lgkmcnt(3)
	v_pk_fma_f32 v[138:139], v[128:129], v[190:191], v[196:197]
	ds_bpermute_b32 v185, v0, v122 offset:192
	s_waitcnt lgkmcnt(2)
	v_pk_fma_f32 v[126:127], v[138:139], v[194:195], v[198:199]
	s_nop 0
	v_cndmask_b32_e64 v124, v126, v138, s[8:9]
	v_cndmask_b32_e64 v124, v124, v128, s[6:7]
	v_cndmask_b32_e64 v10, v124, v10, s[4:5]
	v_fmac_f32_e32 v130, v236, v10
	v_fmac_f32_e32 v133, v131, v10
	v_fmac_f32_e32 v135, v132, v10
	v_fmac_f32_e32 v137, v134, v10
	v_cndmask_b32_e64 v10, v127, v139, s[8:9]
	v_cndmask_b32_e64 v10, v10, v129, s[6:7]
	v_cndmask_b32_e64 v10, v10, v11, s[4:5]
	v_fmac_f32_e32 v118, v136, v10
	v_fmac_f32_e32 v121, v119, v10
	v_fmac_f32_e32 v123, v120, v10
	v_fmac_f32_e32 v125, v122, v10
	v_add_f32_e32 v10, v164, v114
	v_mul_f32_e32 v10, 0xbfb8aa3b, v10
	v_exp_f32_e32 v10, v10
	v_mfma_f32_16x16x32_bf16 v[138:141], v[90:93], v[18:21], 0
	v_add_f32_e32 v10, 1.0, v10
	v_rcp_f32_e32 v11, v10
	v_add_f32_e32 v10, v166, v110
	v_mul_f32_e32 v10, 0xbfb8aa3b, v10
	v_exp_f32_e32 v10, v10
	v_mul_f32_e32 v11, v168, v11
	v_exp_f32_e32 v119, v11
	v_add_f32_e32 v10, 1.0, v10
	v_rcp_f32_e32 v10, v10
	v_fma_f32 v11, -v119, v119, 1.0
	v_max_f32_e32 v11, 0, v11
	v_sqrt_f32_e32 v110, v11
	v_add_f32_e32 v11, v164, v115
	v_mul_f32_e32 v11, 0xbfb8aa3b, v11
	v_exp_f32_e32 v11, v11
	s_nop 0
	v_add_f32_e32 v11, 1.0, v11
	v_rcp_f32_e32 v114, v11
	v_add_f32_e32 v11, v166, v111
	v_mul_f32_e32 v11, 0xbfb8aa3b, v11
	v_exp_f32_e32 v11, v11
	v_mul_f32_e32 v111, v168, v114
	v_exp_f32_e32 v120, v111
	v_add_f32_e32 v11, 1.0, v11
	v_rcp_f32_e32 v11, v11
	v_fma_f32 v111, -v120, v120, 1.0
	v_max_f32_e32 v111, 0, v111
	v_sqrt_f32_e32 v111, v111
	s_nop 0
	v_pk_mul_f32 v[10:11], v[10:11], v[110:111]
	v_add_f32_e32 v110, v164, v116
	v_mul_f32_e32 v110, 0xbfb8aa3b, v110
	v_exp_f32_e32 v110, v110
	v_pk_mul_f32 v[10:11], v[10:11], v[138:139]
	v_add_f32_e32 v110, 1.0, v110
	v_rcp_f32_e32 v111, v110
	v_add_f32_e32 v110, v166, v112
	v_mul_f32_e32 v110, 0xbfb8aa3b, v110
	v_exp_f32_e32 v110, v110
	v_mul_f32_e32 v111, v168, v111
	v_exp_f32_e32 v129, v111
	v_add_f32_e32 v111, v164, v117
	v_mul_f32_e32 v111, 0xbfb8aa3b, v111
	v_exp_f32_e32 v111, v111
	v_add_f32_e32 v112, v166, v113
	v_mul_f32_e32 v112, 0xbfb8aa3b, v112
	v_exp_f32_e32 v112, v112
	v_add_f32_e32 v111, 1.0, v111
	v_rcp_f32_e32 v111, v111
	v_add_f32_e32 v110, 1.0, v110
	v_rcp_f32_e32 v110, v110
	v_add_f32_e32 v112, 1.0, v112
	v_mul_f32_e32 v111, v168, v111
	v_exp_f32_e32 v117, v111
	v_fma_f32 v111, v120, v10, v11
	v_fma_f32 v11, -v129, v129, 1.0
	v_max_f32_e32 v11, 0, v11
	v_sqrt_f32_e32 v128, v11
	v_fma_f32 v11, -v117, v117, 1.0
	v_max_f32_e32 v11, 0, v11
	v_rcp_f32_e32 v114, v112
	v_sqrt_f32_e32 v116, v11
	v_pk_mul_f32 v[112:113], v[110:111], v[128:129]
	v_mul_f32_e32 v11, v120, v119
	v_fmac_f32_e32 v113, v112, v140
	v_mov_b32_e32 v115, v113
	v_pk_mul_f32 v[114:115], v[114:115], v[116:117]
	v_mul_f32_e32 v110, v129, v11
	v_fmac_f32_e32 v115, v114, v141
	v_mfma_f32_16x16x32_bf16 v[138:141], v[90:93], v[22:25], 0
	v_add_f32_e32 v90, v165, v106
	v_mul_f32_e32 v90, 0xbfb8aa3b, v90
	v_exp_f32_e32 v90, v90
	v_mul_f32_e32 v112, v117, v110
	ds_bpermute_b32 v188, v0, v112
	ds_bpermute_b32 v190, v0, v115
	v_add_f32_e32 v90, 1.0, v90
	v_rcp_f32_e32 v91, v90
	v_add_f32_e32 v90, v167, v102
	v_mul_f32_e32 v90, 0xbfb8aa3b, v90
	v_exp_f32_e32 v90, v90
	v_mul_f32_e32 v91, v169, v91
	v_exp_f32_e32 v114, v91
	v_add_f32_e32 v102, v167, v105
	v_add_f32_e32 v90, 1.0, v90
	v_rcp_f32_e32 v90, v90
	v_fma_f32 v91, -v114, v114, 1.0
	v_max_f32_e32 v91, 0, v91
	v_sqrt_f32_e32 v92, v91
	v_add_f32_e32 v91, v165, v107
	v_mul_f32_e32 v91, 0xbfb8aa3b, v91
	v_exp_f32_e32 v91, v91
	v_mul_f32_e32 v102, 0xbfb8aa3b, v102
	v_exp_f32_e32 v102, v102
	ds_bpermute_b32 v192, v0, v112 offset:64
	v_add_f32_e32 v91, 1.0, v91
	v_rcp_f32_e32 v93, v91
	v_add_f32_e32 v91, v167, v103
	v_mul_f32_e32 v91, 0xbfb8aa3b, v91
	v_exp_f32_e32 v91, v91
	v_mul_f32_e32 v93, v169, v93
	v_exp_f32_e32 v117, v93
	v_add_f32_e32 v102, 1.0, v102
	v_add_f32_e32 v91, 1.0, v91
	v_rcp_f32_e32 v91, v91
	v_fma_f32 v93, -v117, v117, 1.0
	v_max_f32_e32 v93, 0, v93
	v_sqrt_f32_e32 v93, v93
	ds_bpermute_b32 v194, v0, v115 offset:64
	ds_bpermute_b32 v196, v0, v112 offset:128
	ds_bpermute_b32 v198, v0, v115 offset:128
	v_pk_mul_f32 v[90:91], v[90:91], v[92:93]
	v_add_f32_e32 v92, v165, v108
	v_mul_f32_e32 v92, 0xbfb8aa3b, v92
	v_exp_f32_e32 v92, v92
	v_pk_mul_f32 v[90:91], v[90:91], v[138:139]
	ds_bpermute_b32 v128, v0, v115 offset:192
	ds_bpermute_b32 v116, v0, v112 offset:192
	v_add_f32_e32 v92, 1.0, v92
	v_rcp_f32_e32 v93, v92
	v_add_f32_e32 v92, v167, v104
	v_mul_f32_e32 v92, 0xbfb8aa3b, v92
	v_exp_f32_e32 v92, v92
	v_mul_f32_e32 v93, v169, v93
	v_exp_f32_e32 v107, v93
	v_add_f32_e32 v93, v165, v109
	v_mul_f32_e32 v93, 0xbfb8aa3b, v93
	v_exp_f32_e32 v93, v93
	v_add_f32_e32 v92, 1.0, v92
	v_rcp_f32_e32 v92, v92
	v_rcp_f32_e32 v104, v102
	v_add_f32_e32 v93, 1.0, v93
	v_rcp_f32_e32 v93, v93
	s_nop 0
	v_mul_f32_e32 v93, v169, v93
	v_exp_f32_e32 v109, v93
	v_fma_f32 v93, v117, v90, v91
	v_fma_f32 v91, -v107, v107, 1.0
	v_max_f32_e32 v91, 0, v91
	v_sqrt_f32_e32 v106, v91
	v_fma_f32 v91, -v109, v109, 1.0
	v_max_f32_e32 v91, 0, v91
	v_sqrt_f32_e32 v108, v91
	v_pk_mul_f32 v[102:103], v[92:93], v[106:107]
	v_mul_f32_e32 v91, v117, v114
	v_fmac_f32_e32 v103, v102, v140
	v_mov_b32_e32 v105, v103
	v_pk_mul_f32 v[104:105], v[104:105], v[108:109]
	v_mul_f32_e32 v92, v107, v91
	v_fmac_f32_e32 v105, v104, v141
	v_mul_f32_e32 v102, v109, v92
	ds_bpermute_b32 v189, v0, v102
	ds_bpermute_b32 v191, v0, v105
	ds_bpermute_b32 v193, v0, v102 offset:64
	ds_bpermute_b32 v195, v0, v105 offset:64
	ds_bpermute_b32 v197, v0, v102 offset:128
	ds_bpermute_b32 v199, v0, v105 offset:128
	s_waitcnt lgkmcnt(4)
; __device__ __forceinline__ float fsig2(float x) { return __builtin_amdgcn_rcpf(1.0f + __builtin_amdgcn_exp2f(-LOG2E * x)); }
; template <int PASS> __device__ __forceinline__ void lru_wave_item(LAS unsigned char* lds, LAS unsigned char* vw, int b, int c, int h, const MixP& p, int lane, float (&Hrun)[8], bool cont) {
;     ...
;         for (int n = 0; n < 8; ++n) {
;             const f32x4 aVn = __builtin_amdgcn_mfma_f32_16x16x32_bf16(af[n >> 1], idf[n & 1], (f32x4){0.f, 0.f, 0.f, 0.f}, 0, 0, 0);
;             float av[4], bxv[4];
; #pragma unroll
;             for (int j = 0; j < 4; ++j) {
;                 const float r = fsig2(aR[n][j] + pba[n]), ig = fsig2(aI[n][j] + pbx[n]);
;                 const float a = __builtin_amdgcn_exp2f(r * pk8[n]), mult = __builtin_amdgcn_sqrtf(fmaxf(1.0f - a * a, 0.f));
;                 av[j] = a; bxv[j] = mult * ig * aVn[j];
;             }
;             const float H0 = bxv[0], H1 = av[1] * H0 + bxv[1], H2 = av[2] * H1 + bxv[2], H3 = av[3] * H2 + bxv[3];
;             const float A0 = av[0], A1 = av[1] * A0, A2 = av[2] * A1, A3 = av[3] * A2;
;             float At[4], Ht[4];
; #pragma unroll
;             for (int q = 0; q < 4; ++q) { At[q] = __shfl(A3, fr + 16 * q); Ht[q] = __shfl(H3, fr + 16 * q); }
;             const float c0 = Hrun[n], c1 = At[0] * c0 + Ht[0], c2 = At[1] * c1 + Ht[1], c3 = At[2] * c2 + Ht[2], c4 = At[3] * c3 + Ht[3];
;             Hrun[n] = c4;
;             if (PASS == 1) Arun[n] *= (At[0] * At[1]) * (At[2] * At[3]);
;             if (PASS == 2) {
;                 const float cin = fq == 0 ? c0 : (fq == 1 ? c1 : (fq == 2 ? c2 : c3));
;                 aR[n][0] = H0 + A0 * cin; aR[n][1] = H1 + A1 * cin; aR[n][2] = H2 + A2 * cin; aR[n][3] = H3 + A3 * cin;
;             }
	v_pk_fma_f32 v[108:109], v[12:13], v[188:189], v[190:191]
	ds_bpermute_b32 v129, v0, v105 offset:192
	s_waitcnt lgkmcnt(3)
	v_pk_fma_f32 v[138:139], v[108:109], v[192:193], v[194:195]
	ds_bpermute_b32 v117, v0, v102 offset:192
	s_waitcnt lgkmcnt(2)
	v_pk_fma_f32 v[106:107], v[138:139], v[196:197], v[198:199]
	s_nop 0
	v_cndmask_b32_e64 v104, v106, v138, s[8:9]
	v_cndmask_b32_e64 v104, v104, v108, s[6:7]
	v_cndmask_b32_e64 v12, v104, v12, s[4:5]
	v_fmac_f32_e32 v111, v11, v12
	v_cndmask_b32_e64 v11, v107, v139, s[8:9]
	v_cndmask_b32_e64 v11, v11, v109, s[6:7]
	v_cndmask_b32_e64 v11, v11, v13, s[4:5]
	v_fmac_f32_e32 v90, v114, v11
	v_fmac_f32_e32 v93, v91, v11
	v_fmac_f32_e32 v103, v92, v11
	v_fmac_f32_e32 v105, v102, v11
	v_add_f32_e32 v11, v170, v98
	v_mul_f32_e32 v11, 0xbfb8aa3b, v11
	v_exp_f32_e32 v11, v11
	v_fmac_f32_e32 v10, v119, v12
	v_fmac_f32_e32 v113, v110, v12
	v_fmac_f32_e32 v115, v112, v12
	v_add_f32_e32 v11, 1.0, v11
	v_rcp_f32_e32 v11, v11
	v_add_f32_e32 v12, v172, v94
	v_mul_f32_e32 v12, 0xbfb8aa3b, v12
	v_exp_f32_e32 v12, v12
	v_mul_f32_e32 v11, v174, v11
	v_exp_f32_e32 v11, v11
	v_mfma_f32_16x16x32_bf16 v[138:141], v[6:9], v[18:21], 0
	v_add_f32_e32 v12, 1.0, v12
	v_rcp_f32_e32 v12, v12
	v_fma_f32 v13, -v11, v11, 1.0
	v_max_f32_e32 v13, 0, v13
	v_sqrt_f32_e32 v94, v13
	v_add_f32_e32 v13, v170, v99
	v_mul_f32_e32 v13, 0xbfb8aa3b, v13
	v_exp_f32_e32 v13, v13
	v_mfma_f32_16x16x32_bf16 v[6:9], v[6:9], v[22:25], 0
	v_add_f32_e32 v13, 1.0, v13
	v_rcp_f32_e32 v91, v13
	v_add_f32_e32 v13, v172, v95
	v_mul_f32_e32 v13, 0xbfb8aa3b, v13
	v_exp_f32_e32 v13, v13
	v_mul_f32_e32 v91, v174, v91
	v_exp_f32_e32 v91, v91
	v_add_f32_e32 v13, 1.0, v13
	v_rcp_f32_e32 v13, v13
	v_fma_f32 v92, -v91, v91, 1.0
	v_max_f32_e32 v92, 0, v92
	v_sqrt_f32_e32 v95, v92
	v_add_f32_e32 v92, v170, v100
	v_mul_f32_e32 v92, 0xbfb8aa3b, v92
	v_exp_f32_e32 v92, v92
	v_pk_mul_f32 v[12:13], v[12:13], v[94:95]
	v_add_f32_e32 v95, v172, v97
	v_mul_f32_e32 v95, 0xbfb8aa3b, v95
	v_add_f32_e32 v92, 1.0, v92
	v_rcp_f32_e32 v92, v92
	v_add_f32_e32 v94, v172, v96
	v_exp_f32_e32 v95, v95
	v_mul_f32_e32 v94, 0xbfb8aa3b, v94
	v_mul_f32_e32 v92, v174, v92
	v_exp_f32_e32 v109, v92
	v_exp_f32_e32 v94, v94
	v_pk_mul_f32 v[12:13], v[12:13], v[138:139]
	v_add_f32_e32 v95, 1.0, v95
	v_rcp_f32_e32 v98, v95
	v_fma_f32 v95, v91, v12, v13
	v_fma_f32 v13, -v109, v109, 1.0
	v_add_f32_e32 v94, 1.0, v94
	v_max_f32_e32 v13, 0, v13
	v_rcp_f32_e32 v94, v94
	v_sqrt_f32_e32 v108, v13
	v_add_f32_e32 v92, v170, v101
	v_mul_f32_e32 v92, 0xbfb8aa3b, v92
	v_exp_f32_e32 v92, v92
	v_pk_mul_f32 v[96:97], v[94:95], v[108:109]
	v_exp_f32_e32 v94, v86
	v_fmac_f32_e32 v97, v96, v140
	v_exp_f32_e32 v96, v87
	v_add_f32_e32 v92, 1.0, v92
	v_fma_f32 v86, -v94, v94, 1.0
	v_max_f32_e32 v86, 0, v86
	v_fma_f32 v87, -v96, v96, 1.0
	v_max_f32_e32 v87, 0, v87
	v_sqrt_f32_e32 v86, v86
	v_sqrt_f32_e32 v87, v87
	v_rcp_f32_e32 v92, v92
	v_mov_b32_e32 v99, v97
	v_pk_mul_f32 v[82:83], v[82:83], v[86:87]
	s_nop 0
	v_pk_mul_f32 v[82:83], v[82:83], v[6:7]
	v_add_f32_e32 v6, v171, v88
	v_mul_f32_e32 v6, 0xbfb8aa3b, v6
	v_exp_f32_e32 v6, v6
	v_add_f32_e32 v7, v173, v84
	v_mul_f32_e32 v7, 0xbfb8aa3b, v7
	v_exp_f32_e32 v7, v7
	v_add_f32_e32 v6, 1.0, v6
	v_rcp_f32_e32 v6, v6
	v_mul_f32_e32 v92, v174, v92
	v_add_f32_e32 v7, 1.0, v7
	v_rcp_f32_e32 v84, v7
	v_mul_f32_e32 v6, v175, v6
	v_exp_f32_e32 v7, v6
	v_add_f32_e32 v6, v171, v89
	v_mul_f32_e32 v6, 0xbfb8aa3b, v6
	v_exp_f32_e32 v6, v6
	v_exp_f32_e32 v101, v92
	v_rcp_f32_e32 v88, v85
	v_fma_f32 v85, v96, v82, v83
	v_add_f32_e32 v6, 1.0, v6
	v_rcp_f32_e32 v6, v6
	v_fma_f32 v13, -v101, v101, 1.0
	v_max_f32_e32 v13, 0, v13
	v_sqrt_f32_e32 v100, v13
	v_mul_f32_e32 v6, v175, v6
	v_exp_f32_e32 v197, v6
	v_fma_f32 v6, -v7, v7, 1.0
	v_max_f32_e32 v6, 0, v6
	v_sqrt_f32_e32 v6, v6
	v_mul_f32_e32 v13, v91, v11
	v_mul_f32_e32 v83, v96, v94
	v_pk_mul_f32 v[98:99], v[98:99], v[100:101]
	v_pk_mul_f32 v[86:87], v[84:85], v[6:7]
	v_fma_f32 v6, -v197, v197, 1.0
	v_max_f32_e32 v6, 0, v6
	v_sqrt_f32_e32 v196, v6
	v_fmac_f32_e32 v87, v86, v8
	v_mov_b32_e32 v89, v87
	v_mul_f32_e32 v91, v109, v13
	v_pk_mul_f32 v[88:89], v[88:89], v[196:197]
	v_mul_f32_e32 v84, v7, v83
	v_fmac_f32_e32 v99, v98, v141
	v_mul_f32_e32 v92, v101, v91
	v_fmac_f32_e32 v89, v88, v9
	v_mul_f32_e32 v86, v197, v84
	ds_bpermute_b32 v138, v0, v92
	ds_bpermute_b32 v140, v0, v99
	ds_bpermute_b32 v139, v0, v86
	ds_bpermute_b32 v141, v0, v89
	ds_bpermute_b32 v188, v0, v92 offset:64
	ds_bpermute_b32 v190, v0, v99 offset:64
	ds_bpermute_b32 v189, v0, v86 offset:64
	ds_bpermute_b32 v191, v0, v89 offset:64
	ds_bpermute_b32 v192, v0, v92 offset:128
	ds_bpermute_b32 v194, v0, v99 offset:128
	ds_bpermute_b32 v193, v0, v86 offset:128
	ds_bpermute_b32 v195, v0, v89 offset:128
	s_waitcnt lgkmcnt(8)
	v_pk_fma_f32 v[8:9], v[14:15], v[138:139], v[140:141]
	ds_bpermute_b32 v108, v0, v99 offset:192
	s_waitcnt lgkmcnt(5)
	v_pk_fma_f32 v[138:139], v[8:9], v[188:189], v[190:191]
	ds_bpermute_b32 v109, v0, v89 offset:192
	s_waitcnt lgkmcnt(2)
	v_pk_fma_f32 v[6:7], v[138:139], v[192:193], v[194:195]
	ds_bpermute_b32 v100, v0, v92 offset:192
	v_cndmask_b32_e64 v88, v6, v138, s[8:9]
	v_cndmask_b32_e64 v8, v88, v8, s[6:7]
	v_cndmask_b32_e64 v8, v8, v14, s[4:5]
	v_fmac_f32_e32 v12, v11, v8
	v_fmac_f32_e32 v95, v13, v8
	v_fmac_f32_e32 v97, v91, v8
	v_fmac_f32_e32 v99, v92, v8
	v_cndmask_b32_e64 v8, v7, v139, s[8:9]
	v_cndmask_b32_e64 v8, v8, v9, s[6:7]
	v_cndmask_b32_e64 v8, v8, v15, s[4:5]
	v_fmac_f32_e32 v82, v94, v8
	v_fmac_f32_e32 v85, v83, v8
	v_fmac_f32_e32 v87, v84, v8
	v_fmac_f32_e32 v89, v86, v8
	v_add_f32_e32 v8, v176, v78
	v_mul_f32_e32 v8, 0xbfb8aa3b, v8
	v_exp_f32_e32 v8, v8
	v_mfma_f32_16x16x32_bf16 v[138:141], v[2:5], v[18:21], 0
	ds_bpermute_b32 v101, v0, v86 offset:192
	v_add_f32_e32 v8, 1.0, v8
	v_rcp_f32_e32 v9, v8
	v_add_f32_e32 v8, v178, v74
	v_mul_f32_e32 v8, 0xbfb8aa3b, v8
	v_exp_f32_e32 v8, v8
	v_mul_f32_e32 v9, v180, v9
	v_exp_f32_e32 v11, v9
	v_mfma_f32_16x16x32_bf16 v[2:5], v[2:5], v[22:25], 0
	v_add_f32_e32 v8, 1.0, v8
	v_rcp_f32_e32 v8, v8
	v_fma_f32 v9, -v11, v11, 1.0
	v_max_f32_e32 v9, 0, v9
	v_sqrt_f32_e32 v14, v9
	v_add_f32_e32 v9, v176, v79
	v_mul_f32_e32 v9, 0xbfb8aa3b, v9
	v_exp_f32_e32 v9, v9
	s_waitcnt lgkmcnt(0)
; #define LAS __attribute__((address_space(3)))
; template <int PASS> __device__ __forceinline__ void lru_wave_item(LAS unsigned char* lds, LAS unsigned char* vw, int b, int c, int h, const MixP& p, int lane, float (&Hrun)[8], bool cont) {
;     ...
;         for (int n = 0; n < 8; ++n) {
;             const f32x4 aVn = __builtin_amdgcn_mfma_f32_16x16x32_bf16(af[n >> 1], idf[n & 1], (f32x4){0.f, 0.f, 0.f, 0.f}, 0, 0, 0);
;             float av[4], bxv[4];
; #pragma unroll
;             for (int j = 0; j < 4; ++j) {
;                 const float r = fsig2(aR[n][j] + pba[n]), ig = fsig2(aI[n][j] + pbx[n]);
;                 const float a = __builtin_amdgcn_exp2f(r * pk8[n]), mult = __builtin_amdgcn_sqrtf(fmaxf(1.0f - a * a, 0.f));
;                 av[j] = a; bxv[j] = mult * ig * aVn[j];
;             }
;             const float H0 = bxv[0], H1 = av[1] * H0 + bxv[1], H2 = av[2] * H1 + bxv[2], H3 = av[3] * H2 + bxv[3];
;             const float A0 = av[0], A1 = av[1] * A0, A2 = av[2] * A1, A3 = av[3] * A2;
;             float At[4], Ht[4];
; #pragma unroll
;             for (int q = 0; q < 4; ++q) { At[q] = __shfl(A3, fr + 16 * q); Ht[q] = __shfl(H3, fr + 16 * q); }
;             const float c0 = Hrun[n], c1 = At[0] * c0 + Ht[0], c2 = At[1] * c1 + Ht[1], c3 = At[2] * c2 + Ht[2], c4 = At[3] * c3 + Ht[3];
;             Hrun[n] = c4;
;             if (PASS == 1) Arun[n] *= (At[0] * At[1]) * (At[2] * At[3]);
;             if (PASS == 2) {
;                 const float cin = fq == 0 ? c0 : (fq == 1 ? c1 : (fq == 2 ? c2 : c3));
;                 aR[n][0] = H0 + A0 * cin; aR[n][1] = H1 + A1 * cin; aR[n][2] = H2 + A2 * cin; aR[n][3] = H3 + A3 * cin;
;             }
;         }
;         if (PASS == 2) {
; #pragma unroll
;             for (int n = 0; n < 8; ++n)
; #pragma unroll
;                 for (int j = 0; j < 4; j += 2) { const unsigned w = cvt_pk_bf16(aR[n][j], aR[n][j + 1]);
;                     *(LAS unsigned short*)(vw + (4 * fq + j) * WROW + (16 * n + fr) * 2) = (unsigned short)(w & 0xffffu);
;                     *(LAS unsigned short*)(vw + (4 * fq + j + 1) * WROW + (16 * n + fr) * 2) = (unsigned short)(w >> 16); }
; #pragma unroll
;             for (int i = 0; i < 4; ++i) {
;                 const int t = fq + 4 * i; const size_t row = (size_t)(row0 + 16 * st + t);
;                 const u32x4 hh = *(const LAS u32x4*)(vw + t * WROW + cg * 16);
	v_pk_fma_f32 v[6:7], v[6:7], v[100:101], v[108:109]
	v_add_f32_e32 v9, 1.0, v9
	v_rcp_f32_e32 v13, v9
	v_add_f32_e32 v9, v178, v75
	v_mul_f32_e32 v9, 0xbfb8aa3b, v9
	v_exp_f32_e32 v9, v9
	v_mul_f32_e32 v13, v180, v13
	v_exp_f32_e32 v13, v13
	v_add_f32_e32 v75, v178, v77
	v_add_f32_e32 v9, 1.0, v9
	v_rcp_f32_e32 v9, v9
	v_fma_f32 v15, -v13, v13, 1.0
	v_max_f32_e32 v15, 0, v15
	v_sqrt_f32_e32 v15, v15
	v_mul_f32_e32 v75, 0xbfb8aa3b, v75
	v_exp_f32_e32 v75, v75
	v_pk_mul_f32 v[8:9], v[8:9], v[14:15]
	s_nop 0
	v_pk_mul_f32 v[14:15], v[8:9], v[138:139]
	v_add_f32_e32 v8, v176, v80
	v_mul_f32_e32 v8, 0xbfb8aa3b, v8
	v_exp_f32_e32 v8, v8
	v_add_f32_e32 v9, v178, v76
	v_mul_f32_e32 v9, 0xbfb8aa3b, v9
	v_exp_f32_e32 v9, v9
	v_add_f32_e32 v8, 1.0, v8
	v_rcp_f32_e32 v8, v8
	v_add_f32_e32 v75, 1.0, v75
	v_add_f32_e32 v9, 1.0, v9
	v_rcp_f32_e32 v74, v9
	v_mul_f32_e32 v8, v180, v8
	v_exp_f32_e32 v9, v8
	v_add_f32_e32 v8, v176, v81
	v_mul_f32_e32 v8, 0xbfb8aa3b, v8
	v_exp_f32_e32 v8, v8
	v_rcp_f32_e32 v78, v75
	v_fma_f32 v75, v13, v14, v15
	v_mul_f32_e32 v13, v13, v11
	v_add_f32_e32 v8, 1.0, v8
	v_rcp_f32_e32 v8, v8
	v_mul_f32_e32 v15, v9, v13
	v_mul_f32_e32 v8, v180, v8
	v_exp_f32_e32 v81, v8
	v_fma_f32 v8, -v9, v9, 1.0
	v_max_f32_e32 v8, 0, v8
	v_sqrt_f32_e32 v8, v8
	s_nop 0
	v_pk_mul_f32 v[76:77], v[74:75], v[8:9]
	v_add_f32_e32 v9, v177, v70
	v_mul_f32_e32 v9, 0xbfb8aa3b, v9
	v_exp_f32_e32 v9, v9
	v_fmac_f32_e32 v77, v76, v140
	v_fma_f32 v8, -v81, v81, 1.0
	v_max_f32_e32 v8, 0, v8
	v_add_f32_e32 v9, 1.0, v9
	v_rcp_f32_e32 v9, v9
	v_sqrt_f32_e32 v80, v8
	v_mov_b32_e32 v79, v77
	v_mul_f32_e32 v74, v81, v15
	v_mul_f32_e32 v9, v181, v9
	v_exp_f32_e32 v76, v9
	v_pk_mul_f32 v[78:79], v[78:79], v[80:81]
	ds_bpermute_b32 v8, v0, v74
	v_fmac_f32_e32 v79, v78, v141
	v_fma_f32 v9, -v76, v76, 1.0
	v_max_f32_e32 v9, 0, v9
	v_sqrt_f32_e32 v70, v9
	v_add_f32_e32 v9, v177, v71
	v_mul_f32_e32 v9, 0xbfb8aa3b, v9
	v_exp_f32_e32 v9, v9
	ds_bpermute_b32 v80, v0, v79
	ds_bpermute_b32 v138, v0, v74 offset:64
	ds_bpermute_b32 v140, v0, v79 offset:64
	v_add_f32_e32 v9, 1.0, v9
	v_rcp_f32_e32 v9, v9
	ds_bpermute_b32 v188, v0, v74 offset:128
	ds_bpermute_b32 v190, v0, v79 offset:128
	ds_bpermute_b32 v192, v0, v74 offset:192
	v_mul_f32_e32 v9, v181, v9
	v_exp_f32_e32 v9, v9
	ds_bpermute_b32 v194, v0, v79 offset:192
	v_fma_f32 v71, -v9, v9, 1.0
	v_max_f32_e32 v71, 0, v71
	v_sqrt_f32_e32 v71, v71
	s_nop 0
	v_pk_mul_f32 v[66:67], v[66:67], v[70:71]
	s_nop 0
	v_pk_mul_f32 v[66:67], v[66:67], v[2:3]
	v_add_f32_e32 v2, v177, v72
	v_mul_f32_e32 v2, 0xbfb8aa3b, v2
	v_exp_f32_e32 v2, v2
	v_add_f32_e32 v3, v179, v68
	v_mul_f32_e32 v3, 0xbfb8aa3b, v3
	v_exp_f32_e32 v3, v3
	v_add_f32_e32 v2, 1.0, v2
	v_rcp_f32_e32 v2, v2
	v_rcp_f32_e32 v70, v69
	v_add_f32_e32 v3, 1.0, v3
	v_rcp_f32_e32 v68, v3
	v_mul_f32_e32 v2, v181, v2
	v_exp_f32_e32 v3, v2
	v_add_f32_e32 v2, v177, v73
	v_mul_f32_e32 v2, 0xbfb8aa3b, v2
	v_exp_f32_e32 v2, v2
	v_fma_f32 v69, v9, v66, v67
	v_mul_f32_e32 v67, v9, v76
	v_add_f32_e32 v2, 1.0, v2
	v_rcp_f32_e32 v2, v2
	s_nop 0
	v_mul_f32_e32 v2, v181, v2
	v_exp_f32_e32 v73, v2
	v_fma_f32 v2, -v3, v3, 1.0
	v_max_f32_e32 v2, 0, v2
	v_sqrt_f32_e32 v2, v2
	s_nop 0
	v_pk_mul_f32 v[196:197], v[68:69], v[2:3]
	v_fma_f32 v2, -v73, v73, 1.0
	v_max_f32_e32 v2, 0, v2
	v_sqrt_f32_e32 v72, v2
	v_fmac_f32_e32 v197, v196, v4
	v_mov_b32_e32 v71, v197
	v_mul_f32_e32 v68, v3, v67
	v_pk_mul_f32 v[70:71], v[70:71], v[72:73]
	v_pk_fma_f32 v[2:3], v[126:127], v[184:185], v[186:187]
	v_fmac_f32_e32 v71, v70, v5
	v_mul_f32_e32 v70, v73, v68
	ds_bpermute_b32 v9, v0, v70
	ds_bpermute_b32 v81, v0, v71
	ds_bpermute_b32 v139, v0, v70 offset:64
	ds_bpermute_b32 v141, v0, v71 offset:64
	ds_bpermute_b32 v189, v0, v70 offset:128
	ds_bpermute_b32 v191, v0, v71 offset:128
	s_waitcnt lgkmcnt(4)
	v_pk_fma_f32 v[72:73], v[16:17], v[8:9], v[80:81]
	ds_bpermute_b32 v193, v0, v70 offset:192
	s_waitcnt lgkmcnt(3)
	v_pk_fma_f32 v[80:81], v[72:73], v[138:139], v[140:141]
	ds_bpermute_b32 v195, v0, v71 offset:192
	s_waitcnt lgkmcnt(2)
	v_pk_fma_f32 v[138:139], v[80:81], v[188:189], v[190:191]
	v_pk_fma_f32 v[4:5], v[106:107], v[116:117], v[128:129]
	v_cndmask_b32_e64 v0, v138, v80, s[8:9]
	v_cndmask_b32_e64 v0, v0, v72, s[6:7]
	v_cndmask_b32_e64 v0, v0, v16, s[4:5]
	v_fmac_f32_e32 v14, v11, v0
	v_fmac_f32_e32 v75, v13, v0
	v_fmac_f32_e32 v77, v15, v0
	v_fmac_f32_e32 v79, v74, v0
	v_cndmask_b32_e64 v0, v139, v81, s[8:9]
	v_cndmask_b32_e64 v0, v0, v73, s[6:7]
	v_cndmask_b32_e64 v0, v0, v17, s[4:5]
	v_fmac_f32_e32 v66, v76, v0
	v_fmac_f32_e32 v69, v67, v0
	v_fmac_f32_e32 v197, v68, v0
	v_fmac_f32_e32 v71, v70, v0
	v_cvt_pk_bf16_f32 v0, v130, v133
	ds_write_b16 v234, v0
	ds_write_b16_d16_hi v234, v0 offset:272
	v_cvt_pk_bf16_f32 v0, v135, v137
	ds_write_b16 v234, v0 offset:544
	ds_write_b16_d16_hi v234, v0 offset:816
	v_cvt_pk_bf16_f32 v0, v118, v121
	ds_write_b16 v234, v0 offset:32
	ds_write_b16_d16_hi v234, v0 offset:304
	v_cvt_pk_bf16_f32 v0, v123, v125
	ds_write_b16 v234, v0 offset:576
	ds_write_b16_d16_hi v234, v0 offset:848
	v_cvt_pk_bf16_f32 v0, v10, v111
	ds_write_b16 v234, v0 offset:64
	ds_write_b16_d16_hi v234, v0 offset:336
	v_cvt_pk_bf16_f32 v0, v113, v115
	ds_write_b16 v234, v0 offset:608
	ds_write_b16_d16_hi v234, v0 offset:880
	v_cvt_pk_bf16_f32 v0, v90, v93
	ds_write_b16 v234, v0 offset:96
	ds_write_b16_d16_hi v234, v0 offset:368
	v_cvt_pk_bf16_f32 v0, v103, v105
	ds_write_b16 v234, v0 offset:640
	ds_write_b16_d16_hi v234, v0 offset:912
	v_cvt_pk_bf16_f32 v0, v12, v95
	ds_write_b16 v234, v0 offset:128
	ds_write_b16_d16_hi v234, v0 offset:400
	v_cvt_pk_bf16_f32 v0, v97, v99
	ds_write_b16 v234, v0 offset:672
	ds_write_b16_d16_hi v234, v0 offset:944
	v_cvt_pk_bf16_f32 v0, v82, v85
	ds_write_b16 v234, v0 offset:160
	ds_write_b16_d16_hi v234, v0 offset:432
	v_cvt_pk_bf16_f32 v0, v87, v89
	ds_write_b16 v234, v0 offset:704
	ds_write_b16_d16_hi v234, v0 offset:976
	v_cvt_pk_bf16_f32 v0, v14, v75
	ds_write_b16 v234, v0 offset:192
	ds_write_b16_d16_hi v234, v0 offset:464
	v_cvt_pk_bf16_f32 v0, v77, v79
	ds_write_b16 v234, v0 offset:736
	ds_write_b16_d16_hi v234, v0 offset:1008
	v_cvt_pk_bf16_f32 v0, v66, v69
	ds_write_b16 v234, v0 offset:224
	ds_write_b16_d16_hi v234, v0 offset:496
	v_cvt_pk_bf16_f32 v0, v197, v71
	ds_write_b16 v234, v0 offset:768
	ds_write_b16_d16_hi v234, v0 offset:1040
	v_or_b32_e32 v0, s19, v203
	v_mad_i64_i32 v[14:15], s[20:21], v0, s83, v[152:153]
	global_load_dwordx4 v[14:17], v[14:15], off
	ds_read_b128 v[10:13], v235
	s_waitcnt lgkmcnt(14)
; #define LAS __attribute__((address_space(3)))
; __device__ __forceinline__ float bflo(unsigned w) { return __uint_as_float(w << 16); }
; __device__ __forceinline__ float bfhi(unsigned w) { return __uint_as_float(w & 0xffff0000u); }
; __device__ __forceinline__ u32x4 pack8(const f32x4 a, const f32x4 b) { u32x4 w; w.x = cvt_pk_bf16(a[0], a[1]); w.y = cvt_pk_bf16(a[2], a[3]); w.z = cvt_pk_bf16(b[0], b[1]); w.w = cvt_pk_bf16(b[2], b[3]); return w; }
; template <int PASS> __device__ __forceinline__ void lru_wave_item(LAS unsigned char* lds, LAS unsigned char* vw, int b, int c, int h, const MixP& p, int lane, float (&Hrun)[8], bool cont) {
;     ...
;             for (int i = 0; i < 4; ++i) {
;                 const int t = fq + 4 * i; const size_t row = (size_t)(row0 + 16 * st + t);
;                 const u32x4 hh = *(const LAS u32x4*)(vw + t * WROW + cg * 16);
;                 const u32x4 g = *(const u32x4*)(p.P2 + row * P2W + h * 128 + cg * 8);
;                 const f32x4 o0 = (f32x4){bflo(hh.x) * bflo(g.x), bfhi(hh.x) * bfhi(g.x), bflo(hh.y) * bflo(g.y), bfhi(hh.y) * bfhi(g.y)};
;                 const f32x4 o1 = (f32x4){bflo(hh.z) * bflo(g.z), bfhi(hh.z) * bfhi(g.z), bflo(hh.w) * bflo(g.w), bfhi(hh.w) * bfhi(g.w)};
;                 *(u32x4*)(p.hl + row * LW + h * 128 + cg * 8) = pack8(o0, o1);
;             }
	v_pk_fma_f32 v[8:9], v[138:139], v[192:193], v[194:195]
	s_waitcnt lgkmcnt(0)
	v_lshlrev_b32_e32 v67, 16, v10
	v_and_b32_e32 v10, 0xffff0000, v10
	s_waitcnt vmcnt(0)
	v_lshlrev_b32_e32 v66, 16, v14
	v_and_b32_e32 v14, 0xffff0000, v14
	v_mul_f32_e32 v66, v66, v67
	v_mul_f32_e32 v10, v14, v10
	v_lshlrev_b32_e32 v14, 16, v15
	v_lshlrev_b32_e32 v67, 16, v11
	v_and_b32_e32 v15, 0xffff0000, v15
	v_and_b32_e32 v11, 0xffff0000, v11
	v_mul_f32_e32 v14, v14, v67
	v_mul_f32_e32 v11, v15, v11
	v_lshlrev_b32_e32 v15, 16, v16
	v_lshlrev_b32_e32 v67, 16, v12
	v_and_b32_e32 v16, 0xffff0000, v16
	v_and_b32_e32 v12, 0xffff0000, v12
	v_mul_f32_e32 v15, v15, v67
	v_mul_f32_e32 v12, v16, v12
	v_lshlrev_b32_e32 v16, 16, v17
	v_lshlrev_b32_e32 v67, 16, v13
	v_and_b32_e32 v17, 0xffff0000, v17
	v_and_b32_e32 v13, 0xffff0000, v13
	v_mul_f32_e32 v13, v17, v13
	v_cvt_pk_bf16_f32 v10, v66, v10
	v_cvt_pk_bf16_f32 v11, v14, v11
	v_cvt_pk_bf16_f32 v12, v15, v12
	v_mad_i64_i32 v[14:15], s[20:21], v0, s40, v[154:155]
	v_or_b32_e32 v0, s19, v225
	v_mul_f32_e32 v16, v16, v67
	v_cvt_pk_bf16_f32 v13, v16, v13
	global_store_dwordx4 v[14:15], v[10:13], off sc1
	v_mad_i64_i32 v[14:15], s[20:21], v0, s83, v[152:153]
	global_load_dwordx4 v[14:17], v[14:15], off
	ds_read_b128 v[10:13], v235 offset:1088
	s_waitcnt lgkmcnt(0)
	v_lshlrev_b32_e32 v66, 16, v10
	v_and_b32_e32 v10, 0xffff0000, v10
	s_waitcnt vmcnt(0)
	v_lshlrev_b32_e32 v67, 16, v14
	v_and_b32_e32 v14, 0xffff0000, v14
	v_mul_f32_e32 v66, v67, v66
	v_mul_f32_e32 v10, v14, v10
	v_lshlrev_b32_e32 v14, 16, v11
	v_lshlrev_b32_e32 v67, 16, v15
	v_and_b32_e32 v15, 0xffff0000, v15
	v_and_b32_e32 v11, 0xffff0000, v11
	v_mul_f32_e32 v14, v67, v14
	v_mul_f32_e32 v11, v15, v11
	v_lshlrev_b32_e32 v15, 16, v12
	v_lshlrev_b32_e32 v67, 16, v16
	v_and_b32_e32 v16, 0xffff0000, v16
	v_and_b32_e32 v12, 0xffff0000, v12
	v_mul_f32_e32 v15, v67, v15
	v_mul_f32_e32 v12, v16, v12
	v_lshlrev_b32_e32 v16, 16, v13
	v_lshlrev_b32_e32 v67, 16, v17
	v_and_b32_e32 v17, 0xffff0000, v17
	v_and_b32_e32 v13, 0xffff0000, v13
	v_mul_f32_e32 v13, v17, v13
	v_cvt_pk_bf16_f32 v10, v66, v10
	v_cvt_pk_bf16_f32 v11, v14, v11
	v_cvt_pk_bf16_f32 v12, v15, v12
	v_mad_i64_i32 v[14:15], s[20:21], v0, s40, v[154:155]
	v_or_b32_e32 v0, s19, v226
	v_mul_f32_e32 v16, v67, v16
	v_cvt_pk_bf16_f32 v13, v16, v13
	global_store_dwordx4 v[14:15], v[10:13], off sc1
	v_mad_i64_i32 v[14:15], s[20:21], v0, s83, v[152:153]
	global_load_dwordx4 v[14:17], v[14:15], off
	ds_read_b128 v[10:13], v235 offset:2176
	s_waitcnt lgkmcnt(0)
	v_lshlrev_b32_e32 v66, 16, v10
	v_and_b32_e32 v10, 0xffff0000, v10
	s_waitcnt vmcnt(0)
	v_lshlrev_b32_e32 v67, 16, v14
	v_and_b32_e32 v14, 0xffff0000, v14
	v_mul_f32_e32 v66, v67, v66
	v_mul_f32_e32 v10, v14, v10
	v_lshlrev_b32_e32 v14, 16, v11
	v_lshlrev_b32_e32 v67, 16, v15
	v_and_b32_e32 v15, 0xffff0000, v15
	v_and_b32_e32 v11, 0xffff0000, v11
	v_mul_f32_e32 v14, v67, v14
	v_mul_f32_e32 v11, v15, v11
	v_lshlrev_b32_e32 v15, 16, v12
	v_lshlrev_b32_e32 v67, 16, v16
	v_and_b32_e32 v16, 0xffff0000, v16
	v_and_b32_e32 v12, 0xffff0000, v12
	v_mul_f32_e32 v15, v67, v15
	v_mul_f32_e32 v12, v16, v12
	v_lshlrev_b32_e32 v16, 16, v13
	v_lshlrev_b32_e32 v67, 16, v17
	v_and_b32_e32 v17, 0xffff0000, v17
	v_and_b32_e32 v13, 0xffff0000, v13
	v_mul_f32_e32 v13, v17, v13
	v_cvt_pk_bf16_f32 v10, v66, v10
	v_cvt_pk_bf16_f32 v11, v14, v11
	v_cvt_pk_bf16_f32 v12, v15, v12
	v_mad_i64_i32 v[14:15], s[20:21], v0, s40, v[154:155]
	v_or_b32_e32 v0, s19, v227
	v_mul_f32_e32 v16, v67, v16
	v_cvt_pk_bf16_f32 v13, v16, v13
	global_store_dwordx4 v[14:15], v[10:13], off sc1
	v_mad_i64_i32 v[14:15], s[20:21], v0, s83, v[152:153]
	global_load_dwordx4 v[14:17], v[14:15], off
	ds_read_b128 v[10:13], v235 offset:3264
	s_mov_b32 s19, 16
	s_waitcnt lgkmcnt(0)
	v_lshlrev_b32_e32 v66, 16, v10
	v_and_b32_e32 v10, 0xffff0000, v10
	s_waitcnt vmcnt(0)
	v_lshlrev_b32_e32 v67, 16, v14
	v_and_b32_e32 v14, 0xffff0000, v14
	v_mul_f32_e32 v66, v67, v66
	v_mul_f32_e32 v10, v14, v10
	v_lshlrev_b32_e32 v14, 16, v11
	v_lshlrev_b32_e32 v67, 16, v15
	v_and_b32_e32 v15, 0xffff0000, v15
	v_and_b32_e32 v11, 0xffff0000, v11
	v_mul_f32_e32 v14, v67, v14
	v_mul_f32_e32 v11, v15, v11
	v_lshlrev_b32_e32 v15, 16, v12
	v_lshlrev_b32_e32 v67, 16, v16
	v_and_b32_e32 v16, 0xffff0000, v16
	v_and_b32_e32 v12, 0xffff0000, v12
	v_mul_f32_e32 v15, v67, v15
	v_mul_f32_e32 v12, v16, v12
	v_lshlrev_b32_e32 v16, 16, v13
	v_lshlrev_b32_e32 v67, 16, v17
	v_and_b32_e32 v17, 0xffff0000, v17
	v_and_b32_e32 v13, 0xffff0000, v13
	v_mul_f32_e32 v13, v17, v13
	v_mul_f32_e32 v16, v67, v16
	v_cvt_pk_bf16_f32 v10, v66, v10
	v_cvt_pk_bf16_f32 v11, v14, v11
	v_cvt_pk_bf16_f32 v12, v15, v12
	v_cvt_pk_bf16_f32 v13, v16, v13
	v_mad_i64_i32 v[14:15], s[20:21], v0, s40, v[154:155]
	global_store_dwordx4 v[14:15], v[10:13], off sc1
	v_mov_b64_e32 v[16:17], v[8:9]
	v_mov_b64_e32 v[14:15], v[6:7]
	v_mov_b64_e32 v[12:13], v[4:5]
	v_mov_b64_e32 v[10:11], v[2:3]
	s_cbranch_vccnz .LBB0_818
	s_add_i32 s1, s1, 1
	s_cmp_ge_i32 s1, s10
	s_cbranch_scc0 .LBB0_811
	s_branch .LBB0_797
